# K-loop load phases: LDS fragment reads issued first, DMA address SALU moved from the phase head to after the ds_reads
# baseline (speedup 1.0000x reference)
.LBB0_444:
	s_lshl_b32 s100, s24, 3
	s_or_b32 s100, s100, s70
	s_ashr_i32 s101, s100, 31
	s_lshl_b64 s[100:101], s[100:101], 2
	s_add_u32 s100, s26, s100
	s_addc_u32 s101, s69, s101
	global_load_dword v232, v1, s[100:101] sc1
	global_load_dword v233, v1, s[100:101] offset:16 sc1
	s_add_u32 s48, s46, 0x20080
	s_addc_u32 s49, s47, 0
	s_add_u32 s25, s50, 0x100
	s_addc_u32 s64, s51, 0
	s_mov_b32 s65, -2
	s_add_i32 s84, 0, 0x10000
	v_add_u32_e32 v0, s84, v147
	ds_read_b128 v[150:153], v0
	ds_read_b128 v[154:157], v0 offset:1024
	ds_read_b128 v[158:161], v0 offset:2048
	ds_read_b128 v[162:165], v0 offset:3072
	ds_read_b128 v[166:169], v0 offset:16384
	ds_read_b128 v[170:173], v0 offset:17408
	ds_read_b128 v[174:177], v0 offset:18432
	ds_read_b128 v[178:181], v0 offset:19456
	ds_read_b128 v[182:185], v148
	ds_read_b128 v[186:189], v148 offset:1024
	ds_read_b128 v[190:193], v148 offset:2048
	ds_read_b128 v[194:197], v148 offset:3072
	ds_read_b128 v[198:201], v148 offset:4096
	ds_read_b128 v[202:205], v148 offset:5120
	ds_read_b128 v[206:209], v148 offset:6144
	ds_read_b128 v[210:213], v148 offset:7168
	s_add_u32 s46, s48, 0xfffe0080
	s_addc_u32 s47, s49, -1
	s_cmp_eq_u32 s65, 4
	s_cselect_b32 s47, s15, s47
	s_cselect_b32 s46, s14, s46
	s_cselect_b32 s51, s17, s64
	s_cselect_b32 s50, s16, s25
	s_add_i32 s86, 0, 0x14000
	s_add_i32 m0, s59, 0xc000
	s_nop 0
	global_load_lds_dwordx4 v132, s[48:49]
	s_add_i32 m0, s59, 0xe000
	s_nop 0
	global_load_lds_dwordx4 v133, s[48:49]
	s_waitcnt vmcnt(8) lgkmcnt(0)
	s_setprio 1
	s_barrier
	v_mfma_i32_16x16x64_i8 v[126:129], v[150:153], v[182:185], 0
	v_mfma_i32_16x16x64_i8 v[122:125], v[158:161], v[182:185], 0
	v_mfma_i32_16x16x64_i8 v[110:113], v[150:153], v[190:193], 0
	v_mfma_i32_16x16x64_i8 v[106:109], v[158:161], v[190:193], 0
	v_mfma_i32_16x16x64_i8 v[94:97], v[150:153], v[198:201], 0
	v_mfma_i32_16x16x64_i8 v[90:93], v[158:161], v[198:201], 0
	v_mfma_i32_16x16x64_i8 v[78:81], v[150:153], v[206:209], 0
	v_mfma_i32_16x16x64_i8 v[74:77], v[158:161], v[206:209], 0
	v_mfma_i32_16x16x64_i8 v[126:129], v[154:157], v[186:189], v[126:129]
	v_mfma_i32_16x16x64_i8 v[122:125], v[162:165], v[186:189], v[122:125]
	v_mfma_i32_16x16x64_i8 v[110:113], v[154:157], v[194:197], v[110:113]
	v_mfma_i32_16x16x64_i8 v[106:109], v[162:165], v[194:197], v[106:109]
	v_mfma_i32_16x16x64_i8 v[94:97], v[154:157], v[202:205], v[94:97]
	v_mfma_i32_16x16x64_i8 v[90:93], v[162:165], v[202:205], v[90:93]
	v_mfma_i32_16x16x64_i8 v[78:81], v[154:157], v[210:213], v[78:81]
	v_mfma_i32_16x16x64_i8 v[74:77], v[162:165], v[210:213], v[74:77]
	s_setprio 0
	s_setprio 1
	v_mfma_i32_16x16x64_i8 v[118:121], v[166:169], v[182:185], 0
	v_mfma_i32_16x16x64_i8 v[114:117], v[174:177], v[182:185], 0
	v_mfma_i32_16x16x64_i8 v[102:105], v[166:169], v[190:193], 0
	v_mfma_i32_16x16x64_i8 v[98:101], v[174:177], v[190:193], 0
	v_mfma_i32_16x16x64_i8 v[86:89], v[166:169], v[198:201], 0
	v_mfma_i32_16x16x64_i8 v[82:85], v[174:177], v[198:201], 0
	v_mfma_i32_16x16x64_i8 v[70:73], v[166:169], v[206:209], 0
	v_mfma_i32_16x16x64_i8 v[66:69], v[174:177], v[206:209], 0
	v_mfma_i32_16x16x64_i8 v[118:121], v[170:173], v[186:189], v[118:121]
	v_mfma_i32_16x16x64_i8 v[114:117], v[178:181], v[186:189], v[114:117]
	v_mfma_i32_16x16x64_i8 v[102:105], v[170:173], v[194:197], v[102:105]
	v_mfma_i32_16x16x64_i8 v[98:101], v[178:181], v[194:197], v[98:101]
	v_mfma_i32_16x16x64_i8 v[86:89], v[170:173], v[202:205], v[86:89]
	v_mfma_i32_16x16x64_i8 v[82:85], v[178:181], v[202:205], v[82:85]
	v_mfma_i32_16x16x64_i8 v[70:73], v[170:173], v[210:213], v[70:73]
	v_mfma_i32_16x16x64_i8 v[66:69], v[178:181], v[210:213], v[66:69]
	s_setprio 0
	s_barrier
	ds_read_b128 v[182:185], v148 offset:16384
	ds_read_b128 v[186:189], v148 offset:17408
	ds_read_b128 v[190:193], v148 offset:18432
	ds_read_b128 v[194:197], v148 offset:19456
	ds_read_b128 v[198:201], v148 offset:20480
	ds_read_b128 v[202:205], v148 offset:21504
	ds_read_b128 v[206:209], v148 offset:22528
	ds_read_b128 v[210:213], v148 offset:23552
	s_add_i32 s84, s84, s40
	s_mov_b32 m0, s84
	s_nop 0
	global_load_lds_dwordx4 v143, s[50:51]
	s_add_i32 m0, s84, 0x2000
	s_add_u32 s84, s50, 0x20000
	global_load_lds_dwordx4 v144, s[50:51]
	s_addc_u32 s85, s51, 0
	s_add_i32 s86, s86, s40
	s_mov_b32 m0, s86
	s_nop 0
	global_load_lds_dwordx4 v143, s[84:85]
	s_add_i32 m0, s86, 0x2000
	s_nop 0
	global_load_lds_dwordx4 v144, s[84:85]
	s_mov_b32 m0, s59
	s_nop 0
	global_load_lds_dwordx4 v132, s[46:47]
	s_mov_b32 m0, s60
	s_nop 0
	global_load_lds_dwordx4 v133, s[46:47]
	s_waitcnt vmcnt(8) lgkmcnt(0)
	s_setprio 1
	s_barrier
	v_mfma_i32_16x16x64_i8 v[62:65], v[150:153], v[182:185], 0
	v_mfma_i32_16x16x64_i8 v[58:61], v[158:161], v[182:185], 0
	v_mfma_i32_16x16x64_i8 v[46:49], v[150:153], v[190:193], 0
	v_mfma_i32_16x16x64_i8 v[42:45], v[158:161], v[190:193], 0
	v_mfma_i32_16x16x64_i8 v[30:33], v[150:153], v[198:201], 0
	v_mfma_i32_16x16x64_i8 v[26:29], v[158:161], v[198:201], 0
	v_mfma_i32_16x16x64_i8 v[14:17], v[150:153], v[206:209], 0
	v_mfma_i32_16x16x64_i8 v[10:13], v[158:161], v[206:209], 0
	v_mfma_i32_16x16x64_i8 v[62:65], v[154:157], v[186:189], v[62:65]
	v_mfma_i32_16x16x64_i8 v[58:61], v[162:165], v[186:189], v[58:61]
	v_mfma_i32_16x16x64_i8 v[46:49], v[154:157], v[194:197], v[46:49]
	v_mfma_i32_16x16x64_i8 v[42:45], v[162:165], v[194:197], v[42:45]
	v_mfma_i32_16x16x64_i8 v[30:33], v[154:157], v[202:205], v[30:33]
	v_mfma_i32_16x16x64_i8 v[26:29], v[162:165], v[202:205], v[26:29]
	v_mfma_i32_16x16x64_i8 v[14:17], v[154:157], v[210:213], v[14:17]
	v_mfma_i32_16x16x64_i8 v[10:13], v[162:165], v[210:213], v[10:13]
	s_setprio 0
	s_setprio 1
	v_mfma_i32_16x16x64_i8 v[54:57], v[166:169], v[182:185], 0
	v_mfma_i32_16x16x64_i8 v[50:53], v[174:177], v[182:185], 0
	v_mfma_i32_16x16x64_i8 v[38:41], v[166:169], v[190:193], 0
	v_mfma_i32_16x16x64_i8 v[34:37], v[174:177], v[190:193], 0
	v_mfma_i32_16x16x64_i8 v[22:25], v[166:169], v[198:201], 0
	v_mfma_i32_16x16x64_i8 v[18:21], v[174:177], v[198:201], 0
	v_mfma_i32_16x16x64_i8 v[6:9], v[166:169], v[206:209], 0
	v_mfma_i32_16x16x64_i8 v[2:5], v[174:177], v[206:209], 0
	v_mfma_i32_16x16x64_i8 v[54:57], v[170:173], v[186:189], v[54:57]
	v_mfma_i32_16x16x64_i8 v[50:53], v[178:181], v[186:189], v[50:53]
	v_mfma_i32_16x16x64_i8 v[38:41], v[170:173], v[194:197], v[38:41]
	v_mfma_i32_16x16x64_i8 v[34:37], v[178:181], v[194:197], v[34:37]
	v_mfma_i32_16x16x64_i8 v[22:25], v[170:173], v[202:205], v[22:25]
	v_mfma_i32_16x16x64_i8 v[18:21], v[178:181], v[202:205], v[18:21]
	v_mfma_i32_16x16x64_i8 v[6:9], v[170:173], v[210:213], v[6:9]
	v_mfma_i32_16x16x64_i8 v[2:5], v[178:181], v[210:213], v[2:5]
	s_setprio 0
	s_barrier
	ds_read_b128 v[150:153], v0 offset:32768
	ds_read_b128 v[154:157], v0 offset:33792
	ds_read_b128 v[158:161], v0 offset:34816
	ds_read_b128 v[162:165], v0 offset:35840
	ds_read_b128 v[166:169], v0 offset:49152
	ds_read_b128 v[170:173], v0 offset:50176
	ds_read_b128 v[174:177], v0 offset:51200
	ds_read_b128 v[178:181], v0 offset:52224
	s_add_u32 s84, s46, 0x20000
	s_mov_b32 m0, s61
	ds_read_b128 v[182:185], v148 offset:32768
	ds_read_b128 v[186:189], v148 offset:33792
	ds_read_b128 v[190:193], v148 offset:34816
	ds_read_b128 v[194:197], v148 offset:35840
	ds_read_b128 v[198:201], v148 offset:36864
	ds_read_b128 v[202:205], v148 offset:37888
	ds_read_b128 v[206:209], v148 offset:38912
	ds_read_b128 v[210:213], v148 offset:39936
	s_addc_u32 s85, s47, 0
	s_add_i32 s86, 0, 0x18000
	s_add_i32 s87, 0, 0x1c000
	s_nop 0
	global_load_lds_dwordx4 v132, s[84:85]
	s_mov_b32 m0, s66
	s_nop 0
	global_load_lds_dwordx4 v133, s[84:85]
	s_waitcnt vmcnt(8) lgkmcnt(0)
	s_setprio 1
	s_barrier
	v_mfma_i32_16x16x64_i8 v[126:129], v[150:153], v[182:185], v[126:129]
	v_mfma_i32_16x16x64_i8 v[122:125], v[158:161], v[182:185], v[122:125]
	v_mfma_i32_16x16x64_i8 v[110:113], v[150:153], v[190:193], v[110:113]
	v_mfma_i32_16x16x64_i8 v[106:109], v[158:161], v[190:193], v[106:109]
	v_mfma_i32_16x16x64_i8 v[94:97], v[150:153], v[198:201], v[94:97]
	v_mfma_i32_16x16x64_i8 v[90:93], v[158:161], v[198:201], v[90:93]
	v_mfma_i32_16x16x64_i8 v[78:81], v[150:153], v[206:209], v[78:81]
	v_mfma_i32_16x16x64_i8 v[74:77], v[158:161], v[206:209], v[74:77]
	v_mfma_i32_16x16x64_i8 v[126:129], v[154:157], v[186:189], v[126:129]
	v_mfma_i32_16x16x64_i8 v[122:125], v[162:165], v[186:189], v[122:125]
	v_mfma_i32_16x16x64_i8 v[110:113], v[154:157], v[194:197], v[110:113]
	v_mfma_i32_16x16x64_i8 v[106:109], v[162:165], v[194:197], v[106:109]
	v_mfma_i32_16x16x64_i8 v[94:97], v[154:157], v[202:205], v[94:97]
	v_mfma_i32_16x16x64_i8 v[90:93], v[162:165], v[202:205], v[90:93]
	v_mfma_i32_16x16x64_i8 v[78:81], v[154:157], v[210:213], v[78:81]
	v_mfma_i32_16x16x64_i8 v[74:77], v[162:165], v[210:213], v[74:77]
	s_setprio 0
	s_setprio 1
	v_mfma_i32_16x16x64_i8 v[118:121], v[166:169], v[182:185], v[118:121]
	v_mfma_i32_16x16x64_i8 v[114:117], v[174:177], v[182:185], v[114:117]
	v_mfma_i32_16x16x64_i8 v[102:105], v[166:169], v[190:193], v[102:105]
	v_mfma_i32_16x16x64_i8 v[98:101], v[174:177], v[190:193], v[98:101]
	v_mfma_i32_16x16x64_i8 v[86:89], v[166:169], v[198:201], v[86:89]
	v_mfma_i32_16x16x64_i8 v[82:85], v[174:177], v[198:201], v[82:85]
	v_mfma_i32_16x16x64_i8 v[70:73], v[166:169], v[206:209], v[70:73]
	v_mfma_i32_16x16x64_i8 v[66:69], v[174:177], v[206:209], v[66:69]
	v_mfma_i32_16x16x64_i8 v[118:121], v[170:173], v[186:189], v[118:121]
	v_mfma_i32_16x16x64_i8 v[114:117], v[178:181], v[186:189], v[114:117]
	v_mfma_i32_16x16x64_i8 v[102:105], v[170:173], v[194:197], v[102:105]
	v_mfma_i32_16x16x64_i8 v[98:101], v[178:181], v[194:197], v[98:101]
	v_mfma_i32_16x16x64_i8 v[86:89], v[170:173], v[202:205], v[86:89]
	v_mfma_i32_16x16x64_i8 v[82:85], v[178:181], v[202:205], v[82:85]
	v_mfma_i32_16x16x64_i8 v[70:73], v[170:173], v[210:213], v[70:73]
	v_mfma_i32_16x16x64_i8 v[66:69], v[178:181], v[210:213], v[66:69]
	s_setprio 0
	s_barrier
	ds_read_b128 v[182:185], v148 offset:49152
	ds_read_b128 v[186:189], v148 offset:50176
	ds_read_b128 v[190:193], v148 offset:51200
	ds_read_b128 v[194:197], v148 offset:52224
	ds_read_b128 v[198:201], v148 offset:53248
	ds_read_b128 v[202:205], v148 offset:54272
	ds_read_b128 v[206:209], v148 offset:55296
	ds_read_b128 v[210:213], v148 offset:56320
	s_add_i32 s84, s86, s40
	s_add_u32 s100, s50, s38
	s_addc_u32 s101, s51, s39
	s_mov_b32 m0, s84
	s_nop 0
	global_load_lds_dwordx4 v143, s[100:101]
	s_add_i32 m0, s84, 0x2000
	s_nop 0
	s_add_u32 s50, s50, 0x20080
	s_addc_u32 s51, s51, 0
	s_add_i32 s84, s87, s40
	global_load_lds_dwordx4 v144, s[100:101]
	s_mov_b32 m0, s84
	s_nop 0
	global_load_lds_dwordx4 v143, s[50:51]
	s_add_i32 m0, s84, 0x2000
	s_nop 0
	global_load_lds_dwordx4 v144, s[50:51]
	s_mov_b32 m0, s75
	s_add_u32 s100, s46, s38
	s_addc_u32 s101, s47, s39
	v_mov_b32_e32 v0, v133
	global_load_lds_dwordx4 v132, s[100:101]
	s_mov_b32 m0, s78
	s_nop 0
	global_load_lds_dwordx4 v133, s[100:101]
	s_waitcnt vmcnt(8) lgkmcnt(0)
	s_setprio 1
	s_barrier
	v_mfma_i32_16x16x64_i8 v[62:65], v[150:153], v[182:185], v[62:65]
	v_mfma_i32_16x16x64_i8 v[58:61], v[158:161], v[182:185], v[58:61]
	v_mfma_i32_16x16x64_i8 v[46:49], v[150:153], v[190:193], v[46:49]
	v_mfma_i32_16x16x64_i8 v[42:45], v[158:161], v[190:193], v[42:45]
	v_mfma_i32_16x16x64_i8 v[30:33], v[150:153], v[198:201], v[30:33]
	v_mfma_i32_16x16x64_i8 v[26:29], v[158:161], v[198:201], v[26:29]
	v_mfma_i32_16x16x64_i8 v[14:17], v[150:153], v[206:209], v[14:17]
	v_mfma_i32_16x16x64_i8 v[10:13], v[158:161], v[206:209], v[10:13]
	v_mfma_i32_16x16x64_i8 v[62:65], v[154:157], v[186:189], v[62:65]
	v_mfma_i32_16x16x64_i8 v[58:61], v[162:165], v[186:189], v[58:61]
	v_mfma_i32_16x16x64_i8 v[46:49], v[154:157], v[194:197], v[46:49]
	v_mfma_i32_16x16x64_i8 v[42:45], v[162:165], v[194:197], v[42:45]
	v_mfma_i32_16x16x64_i8 v[30:33], v[154:157], v[202:205], v[30:33]
	v_mfma_i32_16x16x64_i8 v[26:29], v[162:165], v[202:205], v[26:29]
	v_mfma_i32_16x16x64_i8 v[14:17], v[154:157], v[210:213], v[14:17]
	v_mfma_i32_16x16x64_i8 v[10:13], v[162:165], v[210:213], v[10:13]
	s_setprio 0
	s_setprio 1
	v_mfma_i32_16x16x64_i8 v[54:57], v[166:169], v[182:185], v[54:57]
	v_mfma_i32_16x16x64_i8 v[50:53], v[174:177], v[182:185], v[50:53]
	v_mfma_i32_16x16x64_i8 v[38:41], v[166:169], v[190:193], v[38:41]
	v_mfma_i32_16x16x64_i8 v[34:37], v[174:177], v[190:193], v[34:37]
	v_mfma_i32_16x16x64_i8 v[22:25], v[166:169], v[198:201], v[22:25]
	v_mfma_i32_16x16x64_i8 v[18:21], v[174:177], v[198:201], v[18:21]
	v_mfma_i32_16x16x64_i8 v[6:9], v[166:169], v[206:209], v[6:9]
	v_mfma_i32_16x16x64_i8 v[2:5], v[174:177], v[206:209], v[2:5]
	v_mfma_i32_16x16x64_i8 v[54:57], v[170:173], v[186:189], v[54:57]
	v_mfma_i32_16x16x64_i8 v[50:53], v[178:181], v[186:189], v[50:53]
	v_mfma_i32_16x16x64_i8 v[38:41], v[170:173], v[194:197], v[38:41]
	v_mfma_i32_16x16x64_i8 v[34:37], v[178:181], v[194:197], v[34:37]
	v_mfma_i32_16x16x64_i8 v[22:25], v[170:173], v[202:205], v[22:25]
	v_mfma_i32_16x16x64_i8 v[18:21], v[178:181], v[202:205], v[18:21]
	v_mfma_i32_16x16x64_i8 v[6:9], v[170:173], v[210:213], v[6:9]
	v_mfma_i32_16x16x64_i8 v[2:5], v[178:181], v[210:213], v[2:5]
	s_setprio 0
	s_barrier
	s_add_i32 s65, s65, 2
	s_add_u32 s48, s48, 0x100
	s_addc_u32 s49, s49, 0
	s_add_u32 s25, s25, 0x100
	s_addc_u32 s64, s64, 0
	s_cmp_gt_u32 s65, 5
	s_cbranch_scc0 .LBB0_445
	s_branch .Lpeel_exit_445
	.p2align	6
.LBB0_445:
	s_add_i32 s84, 0, 0x10000
	v_add_u32_e32 v0, s84, v147
	ds_read_b128 v[150:153], v0
	ds_read_b128 v[154:157], v0 offset:1024
	ds_read_b128 v[158:161], v0 offset:2048
	ds_read_b128 v[162:165], v0 offset:3072
	ds_read_b128 v[166:169], v0 offset:16384
	ds_read_b128 v[170:173], v0 offset:17408
	ds_read_b128 v[174:177], v0 offset:18432
	ds_read_b128 v[178:181], v0 offset:19456
	ds_read_b128 v[182:185], v148
	ds_read_b128 v[186:189], v148 offset:1024
	ds_read_b128 v[190:193], v148 offset:2048
	ds_read_b128 v[194:197], v148 offset:3072
	ds_read_b128 v[198:201], v148 offset:4096
	ds_read_b128 v[202:205], v148 offset:5120
	ds_read_b128 v[206:209], v148 offset:6144
	ds_read_b128 v[210:213], v148 offset:7168
	s_add_u32 s46, s48, 0xfffe0080
	s_addc_u32 s47, s49, -1
	s_cmp_eq_u32 s65, 4
	s_cselect_b32 s47, s15, s47
	s_cselect_b32 s46, s14, s46
	s_cselect_b32 s51, s17, s64
	s_cselect_b32 s50, s16, s25
	s_add_i32 s86, 0, 0x14000
	s_add_i32 m0, s59, 0xc000
	s_nop 0
	global_load_lds_dwordx4 v132, s[48:49]
	s_add_i32 m0, s59, 0xe000
	s_nop 0
	global_load_lds_dwordx4 v133, s[48:49]
	s_waitcnt vmcnt(8) lgkmcnt(0)
	s_setprio 1
	s_barrier
	v_mfma_i32_16x16x64_i8 v[126:129], v[150:153], v[182:185], v[126:129]
	v_mfma_i32_16x16x64_i8 v[122:125], v[158:161], v[182:185], v[122:125]
	v_mfma_i32_16x16x64_i8 v[110:113], v[150:153], v[190:193], v[110:113]
	v_mfma_i32_16x16x64_i8 v[106:109], v[158:161], v[190:193], v[106:109]
	v_mfma_i32_16x16x64_i8 v[94:97], v[150:153], v[198:201], v[94:97]
	v_mfma_i32_16x16x64_i8 v[90:93], v[158:161], v[198:201], v[90:93]
	v_mfma_i32_16x16x64_i8 v[78:81], v[150:153], v[206:209], v[78:81]
	v_mfma_i32_16x16x64_i8 v[74:77], v[158:161], v[206:209], v[74:77]
	v_mfma_i32_16x16x64_i8 v[126:129], v[154:157], v[186:189], v[126:129]
	v_mfma_i32_16x16x64_i8 v[122:125], v[162:165], v[186:189], v[122:125]
	v_mfma_i32_16x16x64_i8 v[110:113], v[154:157], v[194:197], v[110:113]
	v_mfma_i32_16x16x64_i8 v[106:109], v[162:165], v[194:197], v[106:109]
	v_mfma_i32_16x16x64_i8 v[94:97], v[154:157], v[202:205], v[94:97]
	v_mfma_i32_16x16x64_i8 v[90:93], v[162:165], v[202:205], v[90:93]
	v_mfma_i32_16x16x64_i8 v[78:81], v[154:157], v[210:213], v[78:81]
	v_mfma_i32_16x16x64_i8 v[74:77], v[162:165], v[210:213], v[74:77]
	s_setprio 0
	s_setprio 1
	v_mfma_i32_16x16x64_i8 v[118:121], v[166:169], v[182:185], v[118:121]
	v_mfma_i32_16x16x64_i8 v[114:117], v[174:177], v[182:185], v[114:117]
	v_mfma_i32_16x16x64_i8 v[102:105], v[166:169], v[190:193], v[102:105]
	v_mfma_i32_16x16x64_i8 v[98:101], v[174:177], v[190:193], v[98:101]
	v_mfma_i32_16x16x64_i8 v[86:89], v[166:169], v[198:201], v[86:89]
	v_mfma_i32_16x16x64_i8 v[82:85], v[174:177], v[198:201], v[82:85]
	v_mfma_i32_16x16x64_i8 v[70:73], v[166:169], v[206:209], v[70:73]
	v_mfma_i32_16x16x64_i8 v[66:69], v[174:177], v[206:209], v[66:69]
	v_mfma_i32_16x16x64_i8 v[118:121], v[170:173], v[186:189], v[118:121]
	v_mfma_i32_16x16x64_i8 v[114:117], v[178:181], v[186:189], v[114:117]
	v_mfma_i32_16x16x64_i8 v[102:105], v[170:173], v[194:197], v[102:105]
	v_mfma_i32_16x16x64_i8 v[98:101], v[178:181], v[194:197], v[98:101]
	v_mfma_i32_16x16x64_i8 v[86:89], v[170:173], v[202:205], v[86:89]
	v_mfma_i32_16x16x64_i8 v[82:85], v[178:181], v[202:205], v[82:85]
	v_mfma_i32_16x16x64_i8 v[70:73], v[170:173], v[210:213], v[70:73]
	v_mfma_i32_16x16x64_i8 v[66:69], v[178:181], v[210:213], v[66:69]
	s_setprio 0
	s_barrier
	ds_read_b128 v[182:185], v148 offset:16384
	ds_read_b128 v[186:189], v148 offset:17408
	ds_read_b128 v[190:193], v148 offset:18432
	ds_read_b128 v[194:197], v148 offset:19456
	ds_read_b128 v[198:201], v148 offset:20480
	ds_read_b128 v[202:205], v148 offset:21504
	ds_read_b128 v[206:209], v148 offset:22528
	ds_read_b128 v[210:213], v148 offset:23552
	s_add_i32 s84, s84, s40
	s_mov_b32 m0, s84
	s_nop 0
	global_load_lds_dwordx4 v143, s[50:51]
	s_add_i32 m0, s84, 0x2000
	s_add_u32 s84, s50, 0x20000
	global_load_lds_dwordx4 v144, s[50:51]
	s_addc_u32 s85, s51, 0
	s_add_i32 s86, s86, s40
	s_mov_b32 m0, s86
	s_nop 0
	global_load_lds_dwordx4 v143, s[84:85]
	s_add_i32 m0, s86, 0x2000
	s_nop 0
	global_load_lds_dwordx4 v144, s[84:85]
	s_mov_b32 m0, s59
	s_nop 0
	global_load_lds_dwordx4 v132, s[46:47]
	s_mov_b32 m0, s60
	s_nop 0
	global_load_lds_dwordx4 v133, s[46:47]
	s_waitcnt vmcnt(8) lgkmcnt(0)
	s_setprio 1
	s_barrier
	v_mfma_i32_16x16x64_i8 v[62:65], v[150:153], v[182:185], v[62:65]
	v_mfma_i32_16x16x64_i8 v[58:61], v[158:161], v[182:185], v[58:61]
	v_mfma_i32_16x16x64_i8 v[46:49], v[150:153], v[190:193], v[46:49]
	v_mfma_i32_16x16x64_i8 v[42:45], v[158:161], v[190:193], v[42:45]
	v_mfma_i32_16x16x64_i8 v[30:33], v[150:153], v[198:201], v[30:33]
	v_mfma_i32_16x16x64_i8 v[26:29], v[158:161], v[198:201], v[26:29]
	v_mfma_i32_16x16x64_i8 v[14:17], v[150:153], v[206:209], v[14:17]
	v_mfma_i32_16x16x64_i8 v[10:13], v[158:161], v[206:209], v[10:13]
	v_mfma_i32_16x16x64_i8 v[62:65], v[154:157], v[186:189], v[62:65]
	v_mfma_i32_16x16x64_i8 v[58:61], v[162:165], v[186:189], v[58:61]
	v_mfma_i32_16x16x64_i8 v[46:49], v[154:157], v[194:197], v[46:49]
	v_mfma_i32_16x16x64_i8 v[42:45], v[162:165], v[194:197], v[42:45]
	v_mfma_i32_16x16x64_i8 v[30:33], v[154:157], v[202:205], v[30:33]
	v_mfma_i32_16x16x64_i8 v[26:29], v[162:165], v[202:205], v[26:29]
	v_mfma_i32_16x16x64_i8 v[14:17], v[154:157], v[210:213], v[14:17]
	v_mfma_i32_16x16x64_i8 v[10:13], v[162:165], v[210:213], v[10:13]
	s_setprio 0
	s_setprio 1
	v_mfma_i32_16x16x64_i8 v[54:57], v[166:169], v[182:185], v[54:57]
	v_mfma_i32_16x16x64_i8 v[50:53], v[174:177], v[182:185], v[50:53]
	v_mfma_i32_16x16x64_i8 v[38:41], v[166:169], v[190:193], v[38:41]
	v_mfma_i32_16x16x64_i8 v[34:37], v[174:177], v[190:193], v[34:37]
	v_mfma_i32_16x16x64_i8 v[22:25], v[166:169], v[198:201], v[22:25]
	v_mfma_i32_16x16x64_i8 v[18:21], v[174:177], v[198:201], v[18:21]
	v_mfma_i32_16x16x64_i8 v[6:9], v[166:169], v[206:209], v[6:9]
	v_mfma_i32_16x16x64_i8 v[2:5], v[174:177], v[206:209], v[2:5]
	v_mfma_i32_16x16x64_i8 v[54:57], v[170:173], v[186:189], v[54:57]
	v_mfma_i32_16x16x64_i8 v[50:53], v[178:181], v[186:189], v[50:53]
	v_mfma_i32_16x16x64_i8 v[38:41], v[170:173], v[194:197], v[38:41]
	v_mfma_i32_16x16x64_i8 v[34:37], v[178:181], v[194:197], v[34:37]
	v_mfma_i32_16x16x64_i8 v[22:25], v[170:173], v[202:205], v[22:25]
	v_mfma_i32_16x16x64_i8 v[18:21], v[178:181], v[202:205], v[18:21]
	v_mfma_i32_16x16x64_i8 v[6:9], v[170:173], v[210:213], v[6:9]
	v_mfma_i32_16x16x64_i8 v[2:5], v[178:181], v[210:213], v[2:5]
	s_setprio 0
	s_barrier
	ds_read_b128 v[150:153], v0 offset:32768
	ds_read_b128 v[154:157], v0 offset:33792
	ds_read_b128 v[158:161], v0 offset:34816
	ds_read_b128 v[162:165], v0 offset:35840
	ds_read_b128 v[166:169], v0 offset:49152
	ds_read_b128 v[170:173], v0 offset:50176
	ds_read_b128 v[174:177], v0 offset:51200
	ds_read_b128 v[178:181], v0 offset:52224
	s_add_u32 s84, s46, 0x20000
	s_mov_b32 m0, s61
	ds_read_b128 v[182:185], v148 offset:32768
	ds_read_b128 v[186:189], v148 offset:33792
	ds_read_b128 v[190:193], v148 offset:34816
	ds_read_b128 v[194:197], v148 offset:35840
	ds_read_b128 v[198:201], v148 offset:36864
	ds_read_b128 v[202:205], v148 offset:37888
	ds_read_b128 v[206:209], v148 offset:38912
	ds_read_b128 v[210:213], v148 offset:39936
	s_addc_u32 s85, s47, 0
	s_add_i32 s86, 0, 0x18000
	s_add_i32 s87, 0, 0x1c000
	s_nop 0
	global_load_lds_dwordx4 v132, s[84:85]
	s_mov_b32 m0, s66
	s_nop 0
	global_load_lds_dwordx4 v133, s[84:85]
	s_waitcnt vmcnt(8) lgkmcnt(0)
	s_setprio 1
	s_barrier
	v_mfma_i32_16x16x64_i8 v[126:129], v[150:153], v[182:185], v[126:129]
	v_mfma_i32_16x16x64_i8 v[122:125], v[158:161], v[182:185], v[122:125]
	v_mfma_i32_16x16x64_i8 v[110:113], v[150:153], v[190:193], v[110:113]
	v_mfma_i32_16x16x64_i8 v[106:109], v[158:161], v[190:193], v[106:109]
	v_mfma_i32_16x16x64_i8 v[94:97], v[150:153], v[198:201], v[94:97]
	v_mfma_i32_16x16x64_i8 v[90:93], v[158:161], v[198:201], v[90:93]
	v_mfma_i32_16x16x64_i8 v[78:81], v[150:153], v[206:209], v[78:81]
	v_mfma_i32_16x16x64_i8 v[74:77], v[158:161], v[206:209], v[74:77]
	v_mfma_i32_16x16x64_i8 v[126:129], v[154:157], v[186:189], v[126:129]
	v_mfma_i32_16x16x64_i8 v[122:125], v[162:165], v[186:189], v[122:125]
	v_mfma_i32_16x16x64_i8 v[110:113], v[154:157], v[194:197], v[110:113]
	v_mfma_i32_16x16x64_i8 v[106:109], v[162:165], v[194:197], v[106:109]
	v_mfma_i32_16x16x64_i8 v[94:97], v[154:157], v[202:205], v[94:97]
	v_mfma_i32_16x16x64_i8 v[90:93], v[162:165], v[202:205], v[90:93]
	v_mfma_i32_16x16x64_i8 v[78:81], v[154:157], v[210:213], v[78:81]
	v_mfma_i32_16x16x64_i8 v[74:77], v[162:165], v[210:213], v[74:77]
	s_setprio 0
	s_setprio 1
	v_mfma_i32_16x16x64_i8 v[118:121], v[166:169], v[182:185], v[118:121]
	v_mfma_i32_16x16x64_i8 v[114:117], v[174:177], v[182:185], v[114:117]
	v_mfma_i32_16x16x64_i8 v[102:105], v[166:169], v[190:193], v[102:105]
	v_mfma_i32_16x16x64_i8 v[98:101], v[174:177], v[190:193], v[98:101]
	v_mfma_i32_16x16x64_i8 v[86:89], v[166:169], v[198:201], v[86:89]
	v_mfma_i32_16x16x64_i8 v[82:85], v[174:177], v[198:201], v[82:85]
	v_mfma_i32_16x16x64_i8 v[70:73], v[166:169], v[206:209], v[70:73]
	v_mfma_i32_16x16x64_i8 v[66:69], v[174:177], v[206:209], v[66:69]
	v_mfma_i32_16x16x64_i8 v[118:121], v[170:173], v[186:189], v[118:121]
	v_mfma_i32_16x16x64_i8 v[114:117], v[178:181], v[186:189], v[114:117]
	v_mfma_i32_16x16x64_i8 v[102:105], v[170:173], v[194:197], v[102:105]
	v_mfma_i32_16x16x64_i8 v[98:101], v[178:181], v[194:197], v[98:101]
	v_mfma_i32_16x16x64_i8 v[86:89], v[170:173], v[202:205], v[86:89]
	v_mfma_i32_16x16x64_i8 v[82:85], v[178:181], v[202:205], v[82:85]
	v_mfma_i32_16x16x64_i8 v[70:73], v[170:173], v[210:213], v[70:73]
	v_mfma_i32_16x16x64_i8 v[66:69], v[178:181], v[210:213], v[66:69]
	s_setprio 0
	s_barrier
	ds_read_b128 v[182:185], v148 offset:49152
	ds_read_b128 v[186:189], v148 offset:50176
	ds_read_b128 v[190:193], v148 offset:51200
	ds_read_b128 v[194:197], v148 offset:52224
	ds_read_b128 v[198:201], v148 offset:53248
	ds_read_b128 v[202:205], v148 offset:54272
	ds_read_b128 v[206:209], v148 offset:55296
	ds_read_b128 v[210:213], v148 offset:56320
	s_add_i32 s84, s86, s40
	s_add_u32 s100, s50, s38
	s_addc_u32 s101, s51, s39
	s_mov_b32 m0, s84
	s_nop 0
	global_load_lds_dwordx4 v143, s[100:101]
	s_add_i32 m0, s84, 0x2000
	s_nop 0
	s_add_u32 s50, s50, 0x20080
	s_addc_u32 s51, s51, 0
	s_add_i32 s84, s87, s40
	global_load_lds_dwordx4 v144, s[100:101]
	s_mov_b32 m0, s84
	s_nop 0
	global_load_lds_dwordx4 v143, s[50:51]
	s_add_i32 m0, s84, 0x2000
	s_nop 0
	global_load_lds_dwordx4 v144, s[50:51]
	s_mov_b32 m0, s75
	s_add_u32 s100, s46, s38
	s_addc_u32 s101, s47, s39
	v_mov_b32_e32 v0, v133
	global_load_lds_dwordx4 v132, s[100:101]
	s_mov_b32 m0, s78
	s_nop 0
	global_load_lds_dwordx4 v133, s[100:101]
	s_waitcnt vmcnt(8) lgkmcnt(0)
	s_setprio 1
	s_barrier
	v_mfma_i32_16x16x64_i8 v[62:65], v[150:153], v[182:185], v[62:65]
	v_mfma_i32_16x16x64_i8 v[58:61], v[158:161], v[182:185], v[58:61]
	v_mfma_i32_16x16x64_i8 v[46:49], v[150:153], v[190:193], v[46:49]
	v_mfma_i32_16x16x64_i8 v[42:45], v[158:161], v[190:193], v[42:45]
	v_mfma_i32_16x16x64_i8 v[30:33], v[150:153], v[198:201], v[30:33]
	v_mfma_i32_16x16x64_i8 v[26:29], v[158:161], v[198:201], v[26:29]
	v_mfma_i32_16x16x64_i8 v[14:17], v[150:153], v[206:209], v[14:17]
	v_mfma_i32_16x16x64_i8 v[10:13], v[158:161], v[206:209], v[10:13]
	v_mfma_i32_16x16x64_i8 v[62:65], v[154:157], v[186:189], v[62:65]
	v_mfma_i32_16x16x64_i8 v[58:61], v[162:165], v[186:189], v[58:61]
	v_mfma_i32_16x16x64_i8 v[46:49], v[154:157], v[194:197], v[46:49]
	v_mfma_i32_16x16x64_i8 v[42:45], v[162:165], v[194:197], v[42:45]
	v_mfma_i32_16x16x64_i8 v[30:33], v[154:157], v[202:205], v[30:33]
	v_mfma_i32_16x16x64_i8 v[26:29], v[162:165], v[202:205], v[26:29]
	v_mfma_i32_16x16x64_i8 v[14:17], v[154:157], v[210:213], v[14:17]
	v_mfma_i32_16x16x64_i8 v[10:13], v[162:165], v[210:213], v[10:13]
	s_setprio 0
	s_setprio 1
	v_mfma_i32_16x16x64_i8 v[54:57], v[166:169], v[182:185], v[54:57]
	v_mfma_i32_16x16x64_i8 v[50:53], v[174:177], v[182:185], v[50:53]
	v_mfma_i32_16x16x64_i8 v[38:41], v[166:169], v[190:193], v[38:41]
	v_mfma_i32_16x16x64_i8 v[34:37], v[174:177], v[190:193], v[34:37]
	v_mfma_i32_16x16x64_i8 v[22:25], v[166:169], v[198:201], v[22:25]
	v_mfma_i32_16x16x64_i8 v[18:21], v[174:177], v[198:201], v[18:21]
	v_mfma_i32_16x16x64_i8 v[6:9], v[166:169], v[206:209], v[6:9]
	v_mfma_i32_16x16x64_i8 v[2:5], v[174:177], v[206:209], v[2:5]
	v_mfma_i32_16x16x64_i8 v[54:57], v[170:173], v[186:189], v[54:57]
	v_mfma_i32_16x16x64_i8 v[50:53], v[178:181], v[186:189], v[50:53]
	v_mfma_i32_16x16x64_i8 v[38:41], v[170:173], v[194:197], v[38:41]
	v_mfma_i32_16x16x64_i8 v[34:37], v[178:181], v[194:197], v[34:37]
	v_mfma_i32_16x16x64_i8 v[22:25], v[170:173], v[202:205], v[22:25]
	v_mfma_i32_16x16x64_i8 v[18:21], v[178:181], v[202:205], v[18:21]
	v_mfma_i32_16x16x64_i8 v[6:9], v[170:173], v[210:213], v[6:9]
	v_mfma_i32_16x16x64_i8 v[2:5], v[178:181], v[210:213], v[2:5]
	s_setprio 0
	s_barrier
	s_add_i32 s65, s65, 2
	s_add_u32 s48, s48, 0x100
	s_addc_u32 s49, s49, 0
	s_add_u32 s25, s25, 0x100
	s_addc_u32 s64, s64, 0
	s_cmp_gt_u32 s65, 5
	s_cbranch_scc0 .LBB0_445

.LBB0_626:
	s_add_u32 s58, s14, s50
	s_addc_u32 s59, s15, s51
	s_add_u32 s46, s58, 0x100
	s_addc_u32 s47, s59, 0
	s_and_b64 s[4:5], s[48:49], exec
	s_cselect_b32 s47, s15, s47
	s_cselect_b32 s46, s14, s46
	s_add_u32 s4, s16, s50
	s_addc_u32 s5, s17, s51
	s_add_u32 s50, s4, 0x100
	s_addc_u32 s51, s5, 0
	s_add_i32 s78, 0, 0x10000
	s_and_b64 s[4:5], s[48:49], exec
	s_cselect_b32 s49, s17, s51
	s_cselect_b32 s48, s16, s50
	s_add_i32 s4, 0, 0x14000
	s_add_u32 s96, s58, 0x80080
	s_addc_u32 s97, s59, 0
	s_add_i32 s82, s78, s42
	s_add_i32 m0, s43, 0xc000
	s_add_i32 s5, s43, 0xe000
	s_add_i32 s76, s82, 0x2000
	v_add_u32_e32 v0, s78, v136
	s_add_u32 s94, s48, 0x40000
	ds_read_b128 v[138:141], v0
	ds_read_b128 v[142:145], v0 offset:1024
	ds_read_b128 v[146:149], v0 offset:2048
	ds_read_b128 v[150:153], v0 offset:3072
	s_addc_u32 s95, s49, 0
	s_add_i32 s77, s4, s42
	ds_read_b128 v[154:157], v0 offset:16384
	ds_read_b128 v[158:161], v0 offset:17408
	ds_read_b128 v[162:165], v0 offset:18432
	ds_read_b128 v[166:169], v0 offset:19456
	s_add_i32 s75, s77, 0x2000
	s_add_i32 s74, 0, 0x18000
	s_add_i32 s71, 0, 0x1c000
	s_add_u32 s58, s46, 0x80000
	s_addc_u32 s59, s47, 0
	s_add_i32 s70, s74, s42
	s_add_i32 s69, s70, 0x2000
	s_add_u32 s50, s48, 0x40080
	s_addc_u32 s51, s49, 0
	s_add_i32 s79, s71, s42
	s_add_i32 s78, s79, 0x2000
	ds_read_b128 v[170:173], v137
	ds_read_b128 v[174:177], v137 offset:1024
	ds_read_b128 v[178:181], v137 offset:2048
	ds_read_b128 v[182:185], v137 offset:3072
	ds_read_b128 v[186:189], v137 offset:4096
	ds_read_b128 v[190:193], v137 offset:5120
	ds_read_b128 v[194:197], v137 offset:6144
	ds_read_b128 v[198:201], v137 offset:7168
	s_nop 0
	global_load_lds_dwordx4 v130, s[96:97]
	s_mov_b32 m0, s5
	s_nop 0
	global_load_lds_dwordx4 v132, s[96:97]
	s_waitcnt vmcnt(8) lgkmcnt(0)
	s_setprio 1
	s_barrier
	v_mfma_f32_16x16x32_bf16 v[126:129], v[138:141], v[170:173], v[126:129]
	v_mfma_f32_16x16x32_bf16 v[122:125], v[146:149], v[170:173], v[122:125]
	v_mfma_f32_16x16x32_bf16 v[118:121], v[138:141], v[178:181], v[118:121]
	v_mfma_f32_16x16x32_bf16 v[110:113], v[146:149], v[178:181], v[110:113]
	v_mfma_f32_16x16x32_bf16 v[102:105], v[138:141], v[186:189], v[102:105]
	v_mfma_f32_16x16x32_bf16 v[94:97], v[146:149], v[186:189], v[94:97]
	v_mfma_f32_16x16x32_bf16 v[86:89], v[138:141], v[194:197], v[86:89]
	v_mfma_f32_16x16x32_bf16 v[78:81], v[146:149], v[194:197], v[78:81]
	v_mfma_f32_16x16x32_bf16 v[126:129], v[142:145], v[174:177], v[126:129]
	v_mfma_f32_16x16x32_bf16 v[122:125], v[150:153], v[174:177], v[122:125]
	v_mfma_f32_16x16x32_bf16 v[118:121], v[142:145], v[182:185], v[118:121]
	v_mfma_f32_16x16x32_bf16 v[110:113], v[150:153], v[182:185], v[110:113]
	v_mfma_f32_16x16x32_bf16 v[102:105], v[142:145], v[190:193], v[102:105]
	v_mfma_f32_16x16x32_bf16 v[94:97], v[150:153], v[190:193], v[94:97]
	v_mfma_f32_16x16x32_bf16 v[86:89], v[142:145], v[198:201], v[86:89]
	v_mfma_f32_16x16x32_bf16 v[78:81], v[150:153], v[198:201], v[78:81]
	s_setprio 0
	s_setprio 1
	v_mfma_f32_16x16x32_bf16 v[114:117], v[154:157], v[170:173], v[114:117]
	v_mfma_f32_16x16x32_bf16 v[106:109], v[162:165], v[170:173], v[106:109]
	v_mfma_f32_16x16x32_bf16 v[98:101], v[154:157], v[178:181], v[98:101]
	v_mfma_f32_16x16x32_bf16 v[90:93], v[162:165], v[178:181], v[90:93]
	v_mfma_f32_16x16x32_bf16 v[82:85], v[154:157], v[186:189], v[82:85]
	v_mfma_f32_16x16x32_bf16 v[74:77], v[162:165], v[186:189], v[74:77]
	v_mfma_f32_16x16x32_bf16 v[70:73], v[154:157], v[194:197], v[70:73]
	v_mfma_f32_16x16x32_bf16 v[62:65], v[162:165], v[194:197], v[62:65]
	v_mfma_f32_16x16x32_bf16 v[114:117], v[158:161], v[174:177], v[114:117]
	v_mfma_f32_16x16x32_bf16 v[106:109], v[166:169], v[174:177], v[106:109]
	v_mfma_f32_16x16x32_bf16 v[98:101], v[158:161], v[182:185], v[98:101]
	v_mfma_f32_16x16x32_bf16 v[90:93], v[166:169], v[182:185], v[90:93]
	v_mfma_f32_16x16x32_bf16 v[82:85], v[158:161], v[190:193], v[82:85]
	v_mfma_f32_16x16x32_bf16 v[74:77], v[166:169], v[190:193], v[74:77]
	v_mfma_f32_16x16x32_bf16 v[70:73], v[158:161], v[198:201], v[70:73]
	v_mfma_f32_16x16x32_bf16 v[62:65], v[166:169], v[198:201], v[62:65]
	s_setprio 0
	s_barrier
	ds_read_b128 v[170:173], v137 offset:16384
	ds_read_b128 v[174:177], v137 offset:17408
	ds_read_b128 v[178:181], v137 offset:18432
	ds_read_b128 v[182:185], v137 offset:19456
	ds_read_b128 v[186:189], v137 offset:20480
	ds_read_b128 v[190:193], v137 offset:21504
	ds_read_b128 v[194:197], v137 offset:22528
	ds_read_b128 v[198:201], v137 offset:23552
	s_mov_b32 m0, s82
	s_nop 0
	global_load_lds_dwordx4 v131, s[48:49]
	s_mov_b32 m0, s76
	s_nop 0
	global_load_lds_dwordx4 v133, s[48:49]
	s_mov_b32 m0, s77
	s_nop 0
	global_load_lds_dwordx4 v131, s[94:95]
	s_mov_b32 m0, s75
	s_nop 0
	global_load_lds_dwordx4 v133, s[94:95]
	s_mov_b32 m0, s43
	s_nop 0
	global_load_lds_dwordx4 v130, s[46:47]
	s_mov_b32 m0, s60
	s_nop 0
	global_load_lds_dwordx4 v132, s[46:47]
	s_waitcnt vmcnt(8) lgkmcnt(0)
	s_setprio 1
	s_barrier
	v_mfma_f32_16x16x32_bf16 v[66:69], v[138:141], v[170:173], v[66:69]
	v_mfma_f32_16x16x32_bf16 v[58:61], v[146:149], v[170:173], v[58:61]
	v_mfma_f32_16x16x32_bf16 v[54:57], v[138:141], v[178:181], v[54:57]
	v_mfma_f32_16x16x32_bf16 v[46:49], v[146:149], v[178:181], v[46:49]
	v_mfma_f32_16x16x32_bf16 v[38:41], v[138:141], v[186:189], v[38:41]
	v_mfma_f32_16x16x32_bf16 v[30:33], v[146:149], v[186:189], v[30:33]
	v_mfma_f32_16x16x32_bf16 v[22:25], v[138:141], v[194:197], v[22:25]
	v_mfma_f32_16x16x32_bf16 v[14:17], v[146:149], v[194:197], v[14:17]
	v_mfma_f32_16x16x32_bf16 v[66:69], v[142:145], v[174:177], v[66:69]
	v_mfma_f32_16x16x32_bf16 v[58:61], v[150:153], v[174:177], v[58:61]
	v_mfma_f32_16x16x32_bf16 v[54:57], v[142:145], v[182:185], v[54:57]
	v_mfma_f32_16x16x32_bf16 v[46:49], v[150:153], v[182:185], v[46:49]
	v_mfma_f32_16x16x32_bf16 v[38:41], v[142:145], v[190:193], v[38:41]
	v_mfma_f32_16x16x32_bf16 v[30:33], v[150:153], v[190:193], v[30:33]
	v_mfma_f32_16x16x32_bf16 v[22:25], v[142:145], v[198:201], v[22:25]
	v_mfma_f32_16x16x32_bf16 v[14:17], v[150:153], v[198:201], v[14:17]
	s_setprio 0
	s_setprio 1
	v_mfma_f32_16x16x32_bf16 v[50:53], v[154:157], v[170:173], v[50:53]
	v_mfma_f32_16x16x32_bf16 v[42:45], v[162:165], v[170:173], v[42:45]
	v_mfma_f32_16x16x32_bf16 v[34:37], v[154:157], v[178:181], v[34:37]
	v_mfma_f32_16x16x32_bf16 v[26:29], v[162:165], v[178:181], v[26:29]
	v_mfma_f32_16x16x32_bf16 v[18:21], v[154:157], v[186:189], v[18:21]
	v_mfma_f32_16x16x32_bf16 v[10:13], v[162:165], v[186:189], v[10:13]
	v_mfma_f32_16x16x32_bf16 v[6:9], v[154:157], v[194:197], v[6:9]
	v_mfma_f32_16x16x32_bf16 v[2:5], v[162:165], v[194:197], v[2:5]
	v_mfma_f32_16x16x32_bf16 v[50:53], v[158:161], v[174:177], v[50:53]
	v_mfma_f32_16x16x32_bf16 v[42:45], v[166:169], v[174:177], v[42:45]
	v_mfma_f32_16x16x32_bf16 v[34:37], v[158:161], v[182:185], v[34:37]
	v_mfma_f32_16x16x32_bf16 v[26:29], v[166:169], v[182:185], v[26:29]
	v_mfma_f32_16x16x32_bf16 v[18:21], v[158:161], v[190:193], v[18:21]
	v_mfma_f32_16x16x32_bf16 v[10:13], v[166:169], v[190:193], v[10:13]
	v_mfma_f32_16x16x32_bf16 v[6:9], v[158:161], v[198:201], v[6:9]
	v_mfma_f32_16x16x32_bf16 v[2:5], v[166:169], v[198:201], v[2:5]
	s_setprio 0
	s_barrier
	ds_read_b128 v[138:141], v0 offset:32768
	ds_read_b128 v[142:145], v0 offset:33792
	ds_read_b128 v[146:149], v0 offset:34816
	ds_read_b128 v[150:153], v0 offset:35840
	ds_read_b128 v[154:157], v0 offset:49152
	ds_read_b128 v[158:161], v0 offset:50176
	ds_read_b128 v[162:165], v0 offset:51200
	ds_read_b128 v[166:169], v0 offset:52224
	s_mov_b32 m0, s65
	ds_read_b128 v[170:173], v137 offset:32768
	ds_read_b128 v[174:177], v137 offset:33792
	ds_read_b128 v[178:181], v137 offset:34816
	ds_read_b128 v[182:185], v137 offset:35840
	ds_read_b128 v[186:189], v137 offset:36864
	ds_read_b128 v[190:193], v137 offset:37888
	ds_read_b128 v[194:197], v137 offset:38912
	ds_read_b128 v[198:201], v137 offset:39936
	s_nop 0
	global_load_lds_dwordx4 v130, s[58:59]
	s_mov_b32 m0, s66
	s_nop 0
	global_load_lds_dwordx4 v132, s[58:59]
	s_waitcnt vmcnt(8) lgkmcnt(0)
	s_setprio 1
	s_barrier
	v_mfma_f32_16x16x32_bf16 v[126:129], v[138:141], v[170:173], v[126:129]
	v_mfma_f32_16x16x32_bf16 v[122:125], v[146:149], v[170:173], v[122:125]
	v_mfma_f32_16x16x32_bf16 v[118:121], v[138:141], v[178:181], v[118:121]
	v_mfma_f32_16x16x32_bf16 v[110:113], v[146:149], v[178:181], v[110:113]
	v_mfma_f32_16x16x32_bf16 v[102:105], v[138:141], v[186:189], v[102:105]
	v_mfma_f32_16x16x32_bf16 v[94:97], v[146:149], v[186:189], v[94:97]
	v_mfma_f32_16x16x32_bf16 v[86:89], v[138:141], v[194:197], v[86:89]
	v_mfma_f32_16x16x32_bf16 v[78:81], v[146:149], v[194:197], v[78:81]
	v_mfma_f32_16x16x32_bf16 v[126:129], v[142:145], v[174:177], v[126:129]
	v_mfma_f32_16x16x32_bf16 v[122:125], v[150:153], v[174:177], v[122:125]
	v_mfma_f32_16x16x32_bf16 v[118:121], v[142:145], v[182:185], v[118:121]
	v_mfma_f32_16x16x32_bf16 v[110:113], v[150:153], v[182:185], v[110:113]
	v_mfma_f32_16x16x32_bf16 v[102:105], v[142:145], v[190:193], v[102:105]
	v_mfma_f32_16x16x32_bf16 v[94:97], v[150:153], v[190:193], v[94:97]
	v_mfma_f32_16x16x32_bf16 v[86:89], v[142:145], v[198:201], v[86:89]
	v_mfma_f32_16x16x32_bf16 v[78:81], v[150:153], v[198:201], v[78:81]
	s_setprio 0
	s_setprio 1
	v_mfma_f32_16x16x32_bf16 v[114:117], v[154:157], v[170:173], v[114:117]
	v_mfma_f32_16x16x32_bf16 v[106:109], v[162:165], v[170:173], v[106:109]
	v_mfma_f32_16x16x32_bf16 v[98:101], v[154:157], v[178:181], v[98:101]
	v_mfma_f32_16x16x32_bf16 v[90:93], v[162:165], v[178:181], v[90:93]
	v_mfma_f32_16x16x32_bf16 v[82:85], v[154:157], v[186:189], v[82:85]
	v_mfma_f32_16x16x32_bf16 v[74:77], v[162:165], v[186:189], v[74:77]
	v_mfma_f32_16x16x32_bf16 v[70:73], v[154:157], v[194:197], v[70:73]
	v_mfma_f32_16x16x32_bf16 v[62:65], v[162:165], v[194:197], v[62:65]
	v_mfma_f32_16x16x32_bf16 v[114:117], v[158:161], v[174:177], v[114:117]
	v_mfma_f32_16x16x32_bf16 v[106:109], v[166:169], v[174:177], v[106:109]
	v_mfma_f32_16x16x32_bf16 v[98:101], v[158:161], v[182:185], v[98:101]
	v_mfma_f32_16x16x32_bf16 v[90:93], v[166:169], v[182:185], v[90:93]
	v_mfma_f32_16x16x32_bf16 v[82:85], v[158:161], v[190:193], v[82:85]
	v_mfma_f32_16x16x32_bf16 v[74:77], v[166:169], v[190:193], v[74:77]
	v_mfma_f32_16x16x32_bf16 v[70:73], v[158:161], v[198:201], v[70:73]
	v_mfma_f32_16x16x32_bf16 v[62:65], v[166:169], v[198:201], v[62:65]
	s_setprio 0
	s_barrier
	ds_read_b128 v[170:173], v137 offset:49152
	ds_read_b128 v[174:177], v137 offset:50176
	ds_read_b128 v[178:181], v137 offset:51200
	ds_read_b128 v[182:185], v137 offset:52224
	ds_read_b128 v[186:189], v137 offset:53248
	ds_read_b128 v[190:193], v137 offset:54272
	ds_read_b128 v[194:197], v137 offset:55296
	ds_read_b128 v[198:201], v137 offset:56320
	s_mov_b32 m0, s70
	s_add_u32 s100, s48, s38
	s_addc_u32 s101, s49, s39
	global_load_lds_dwordx4 v131, s[100:101]
	s_mov_b32 m0, s69
	s_nop 0
	global_load_lds_dwordx4 v133, s[100:101]
	s_mov_b32 m0, s79
	s_nop 0
	global_load_lds_dwordx4 v131, s[50:51]
	s_mov_b32 m0, s78
	s_nop 0
	global_load_lds_dwordx4 v133, s[50:51]
	s_mov_b32 m0, s67
	s_add_u32 s100, s46, s38
	s_addc_u32 s101, s47, s39
	v_mov_b32_e32 v0, v132
	global_load_lds_dwordx4 v130, s[100:101]
	s_mov_b32 m0, s68
	s_nop 0
	global_load_lds_dwordx4 v132, s[100:101]
	s_waitcnt vmcnt(8) lgkmcnt(0)
	s_setprio 1
	s_barrier
	v_mfma_f32_16x16x32_bf16 v[66:69], v[138:141], v[170:173], v[66:69]
	v_mfma_f32_16x16x32_bf16 v[58:61], v[146:149], v[170:173], v[58:61]
	v_mfma_f32_16x16x32_bf16 v[54:57], v[138:141], v[178:181], v[54:57]
	v_mfma_f32_16x16x32_bf16 v[46:49], v[146:149], v[178:181], v[46:49]
	v_mfma_f32_16x16x32_bf16 v[38:41], v[138:141], v[186:189], v[38:41]
	v_mfma_f32_16x16x32_bf16 v[30:33], v[146:149], v[186:189], v[30:33]
	v_mfma_f32_16x16x32_bf16 v[22:25], v[138:141], v[194:197], v[22:25]
	v_mfma_f32_16x16x32_bf16 v[14:17], v[146:149], v[194:197], v[14:17]
	v_mfma_f32_16x16x32_bf16 v[66:69], v[142:145], v[174:177], v[66:69]
	v_mfma_f32_16x16x32_bf16 v[58:61], v[150:153], v[174:177], v[58:61]
	v_mfma_f32_16x16x32_bf16 v[54:57], v[142:145], v[182:185], v[54:57]
	v_mfma_f32_16x16x32_bf16 v[46:49], v[150:153], v[182:185], v[46:49]
	v_mfma_f32_16x16x32_bf16 v[38:41], v[142:145], v[190:193], v[38:41]
	v_mfma_f32_16x16x32_bf16 v[30:33], v[150:153], v[190:193], v[30:33]
	v_mfma_f32_16x16x32_bf16 v[22:25], v[142:145], v[198:201], v[22:25]
	v_mfma_f32_16x16x32_bf16 v[14:17], v[150:153], v[198:201], v[14:17]
	s_setprio 0
	s_setprio 1
	v_mfma_f32_16x16x32_bf16 v[50:53], v[154:157], v[170:173], v[50:53]
	v_mfma_f32_16x16x32_bf16 v[42:45], v[162:165], v[170:173], v[42:45]
	v_mfma_f32_16x16x32_bf16 v[34:37], v[154:157], v[178:181], v[34:37]
	v_mfma_f32_16x16x32_bf16 v[26:29], v[162:165], v[178:181], v[26:29]
	v_mfma_f32_16x16x32_bf16 v[18:21], v[154:157], v[186:189], v[18:21]
	v_mfma_f32_16x16x32_bf16 v[10:13], v[162:165], v[186:189], v[10:13]
	v_mfma_f32_16x16x32_bf16 v[6:9], v[154:157], v[194:197], v[6:9]
	v_mfma_f32_16x16x32_bf16 v[2:5], v[162:165], v[194:197], v[2:5]
	v_mfma_f32_16x16x32_bf16 v[50:53], v[158:161], v[174:177], v[50:53]
	v_mfma_f32_16x16x32_bf16 v[42:45], v[166:169], v[174:177], v[42:45]
	v_mfma_f32_16x16x32_bf16 v[34:37], v[158:161], v[182:185], v[34:37]
	v_mfma_f32_16x16x32_bf16 v[26:29], v[166:169], v[182:185], v[26:29]
	v_mfma_f32_16x16x32_bf16 v[18:21], v[158:161], v[190:193], v[18:21]
	v_mfma_f32_16x16x32_bf16 v[10:13], v[166:169], v[190:193], v[10:13]
	v_mfma_f32_16x16x32_bf16 v[6:9], v[158:161], v[198:201], v[6:9]
	v_mfma_f32_16x16x32_bf16 v[2:5], v[166:169], v[198:201], v[2:5]
	s_setprio 0
	s_barrier
	s_andn2_b64 vcc, exec, s[22:23]
	s_mov_b64 s[48:49], -1
	s_mov_b64 s[22:23], 0
	s_mov_b64 s[50:51], 0x100
	s_cbranch_vccz .LBB0_626
	s_cmpk_lt_u32 s25, 0x100
	s_cbranch_scc0 .LBB0_629
	s_barrier

.LBB0_634:
	s_add_u32 s50, s2, s48
	s_addc_u32 s51, s3, s49
	s_add_u32 s22, s50, 0x100
	s_addc_u32 s23, s51, 0
	s_and_b64 s[4:5], s[46:47], exec
	s_cselect_b32 s23, s3, s23
	s_cselect_b32 s22, s2, s22
	s_add_u32 s4, s14, s48
	s_addc_u32 s5, s15, s49
	s_add_u32 s48, s4, 0x900
	s_addc_u32 s49, s5, 0
	s_add_i32 s78, 0, 0x10000
	s_and_b64 s[4:5], s[46:47], exec
	s_cselect_b32 s47, s66, s49
	s_cselect_b32 s46, s65, s48
	s_add_i32 s4, 0, 0x14000
	s_add_u32 s94, s50, 0x40080
	s_addc_u32 s95, s51, 0
	s_add_i32 s82, s78, s40
	s_add_i32 m0, s41, 0xc000
	s_add_i32 s5, s41, 0xe000
	s_add_i32 s76, s82, 0x2000
	v_add_u32_e32 v0, s78, v136
	s_add_u32 s58, s46, 0x80000
	ds_read_b128 v[138:141], v0
	ds_read_b128 v[142:145], v0 offset:1024
	ds_read_b128 v[146:149], v0 offset:2048
	ds_read_b128 v[150:153], v0 offset:3072
	s_addc_u32 s59, s47, 0
	s_add_i32 s77, s4, s40
	ds_read_b128 v[154:157], v0 offset:16384
	ds_read_b128 v[158:161], v0 offset:17408
	ds_read_b128 v[162:165], v0 offset:18432
	ds_read_b128 v[166:169], v0 offset:19456
	s_add_i32 s75, s77, 0x2000
	s_add_i32 s74, 0, 0x18000
	s_add_i32 s71, 0, 0x1c000
	s_add_u32 s50, s22, 0x40000
	s_addc_u32 s51, s23, 0
	s_add_i32 s70, s74, s40
	s_add_i32 s69, s70, 0x2000
	s_add_u32 s48, s46, 0x80080
	s_addc_u32 s49, s47, 0
	s_add_i32 s79, s71, s40
	s_add_i32 s78, s79, 0x2000
	ds_read_b128 v[170:173], v137
	ds_read_b128 v[174:177], v137 offset:1024
	ds_read_b128 v[178:181], v137 offset:2048
	ds_read_b128 v[182:185], v137 offset:3072
	ds_read_b128 v[186:189], v137 offset:4096
	ds_read_b128 v[190:193], v137 offset:5120
	ds_read_b128 v[194:197], v137 offset:6144
	ds_read_b128 v[198:201], v137 offset:7168
	s_nop 0
	global_load_lds_dwordx4 v130, s[94:95]
	s_mov_b32 m0, s5
	s_nop 0
	global_load_lds_dwordx4 v132, s[94:95]
	s_waitcnt vmcnt(8) lgkmcnt(0)
	s_setprio 1
	s_barrier
	v_mfma_f32_16x16x32_bf16 v[126:129], v[138:141], v[170:173], v[126:129]
	v_mfma_f32_16x16x32_bf16 v[122:125], v[146:149], v[170:173], v[122:125]
	v_mfma_f32_16x16x32_bf16 v[118:121], v[138:141], v[178:181], v[118:121]
	v_mfma_f32_16x16x32_bf16 v[110:113], v[146:149], v[178:181], v[110:113]
	v_mfma_f32_16x16x32_bf16 v[102:105], v[138:141], v[186:189], v[102:105]
	v_mfma_f32_16x16x32_bf16 v[94:97], v[146:149], v[186:189], v[94:97]
	v_mfma_f32_16x16x32_bf16 v[86:89], v[138:141], v[194:197], v[86:89]
	v_mfma_f32_16x16x32_bf16 v[78:81], v[146:149], v[194:197], v[78:81]
	v_mfma_f32_16x16x32_bf16 v[126:129], v[142:145], v[174:177], v[126:129]
	v_mfma_f32_16x16x32_bf16 v[122:125], v[150:153], v[174:177], v[122:125]
	v_mfma_f32_16x16x32_bf16 v[118:121], v[142:145], v[182:185], v[118:121]
	v_mfma_f32_16x16x32_bf16 v[110:113], v[150:153], v[182:185], v[110:113]
	v_mfma_f32_16x16x32_bf16 v[102:105], v[142:145], v[190:193], v[102:105]
	v_mfma_f32_16x16x32_bf16 v[94:97], v[150:153], v[190:193], v[94:97]
	v_mfma_f32_16x16x32_bf16 v[86:89], v[142:145], v[198:201], v[86:89]
	v_mfma_f32_16x16x32_bf16 v[78:81], v[150:153], v[198:201], v[78:81]
	s_setprio 0
	s_setprio 1
	v_mfma_f32_16x16x32_bf16 v[114:117], v[154:157], v[170:173], v[114:117]
	v_mfma_f32_16x16x32_bf16 v[106:109], v[162:165], v[170:173], v[106:109]
	v_mfma_f32_16x16x32_bf16 v[98:101], v[154:157], v[178:181], v[98:101]
	v_mfma_f32_16x16x32_bf16 v[90:93], v[162:165], v[178:181], v[90:93]
	v_mfma_f32_16x16x32_bf16 v[82:85], v[154:157], v[186:189], v[82:85]
	v_mfma_f32_16x16x32_bf16 v[74:77], v[162:165], v[186:189], v[74:77]
	v_mfma_f32_16x16x32_bf16 v[70:73], v[154:157], v[194:197], v[70:73]
	v_mfma_f32_16x16x32_bf16 v[62:65], v[162:165], v[194:197], v[62:65]
	v_mfma_f32_16x16x32_bf16 v[114:117], v[158:161], v[174:177], v[114:117]
	v_mfma_f32_16x16x32_bf16 v[106:109], v[166:169], v[174:177], v[106:109]
	v_mfma_f32_16x16x32_bf16 v[98:101], v[158:161], v[182:185], v[98:101]
	v_mfma_f32_16x16x32_bf16 v[90:93], v[166:169], v[182:185], v[90:93]
	v_mfma_f32_16x16x32_bf16 v[82:85], v[158:161], v[190:193], v[82:85]
	v_mfma_f32_16x16x32_bf16 v[74:77], v[166:169], v[190:193], v[74:77]
	v_mfma_f32_16x16x32_bf16 v[70:73], v[158:161], v[198:201], v[70:73]
	v_mfma_f32_16x16x32_bf16 v[62:65], v[166:169], v[198:201], v[62:65]
	s_setprio 0
	s_barrier
	ds_read_b128 v[170:173], v137 offset:16384
	ds_read_b128 v[174:177], v137 offset:17408
	ds_read_b128 v[178:181], v137 offset:18432
	ds_read_b128 v[182:185], v137 offset:19456
	ds_read_b128 v[186:189], v137 offset:20480
	ds_read_b128 v[190:193], v137 offset:21504
	ds_read_b128 v[194:197], v137 offset:22528
	ds_read_b128 v[198:201], v137 offset:23552
	s_mov_b32 m0, s82
	s_nop 0
	global_load_lds_dwordx4 v131, s[46:47]
	s_mov_b32 m0, s76
	s_nop 0
	global_load_lds_dwordx4 v133, s[46:47]
	s_mov_b32 m0, s77
	s_nop 0
	global_load_lds_dwordx4 v131, s[58:59]
	s_mov_b32 m0, s75
	s_nop 0
	global_load_lds_dwordx4 v133, s[58:59]
	s_mov_b32 m0, s41
	s_nop 0
	global_load_lds_dwordx4 v130, s[22:23]
	s_mov_b32 m0, s42
	s_nop 0
	global_load_lds_dwordx4 v132, s[22:23]
	s_waitcnt vmcnt(8) lgkmcnt(0)
	s_setprio 1
	s_barrier
	v_mfma_f32_16x16x32_bf16 v[66:69], v[138:141], v[170:173], v[66:69]
	v_mfma_f32_16x16x32_bf16 v[58:61], v[146:149], v[170:173], v[58:61]
	v_mfma_f32_16x16x32_bf16 v[54:57], v[138:141], v[178:181], v[54:57]
	v_mfma_f32_16x16x32_bf16 v[46:49], v[146:149], v[178:181], v[46:49]
	v_mfma_f32_16x16x32_bf16 v[38:41], v[138:141], v[186:189], v[38:41]
	v_mfma_f32_16x16x32_bf16 v[30:33], v[146:149], v[186:189], v[30:33]
	v_mfma_f32_16x16x32_bf16 v[22:25], v[138:141], v[194:197], v[22:25]
	v_mfma_f32_16x16x32_bf16 v[14:17], v[146:149], v[194:197], v[14:17]
	v_mfma_f32_16x16x32_bf16 v[66:69], v[142:145], v[174:177], v[66:69]
	v_mfma_f32_16x16x32_bf16 v[58:61], v[150:153], v[174:177], v[58:61]
	v_mfma_f32_16x16x32_bf16 v[54:57], v[142:145], v[182:185], v[54:57]
	v_mfma_f32_16x16x32_bf16 v[46:49], v[150:153], v[182:185], v[46:49]
	v_mfma_f32_16x16x32_bf16 v[38:41], v[142:145], v[190:193], v[38:41]
	v_mfma_f32_16x16x32_bf16 v[30:33], v[150:153], v[190:193], v[30:33]
	v_mfma_f32_16x16x32_bf16 v[22:25], v[142:145], v[198:201], v[22:25]
	v_mfma_f32_16x16x32_bf16 v[14:17], v[150:153], v[198:201], v[14:17]
	s_setprio 0
	s_setprio 1
	v_mfma_f32_16x16x32_bf16 v[50:53], v[154:157], v[170:173], v[50:53]
	v_mfma_f32_16x16x32_bf16 v[42:45], v[162:165], v[170:173], v[42:45]
	v_mfma_f32_16x16x32_bf16 v[34:37], v[154:157], v[178:181], v[34:37]
	v_mfma_f32_16x16x32_bf16 v[26:29], v[162:165], v[178:181], v[26:29]
	v_mfma_f32_16x16x32_bf16 v[18:21], v[154:157], v[186:189], v[18:21]
	v_mfma_f32_16x16x32_bf16 v[10:13], v[162:165], v[186:189], v[10:13]
	v_mfma_f32_16x16x32_bf16 v[6:9], v[154:157], v[194:197], v[6:9]
	v_mfma_f32_16x16x32_bf16 v[2:5], v[162:165], v[194:197], v[2:5]
	v_mfma_f32_16x16x32_bf16 v[50:53], v[158:161], v[174:177], v[50:53]
	v_mfma_f32_16x16x32_bf16 v[42:45], v[166:169], v[174:177], v[42:45]
	v_mfma_f32_16x16x32_bf16 v[34:37], v[158:161], v[182:185], v[34:37]
	v_mfma_f32_16x16x32_bf16 v[26:29], v[166:169], v[182:185], v[26:29]
	v_mfma_f32_16x16x32_bf16 v[18:21], v[158:161], v[190:193], v[18:21]
	v_mfma_f32_16x16x32_bf16 v[10:13], v[166:169], v[190:193], v[10:13]
	v_mfma_f32_16x16x32_bf16 v[6:9], v[158:161], v[198:201], v[6:9]
	v_mfma_f32_16x16x32_bf16 v[2:5], v[166:169], v[198:201], v[2:5]
	s_setprio 0
	s_barrier
	ds_read_b128 v[138:141], v0 offset:32768
	ds_read_b128 v[142:145], v0 offset:33792
	ds_read_b128 v[146:149], v0 offset:34816
	ds_read_b128 v[150:153], v0 offset:35840
	ds_read_b128 v[154:157], v0 offset:49152
	ds_read_b128 v[158:161], v0 offset:50176
	ds_read_b128 v[162:165], v0 offset:51200
	ds_read_b128 v[166:169], v0 offset:52224
	s_mov_b32 m0, s43
	ds_read_b128 v[170:173], v137 offset:32768
	ds_read_b128 v[174:177], v137 offset:33792
	ds_read_b128 v[178:181], v137 offset:34816
	ds_read_b128 v[182:185], v137 offset:35840
	ds_read_b128 v[186:189], v137 offset:36864
	ds_read_b128 v[190:193], v137 offset:37888
	ds_read_b128 v[194:197], v137 offset:38912
	ds_read_b128 v[198:201], v137 offset:39936
	s_nop 0
	global_load_lds_dwordx4 v130, s[50:51]
	s_mov_b32 m0, s64
	s_nop 0
	global_load_lds_dwordx4 v132, s[50:51]
	s_waitcnt vmcnt(8) lgkmcnt(0)
	s_setprio 1
	s_barrier
	v_mfma_f32_16x16x32_bf16 v[126:129], v[138:141], v[170:173], v[126:129]
	v_mfma_f32_16x16x32_bf16 v[122:125], v[146:149], v[170:173], v[122:125]
	v_mfma_f32_16x16x32_bf16 v[118:121], v[138:141], v[178:181], v[118:121]
	v_mfma_f32_16x16x32_bf16 v[110:113], v[146:149], v[178:181], v[110:113]
	v_mfma_f32_16x16x32_bf16 v[102:105], v[138:141], v[186:189], v[102:105]
	v_mfma_f32_16x16x32_bf16 v[94:97], v[146:149], v[186:189], v[94:97]
	v_mfma_f32_16x16x32_bf16 v[86:89], v[138:141], v[194:197], v[86:89]
	v_mfma_f32_16x16x32_bf16 v[78:81], v[146:149], v[194:197], v[78:81]
	v_mfma_f32_16x16x32_bf16 v[126:129], v[142:145], v[174:177], v[126:129]
	v_mfma_f32_16x16x32_bf16 v[122:125], v[150:153], v[174:177], v[122:125]
	v_mfma_f32_16x16x32_bf16 v[118:121], v[142:145], v[182:185], v[118:121]
	v_mfma_f32_16x16x32_bf16 v[110:113], v[150:153], v[182:185], v[110:113]
	v_mfma_f32_16x16x32_bf16 v[102:105], v[142:145], v[190:193], v[102:105]
	v_mfma_f32_16x16x32_bf16 v[94:97], v[150:153], v[190:193], v[94:97]
	v_mfma_f32_16x16x32_bf16 v[86:89], v[142:145], v[198:201], v[86:89]
	v_mfma_f32_16x16x32_bf16 v[78:81], v[150:153], v[198:201], v[78:81]
	s_setprio 0
	s_setprio 1
	v_mfma_f32_16x16x32_bf16 v[114:117], v[154:157], v[170:173], v[114:117]
	v_mfma_f32_16x16x32_bf16 v[106:109], v[162:165], v[170:173], v[106:109]
	v_mfma_f32_16x16x32_bf16 v[98:101], v[154:157], v[178:181], v[98:101]
	v_mfma_f32_16x16x32_bf16 v[90:93], v[162:165], v[178:181], v[90:93]
	v_mfma_f32_16x16x32_bf16 v[82:85], v[154:157], v[186:189], v[82:85]
	v_mfma_f32_16x16x32_bf16 v[74:77], v[162:165], v[186:189], v[74:77]
	v_mfma_f32_16x16x32_bf16 v[70:73], v[154:157], v[194:197], v[70:73]
	v_mfma_f32_16x16x32_bf16 v[62:65], v[162:165], v[194:197], v[62:65]
	v_mfma_f32_16x16x32_bf16 v[114:117], v[158:161], v[174:177], v[114:117]
	v_mfma_f32_16x16x32_bf16 v[106:109], v[166:169], v[174:177], v[106:109]
	v_mfma_f32_16x16x32_bf16 v[98:101], v[158:161], v[182:185], v[98:101]
	v_mfma_f32_16x16x32_bf16 v[90:93], v[166:169], v[182:185], v[90:93]
	v_mfma_f32_16x16x32_bf16 v[82:85], v[158:161], v[190:193], v[82:85]
	v_mfma_f32_16x16x32_bf16 v[74:77], v[166:169], v[190:193], v[74:77]
	v_mfma_f32_16x16x32_bf16 v[70:73], v[158:161], v[198:201], v[70:73]
	v_mfma_f32_16x16x32_bf16 v[62:65], v[166:169], v[198:201], v[62:65]
	s_setprio 0
	s_barrier
	ds_read_b128 v[170:173], v137 offset:49152
	ds_read_b128 v[174:177], v137 offset:50176
	ds_read_b128 v[178:181], v137 offset:51200
	ds_read_b128 v[182:185], v137 offset:52224
	ds_read_b128 v[186:189], v137 offset:53248
	ds_read_b128 v[190:193], v137 offset:54272
	ds_read_b128 v[194:197], v137 offset:55296
	ds_read_b128 v[198:201], v137 offset:56320
	s_mov_b32 m0, s70
	s_add_u32 s100, s46, s38
	s_addc_u32 s101, s47, s39
	global_load_lds_dwordx4 v131, s[100:101]
	s_mov_b32 m0, s69
	s_nop 0
	global_load_lds_dwordx4 v133, s[100:101]
	s_mov_b32 m0, s79
	s_nop 0
	global_load_lds_dwordx4 v131, s[48:49]
	s_mov_b32 m0, s78
	s_nop 0
	global_load_lds_dwordx4 v133, s[48:49]
	s_mov_b32 m0, s67
	s_add_u32 s100, s22, s38
	s_addc_u32 s101, s23, s39
	v_mov_b32_e32 v0, v132
	global_load_lds_dwordx4 v130, s[100:101]
	s_mov_b32 m0, s68
	s_nop 0
	global_load_lds_dwordx4 v132, s[100:101]
	s_waitcnt vmcnt(8) lgkmcnt(0)
	s_setprio 1
	s_barrier
	v_mfma_f32_16x16x32_bf16 v[66:69], v[138:141], v[170:173], v[66:69]
	v_mfma_f32_16x16x32_bf16 v[58:61], v[146:149], v[170:173], v[58:61]
	v_mfma_f32_16x16x32_bf16 v[54:57], v[138:141], v[178:181], v[54:57]
	v_mfma_f32_16x16x32_bf16 v[46:49], v[146:149], v[178:181], v[46:49]
	v_mfma_f32_16x16x32_bf16 v[38:41], v[138:141], v[186:189], v[38:41]
	v_mfma_f32_16x16x32_bf16 v[30:33], v[146:149], v[186:189], v[30:33]
	v_mfma_f32_16x16x32_bf16 v[22:25], v[138:141], v[194:197], v[22:25]
	v_mfma_f32_16x16x32_bf16 v[14:17], v[146:149], v[194:197], v[14:17]
	v_mfma_f32_16x16x32_bf16 v[66:69], v[142:145], v[174:177], v[66:69]
	v_mfma_f32_16x16x32_bf16 v[58:61], v[150:153], v[174:177], v[58:61]
	v_mfma_f32_16x16x32_bf16 v[54:57], v[142:145], v[182:185], v[54:57]
	v_mfma_f32_16x16x32_bf16 v[46:49], v[150:153], v[182:185], v[46:49]
	v_mfma_f32_16x16x32_bf16 v[38:41], v[142:145], v[190:193], v[38:41]
	v_mfma_f32_16x16x32_bf16 v[30:33], v[150:153], v[190:193], v[30:33]
	v_mfma_f32_16x16x32_bf16 v[22:25], v[142:145], v[198:201], v[22:25]
	v_mfma_f32_16x16x32_bf16 v[14:17], v[150:153], v[198:201], v[14:17]
	s_setprio 0
	s_setprio 1
	v_mfma_f32_16x16x32_bf16 v[50:53], v[154:157], v[170:173], v[50:53]
	v_mfma_f32_16x16x32_bf16 v[42:45], v[162:165], v[170:173], v[42:45]
	v_mfma_f32_16x16x32_bf16 v[34:37], v[154:157], v[178:181], v[34:37]
	v_mfma_f32_16x16x32_bf16 v[26:29], v[162:165], v[178:181], v[26:29]
	v_mfma_f32_16x16x32_bf16 v[18:21], v[154:157], v[186:189], v[18:21]
	v_mfma_f32_16x16x32_bf16 v[10:13], v[162:165], v[186:189], v[10:13]
	v_mfma_f32_16x16x32_bf16 v[6:9], v[154:157], v[194:197], v[6:9]
	v_mfma_f32_16x16x32_bf16 v[2:5], v[162:165], v[194:197], v[2:5]
	v_mfma_f32_16x16x32_bf16 v[50:53], v[158:161], v[174:177], v[50:53]
	v_mfma_f32_16x16x32_bf16 v[42:45], v[166:169], v[174:177], v[42:45]
	v_mfma_f32_16x16x32_bf16 v[34:37], v[158:161], v[182:185], v[34:37]
	v_mfma_f32_16x16x32_bf16 v[26:29], v[166:169], v[182:185], v[26:29]
	v_mfma_f32_16x16x32_bf16 v[18:21], v[158:161], v[190:193], v[18:21]
	v_mfma_f32_16x16x32_bf16 v[10:13], v[166:169], v[190:193], v[10:13]
	v_mfma_f32_16x16x32_bf16 v[6:9], v[158:161], v[198:201], v[6:9]
	v_mfma_f32_16x16x32_bf16 v[2:5], v[166:169], v[198:201], v[2:5]
	s_setprio 0
	s_barrier
	s_andn2_b64 vcc, exec, s[16:17]
	s_mov_b64 s[46:47], -1
	s_mov_b64 s[16:17], 0
	s_mov_b64 s[48:49], 0x100
	s_cbranch_vccz .LBB0_634
	s_cmpk_lt_u32 s25, 0x100
	s_cbranch_scc0 .LBB0_637
	s_barrier

.LBB0_667:
	s_add_i32 s77, 0, 0x10000
	v_add_u32_e32 v0, s77, v144
	ds_read_b128 v[146:149], v0
	ds_read_b128 v[150:153], v0 offset:1024
	ds_read_b128 v[154:157], v0 offset:2048
	ds_read_b128 v[158:161], v0 offset:3072
	ds_read_b128 v[162:165], v0 offset:16384
	ds_read_b128 v[166:169], v0 offset:17408
	ds_read_b128 v[170:173], v0 offset:18432
	ds_read_b128 v[174:177], v0 offset:19456
	ds_read_b128 v[178:181], v145
	ds_read_b128 v[182:185], v145 offset:1024
	ds_read_b128 v[186:189], v145 offset:2048
	ds_read_b128 v[190:193], v145 offset:3072
	ds_read_b128 v[194:197], v145 offset:4096
	ds_read_b128 v[198:201], v145 offset:5120
	ds_read_b128 v[202:205], v145 offset:6144
	ds_read_b128 v[206:209], v145 offset:7168
	s_add_u32 s4, s70, s50
	s_addc_u32 s5, s71, s51
	s_add_u32 s46, s4, 0x9400100
	s_addc_u32 s47, s5, 0
	s_add_u32 s58, s74, s50
	s_addc_u32 s59, s75, s51
	s_cmpk_eq_i32 s50, 0x300
	s_cselect_b32 s47, s23, s47
	s_cselect_b32 s46, s22, s46
	s_cselect_b32 s59, s49, s59
	s_cselect_b32 s58, s48, s58
	s_add_i32 s78, 0, 0x14000
	s_add_i32 m0, s61, 0xc000
	s_add_u32 s100, s4, s54
	s_addc_u32 s101, s5, s55
	global_load_lds_dwordx4 v130, s[100:101]
	s_add_i32 m0, s61, 0xe000
	s_nop 0
	global_load_lds_dwordx4 v141, s[100:101]
	s_waitcnt vmcnt(8) lgkmcnt(0)
	s_setprio 1
	s_barrier
	v_mfma_i32_16x16x64_i8 v[126:129], v[146:149], v[178:181], v[126:129]
	v_mfma_i32_16x16x64_i8 v[122:125], v[154:157], v[178:181], v[122:125]
	v_mfma_i32_16x16x64_i8 v[110:113], v[146:149], v[186:189], v[110:113]
	v_mfma_i32_16x16x64_i8 v[106:109], v[154:157], v[186:189], v[106:109]
	v_mfma_i32_16x16x64_i8 v[94:97], v[146:149], v[194:197], v[94:97]
	v_mfma_i32_16x16x64_i8 v[90:93], v[154:157], v[194:197], v[90:93]
	v_mfma_i32_16x16x64_i8 v[78:81], v[146:149], v[202:205], v[78:81]
	v_mfma_i32_16x16x64_i8 v[74:77], v[154:157], v[202:205], v[74:77]
	v_mfma_i32_16x16x64_i8 v[126:129], v[150:153], v[182:185], v[126:129]
	v_mfma_i32_16x16x64_i8 v[122:125], v[158:161], v[182:185], v[122:125]
	v_mfma_i32_16x16x64_i8 v[110:113], v[150:153], v[190:193], v[110:113]
	v_mfma_i32_16x16x64_i8 v[106:109], v[158:161], v[190:193], v[106:109]
	v_mfma_i32_16x16x64_i8 v[94:97], v[150:153], v[198:201], v[94:97]
	v_mfma_i32_16x16x64_i8 v[90:93], v[158:161], v[198:201], v[90:93]
	v_mfma_i32_16x16x64_i8 v[78:81], v[150:153], v[206:209], v[78:81]
	v_mfma_i32_16x16x64_i8 v[74:77], v[158:161], v[206:209], v[74:77]
	s_setprio 0
	s_setprio 1
	v_mfma_i32_16x16x64_i8 v[118:121], v[162:165], v[178:181], v[118:121]
	v_mfma_i32_16x16x64_i8 v[114:117], v[170:173], v[178:181], v[114:117]
	v_mfma_i32_16x16x64_i8 v[102:105], v[162:165], v[186:189], v[102:105]
	v_mfma_i32_16x16x64_i8 v[98:101], v[170:173], v[186:189], v[98:101]
	v_mfma_i32_16x16x64_i8 v[86:89], v[162:165], v[194:197], v[86:89]
	v_mfma_i32_16x16x64_i8 v[82:85], v[170:173], v[194:197], v[82:85]
	v_mfma_i32_16x16x64_i8 v[70:73], v[162:165], v[202:205], v[70:73]
	v_mfma_i32_16x16x64_i8 v[66:69], v[170:173], v[202:205], v[66:69]
	v_mfma_i32_16x16x64_i8 v[118:121], v[166:169], v[182:185], v[118:121]
	v_mfma_i32_16x16x64_i8 v[114:117], v[174:177], v[182:185], v[114:117]
	v_mfma_i32_16x16x64_i8 v[102:105], v[166:169], v[190:193], v[102:105]
	v_mfma_i32_16x16x64_i8 v[98:101], v[174:177], v[190:193], v[98:101]
	v_mfma_i32_16x16x64_i8 v[86:89], v[166:169], v[198:201], v[86:89]
	v_mfma_i32_16x16x64_i8 v[82:85], v[174:177], v[198:201], v[82:85]
	v_mfma_i32_16x16x64_i8 v[70:73], v[166:169], v[206:209], v[70:73]
	v_mfma_i32_16x16x64_i8 v[66:69], v[174:177], v[206:209], v[66:69]
	s_setprio 0
	s_barrier
	ds_read_b128 v[178:181], v145 offset:16384
	ds_read_b128 v[182:185], v145 offset:17408
	ds_read_b128 v[186:189], v145 offset:18432
	ds_read_b128 v[190:193], v145 offset:19456
	ds_read_b128 v[194:197], v145 offset:20480
	ds_read_b128 v[198:201], v145 offset:21504
	ds_read_b128 v[202:205], v145 offset:22528
	ds_read_b128 v[206:209], v145 offset:23552
	s_add_i32 s4, s77, s60
	s_mov_b32 m0, s4
	s_nop 0
	global_load_lds_dwordx4 v131, s[58:59]
	s_add_i32 m0, s4, 0x2000
	s_add_u32 s4, s58, 0x20000
	global_load_lds_dwordx4 v142, s[58:59]
	s_addc_u32 s5, s59, 0
	s_add_i32 s77, s78, s60
	s_mov_b32 m0, s77
	s_nop 0
	global_load_lds_dwordx4 v131, s[4:5]
	s_add_i32 m0, s77, 0x2000
	s_nop 0
	global_load_lds_dwordx4 v142, s[4:5]
	s_mov_b32 m0, s61
	s_nop 0
	global_load_lds_dwordx4 v130, s[46:47]
	s_mov_b32 m0, s65
	s_nop 0
	global_load_lds_dwordx4 v141, s[46:47]
	s_waitcnt vmcnt(8) lgkmcnt(0)
	s_setprio 1
	s_barrier
	v_mfma_i32_16x16x64_i8 v[62:65], v[146:149], v[178:181], v[62:65]
	v_mfma_i32_16x16x64_i8 v[58:61], v[154:157], v[178:181], v[58:61]
	v_mfma_i32_16x16x64_i8 v[46:49], v[146:149], v[186:189], v[46:49]
	v_mfma_i32_16x16x64_i8 v[42:45], v[154:157], v[186:189], v[42:45]
	v_mfma_i32_16x16x64_i8 v[30:33], v[146:149], v[194:197], v[30:33]
	v_mfma_i32_16x16x64_i8 v[26:29], v[154:157], v[194:197], v[26:29]
	v_mfma_i32_16x16x64_i8 v[14:17], v[146:149], v[202:205], v[14:17]
	v_mfma_i32_16x16x64_i8 v[10:13], v[154:157], v[202:205], v[10:13]
	v_mfma_i32_16x16x64_i8 v[62:65], v[150:153], v[182:185], v[62:65]
	v_mfma_i32_16x16x64_i8 v[58:61], v[158:161], v[182:185], v[58:61]
	v_mfma_i32_16x16x64_i8 v[46:49], v[150:153], v[190:193], v[46:49]
	v_mfma_i32_16x16x64_i8 v[42:45], v[158:161], v[190:193], v[42:45]
	v_mfma_i32_16x16x64_i8 v[30:33], v[150:153], v[198:201], v[30:33]
	v_mfma_i32_16x16x64_i8 v[26:29], v[158:161], v[198:201], v[26:29]
	v_mfma_i32_16x16x64_i8 v[14:17], v[150:153], v[206:209], v[14:17]
	v_mfma_i32_16x16x64_i8 v[10:13], v[158:161], v[206:209], v[10:13]
	s_setprio 0
	s_setprio 1
	v_mfma_i32_16x16x64_i8 v[54:57], v[162:165], v[178:181], v[54:57]
	v_mfma_i32_16x16x64_i8 v[50:53], v[170:173], v[178:181], v[50:53]
	v_mfma_i32_16x16x64_i8 v[38:41], v[162:165], v[186:189], v[38:41]
	v_mfma_i32_16x16x64_i8 v[34:37], v[170:173], v[186:189], v[34:37]
	v_mfma_i32_16x16x64_i8 v[22:25], v[162:165], v[194:197], v[22:25]
	v_mfma_i32_16x16x64_i8 v[18:21], v[170:173], v[194:197], v[18:21]
	v_mfma_i32_16x16x64_i8 v[6:9], v[162:165], v[202:205], v[6:9]
	v_mfma_i32_16x16x64_i8 v[2:5], v[170:173], v[202:205], v[2:5]
	v_mfma_i32_16x16x64_i8 v[54:57], v[166:169], v[182:185], v[54:57]
	v_mfma_i32_16x16x64_i8 v[50:53], v[174:177], v[182:185], v[50:53]
	v_mfma_i32_16x16x64_i8 v[38:41], v[166:169], v[190:193], v[38:41]
	v_mfma_i32_16x16x64_i8 v[34:37], v[174:177], v[190:193], v[34:37]
	v_mfma_i32_16x16x64_i8 v[22:25], v[166:169], v[198:201], v[22:25]
	v_mfma_i32_16x16x64_i8 v[18:21], v[174:177], v[198:201], v[18:21]
	v_mfma_i32_16x16x64_i8 v[6:9], v[166:169], v[206:209], v[6:9]
	v_mfma_i32_16x16x64_i8 v[2:5], v[174:177], v[206:209], v[2:5]
	s_setprio 0
	s_barrier
	ds_read_b128 v[146:149], v0 offset:32768
	ds_read_b128 v[150:153], v0 offset:33792
	ds_read_b128 v[154:157], v0 offset:34816
	ds_read_b128 v[158:161], v0 offset:35840
	ds_read_b128 v[162:165], v0 offset:49152
	ds_read_b128 v[166:169], v0 offset:50176
	ds_read_b128 v[170:173], v0 offset:51200
	ds_read_b128 v[174:177], v0 offset:52224
	s_add_u32 s4, s46, 0x20000
	s_mov_b32 m0, s66
	ds_read_b128 v[178:181], v145 offset:32768
	ds_read_b128 v[182:185], v145 offset:33792
	ds_read_b128 v[186:189], v145 offset:34816
	ds_read_b128 v[190:193], v145 offset:35840
	ds_read_b128 v[194:197], v145 offset:36864
	ds_read_b128 v[198:201], v145 offset:37888
	ds_read_b128 v[202:205], v145 offset:38912
	ds_read_b128 v[206:209], v145 offset:39936
	s_addc_u32 s5, s47, 0
	s_add_i32 s77, 0, 0x18000
	s_add_i32 s78, 0, 0x1c000
	s_nop 0
	global_load_lds_dwordx4 v130, s[4:5]
	s_mov_b32 m0, s67
	s_nop 0
	global_load_lds_dwordx4 v141, s[4:5]
	s_waitcnt vmcnt(8) lgkmcnt(0)
	s_setprio 1
	s_barrier
	v_mfma_i32_16x16x64_i8 v[126:129], v[146:149], v[178:181], v[126:129]
	v_mfma_i32_16x16x64_i8 v[122:125], v[154:157], v[178:181], v[122:125]
	v_mfma_i32_16x16x64_i8 v[110:113], v[146:149], v[186:189], v[110:113]
	v_mfma_i32_16x16x64_i8 v[106:109], v[154:157], v[186:189], v[106:109]
	v_mfma_i32_16x16x64_i8 v[94:97], v[146:149], v[194:197], v[94:97]
	v_mfma_i32_16x16x64_i8 v[90:93], v[154:157], v[194:197], v[90:93]
	v_mfma_i32_16x16x64_i8 v[78:81], v[146:149], v[202:205], v[78:81]
	v_mfma_i32_16x16x64_i8 v[74:77], v[154:157], v[202:205], v[74:77]
	v_mfma_i32_16x16x64_i8 v[126:129], v[150:153], v[182:185], v[126:129]
	v_mfma_i32_16x16x64_i8 v[122:125], v[158:161], v[182:185], v[122:125]
	v_mfma_i32_16x16x64_i8 v[110:113], v[150:153], v[190:193], v[110:113]
	v_mfma_i32_16x16x64_i8 v[106:109], v[158:161], v[190:193], v[106:109]
	v_mfma_i32_16x16x64_i8 v[94:97], v[150:153], v[198:201], v[94:97]
	v_mfma_i32_16x16x64_i8 v[90:93], v[158:161], v[198:201], v[90:93]
	v_mfma_i32_16x16x64_i8 v[78:81], v[150:153], v[206:209], v[78:81]
	v_mfma_i32_16x16x64_i8 v[74:77], v[158:161], v[206:209], v[74:77]
	s_setprio 0
	s_setprio 1
	v_mfma_i32_16x16x64_i8 v[118:121], v[162:165], v[178:181], v[118:121]
	v_mfma_i32_16x16x64_i8 v[114:117], v[170:173], v[178:181], v[114:117]
	v_mfma_i32_16x16x64_i8 v[102:105], v[162:165], v[186:189], v[102:105]
	v_mfma_i32_16x16x64_i8 v[98:101], v[170:173], v[186:189], v[98:101]
	v_mfma_i32_16x16x64_i8 v[86:89], v[162:165], v[194:197], v[86:89]
	v_mfma_i32_16x16x64_i8 v[82:85], v[170:173], v[194:197], v[82:85]
	v_mfma_i32_16x16x64_i8 v[70:73], v[162:165], v[202:205], v[70:73]
	v_mfma_i32_16x16x64_i8 v[66:69], v[170:173], v[202:205], v[66:69]
	v_mfma_i32_16x16x64_i8 v[118:121], v[166:169], v[182:185], v[118:121]
	v_mfma_i32_16x16x64_i8 v[114:117], v[174:177], v[182:185], v[114:117]
	v_mfma_i32_16x16x64_i8 v[102:105], v[166:169], v[190:193], v[102:105]
	v_mfma_i32_16x16x64_i8 v[98:101], v[174:177], v[190:193], v[98:101]
	v_mfma_i32_16x16x64_i8 v[86:89], v[166:169], v[198:201], v[86:89]
	v_mfma_i32_16x16x64_i8 v[82:85], v[174:177], v[198:201], v[82:85]
	v_mfma_i32_16x16x64_i8 v[70:73], v[166:169], v[206:209], v[70:73]
	v_mfma_i32_16x16x64_i8 v[66:69], v[174:177], v[206:209], v[66:69]
	s_setprio 0
	s_barrier
	ds_read_b128 v[178:181], v145 offset:49152
	ds_read_b128 v[182:185], v145 offset:50176
	ds_read_b128 v[186:189], v145 offset:51200
	ds_read_b128 v[190:193], v145 offset:52224
	ds_read_b128 v[194:197], v145 offset:53248
	ds_read_b128 v[198:201], v145 offset:54272
	ds_read_b128 v[202:205], v145 offset:55296
	ds_read_b128 v[206:209], v145 offset:56320
	s_add_i32 s4, s77, s60
	s_add_u32 s100, s58, s38
	s_addc_u32 s101, s59, s39
	s_mov_b32 m0, s4
	s_nop 0
	global_load_lds_dwordx4 v131, s[100:101]
	s_add_i32 m0, s4, 0x2000
	s_add_u32 s4, s58, 0x20080
	s_addc_u32 s5, s59, 0
	s_add_i32 s58, s78, s60
	global_load_lds_dwordx4 v142, s[100:101]
	s_mov_b32 m0, s58
	s_nop 0
	global_load_lds_dwordx4 v131, s[4:5]
	s_add_i32 m0, s58, 0x2000
	s_nop 0
	global_load_lds_dwordx4 v142, s[4:5]
	s_mov_b32 m0, s68
	s_add_u32 s100, s46, s38
	s_addc_u32 s101, s47, s39
	v_mov_b32_e32 v0, v141
	global_load_lds_dwordx4 v130, s[100:101]
	s_mov_b32 m0, s69
	s_nop 0
	global_load_lds_dwordx4 v141, s[100:101]
	s_waitcnt vmcnt(8) lgkmcnt(0)
	s_setprio 1
	s_barrier
	v_mfma_i32_16x16x64_i8 v[62:65], v[146:149], v[178:181], v[62:65]
	v_mfma_i32_16x16x64_i8 v[58:61], v[154:157], v[178:181], v[58:61]
	v_mfma_i32_16x16x64_i8 v[46:49], v[146:149], v[186:189], v[46:49]
	v_mfma_i32_16x16x64_i8 v[42:45], v[154:157], v[186:189], v[42:45]
	v_mfma_i32_16x16x64_i8 v[30:33], v[146:149], v[194:197], v[30:33]
	v_mfma_i32_16x16x64_i8 v[26:29], v[154:157], v[194:197], v[26:29]
	v_mfma_i32_16x16x64_i8 v[14:17], v[146:149], v[202:205], v[14:17]
	v_mfma_i32_16x16x64_i8 v[10:13], v[154:157], v[202:205], v[10:13]
	v_mfma_i32_16x16x64_i8 v[62:65], v[150:153], v[182:185], v[62:65]
	v_mfma_i32_16x16x64_i8 v[58:61], v[158:161], v[182:185], v[58:61]
	v_mfma_i32_16x16x64_i8 v[46:49], v[150:153], v[190:193], v[46:49]
	v_mfma_i32_16x16x64_i8 v[42:45], v[158:161], v[190:193], v[42:45]
	v_mfma_i32_16x16x64_i8 v[30:33], v[150:153], v[198:201], v[30:33]
	v_mfma_i32_16x16x64_i8 v[26:29], v[158:161], v[198:201], v[26:29]
	v_mfma_i32_16x16x64_i8 v[14:17], v[150:153], v[206:209], v[14:17]
	v_mfma_i32_16x16x64_i8 v[10:13], v[158:161], v[206:209], v[10:13]
	s_setprio 0
	s_setprio 1
	v_mfma_i32_16x16x64_i8 v[54:57], v[162:165], v[178:181], v[54:57]
	v_mfma_i32_16x16x64_i8 v[50:53], v[170:173], v[178:181], v[50:53]
	v_mfma_i32_16x16x64_i8 v[38:41], v[162:165], v[186:189], v[38:41]
	v_mfma_i32_16x16x64_i8 v[34:37], v[170:173], v[186:189], v[34:37]
	v_mfma_i32_16x16x64_i8 v[22:25], v[162:165], v[194:197], v[22:25]
	v_mfma_i32_16x16x64_i8 v[18:21], v[170:173], v[194:197], v[18:21]
	v_mfma_i32_16x16x64_i8 v[6:9], v[162:165], v[202:205], v[6:9]
	v_mfma_i32_16x16x64_i8 v[2:5], v[170:173], v[202:205], v[2:5]
	v_mfma_i32_16x16x64_i8 v[54:57], v[166:169], v[182:185], v[54:57]
	v_mfma_i32_16x16x64_i8 v[50:53], v[174:177], v[182:185], v[50:53]
	v_mfma_i32_16x16x64_i8 v[38:41], v[166:169], v[190:193], v[38:41]
	v_mfma_i32_16x16x64_i8 v[34:37], v[174:177], v[190:193], v[34:37]
	v_mfma_i32_16x16x64_i8 v[22:25], v[166:169], v[198:201], v[22:25]
	v_mfma_i32_16x16x64_i8 v[18:21], v[174:177], v[198:201], v[18:21]
	v_mfma_i32_16x16x64_i8 v[6:9], v[166:169], v[206:209], v[6:9]
	v_mfma_i32_16x16x64_i8 v[2:5], v[174:177], v[206:209], v[2:5]
	s_setprio 0
	s_barrier
	s_add_i32 s76, s76, 2
	s_add_u32 s50, s50, 0x100
	s_addc_u32 s51, s51, 0
	s_cmp_gt_u32 s76, 5
	s_cbranch_scc0 .LBB0_667
	s_cmpk_lt_u32 s17, 0x100
	s_cbranch_scc0 .LBB0_661
	s_barrier
	s_branch .LBB0_661

.LBB0_821:
	s_add_i32 s85, 0, 0x10000
	v_add_u32_e32 v0, s85, v134
	ds_read_b128 v[136:139], v0
	ds_read_b128 v[140:143], v0 offset:1024
	ds_read_b128 v[144:147], v0 offset:2048
	ds_read_b128 v[148:151], v0 offset:3072
	ds_read_b128 v[152:155], v0 offset:16384
	ds_read_b128 v[156:159], v0 offset:17408
	ds_read_b128 v[160:163], v0 offset:18432
	ds_read_b128 v[164:167], v0 offset:19456
	ds_read_b128 v[168:171], v135
	ds_read_b128 v[172:175], v135 offset:1024
	ds_read_b128 v[176:179], v135 offset:2048
	ds_read_b128 v[180:183], v135 offset:3072
	ds_read_b128 v[184:187], v135 offset:4096
	ds_read_b128 v[188:191], v135 offset:5120
	ds_read_b128 v[192:195], v135 offset:6144
	ds_read_b128 v[198:201], v135 offset:7168
	s_add_u32 s4, s79, s50
	s_addc_u32 s5, s82, s51
	s_add_u32 s46, s4, 0x9800100
	s_addc_u32 s47, s5, 0
	s_add_u32 s58, s64, s50
	s_addc_u32 s59, s83, s51
	s_cmpk_eq_i32 s50, 0x1500
	s_cselect_b32 s47, s49, s47
	s_cselect_b32 s46, s48, s46
	s_cselect_b32 s59, s71, s59
	s_cselect_b32 s58, s70, s58
	s_add_i32 s86, 0, 0x14000
	s_add_i32 m0, s60, 0xc000
	s_add_u32 s100, s4, s88
	s_addc_u32 s101, s5, s89
	global_load_lds_dwordx4 v130, s[100:101]
	s_add_i32 m0, s60, 0xe000
	s_nop 0
	global_load_lds_dwordx4 v131, s[100:101]
	s_waitcnt vmcnt(8) lgkmcnt(0)
	s_setprio 1
	s_barrier
	v_mfma_f32_16x16x32_bf16 v[126:129], v[136:139], v[168:171], v[126:129]
	v_mfma_f32_16x16x32_bf16 v[122:125], v[144:147], v[168:171], v[122:125]
	v_mfma_f32_16x16x32_bf16 v[110:113], v[136:139], v[176:179], v[110:113]
	v_mfma_f32_16x16x32_bf16 v[106:109], v[144:147], v[176:179], v[106:109]
	v_mfma_f32_16x16x32_bf16 v[94:97], v[136:139], v[184:187], v[94:97]
	v_mfma_f32_16x16x32_bf16 v[90:93], v[144:147], v[184:187], v[90:93]
	v_mfma_f32_16x16x32_bf16 v[78:81], v[136:139], v[192:195], v[78:81]
	v_mfma_f32_16x16x32_bf16 v[74:77], v[144:147], v[192:195], v[74:77]
	v_mfma_f32_16x16x32_bf16 v[126:129], v[140:143], v[172:175], v[126:129]
	v_mfma_f32_16x16x32_bf16 v[122:125], v[148:151], v[172:175], v[122:125]
	v_mfma_f32_16x16x32_bf16 v[110:113], v[140:143], v[180:183], v[110:113]
	v_mfma_f32_16x16x32_bf16 v[106:109], v[148:151], v[180:183], v[106:109]
	v_mfma_f32_16x16x32_bf16 v[94:97], v[140:143], v[188:191], v[94:97]
	v_mfma_f32_16x16x32_bf16 v[90:93], v[148:151], v[188:191], v[90:93]
	v_mfma_f32_16x16x32_bf16 v[78:81], v[140:143], v[198:201], v[78:81]
	v_mfma_f32_16x16x32_bf16 v[74:77], v[148:151], v[198:201], v[74:77]
	s_setprio 0
	s_setprio 1
	v_mfma_f32_16x16x32_bf16 v[118:121], v[152:155], v[168:171], v[118:121]
	v_mfma_f32_16x16x32_bf16 v[114:117], v[160:163], v[168:171], v[114:117]
	v_mfma_f32_16x16x32_bf16 v[102:105], v[152:155], v[176:179], v[102:105]
	v_mfma_f32_16x16x32_bf16 v[98:101], v[160:163], v[176:179], v[98:101]
	v_mfma_f32_16x16x32_bf16 v[86:89], v[152:155], v[184:187], v[86:89]
	v_mfma_f32_16x16x32_bf16 v[82:85], v[160:163], v[184:187], v[82:85]
	v_mfma_f32_16x16x32_bf16 v[70:73], v[152:155], v[192:195], v[70:73]
	v_mfma_f32_16x16x32_bf16 v[66:69], v[160:163], v[192:195], v[66:69]
	v_mfma_f32_16x16x32_bf16 v[118:121], v[156:159], v[172:175], v[118:121]
	v_mfma_f32_16x16x32_bf16 v[114:117], v[164:167], v[172:175], v[114:117]
	v_mfma_f32_16x16x32_bf16 v[102:105], v[156:159], v[180:183], v[102:105]
	v_mfma_f32_16x16x32_bf16 v[98:101], v[164:167], v[180:183], v[98:101]
	v_mfma_f32_16x16x32_bf16 v[86:89], v[156:159], v[188:191], v[86:89]
	v_mfma_f32_16x16x32_bf16 v[82:85], v[164:167], v[188:191], v[82:85]
	v_mfma_f32_16x16x32_bf16 v[70:73], v[156:159], v[198:201], v[70:73]
	v_mfma_f32_16x16x32_bf16 v[66:69], v[164:167], v[198:201], v[66:69]
	s_setprio 0
	s_barrier
	ds_read_b128 v[168:171], v135 offset:16384
	ds_read_b128 v[172:175], v135 offset:17408
	ds_read_b128 v[176:179], v135 offset:18432
	ds_read_b128 v[180:183], v135 offset:19456
	ds_read_b128 v[184:187], v135 offset:20480
	ds_read_b128 v[188:191], v135 offset:21504
	ds_read_b128 v[192:195], v135 offset:22528
	ds_read_b128 v[198:201], v135 offset:23552
	s_add_i32 s4, s85, s26
	s_mov_b32 m0, s4
	s_nop 0
	global_load_lds_dwordx4 v132, s[58:59]
	s_add_i32 m0, s4, 0x2000
	s_add_u32 s4, s58, 0xb0000
	global_load_lds_dwordx4 v133, s[58:59]
	s_addc_u32 s5, s59, 0
	s_add_i32 s85, s86, s26
	s_mov_b32 m0, s85
	s_nop 0
	global_load_lds_dwordx4 v132, s[4:5]
	s_add_i32 m0, s85, 0x2000
	s_nop 0
	global_load_lds_dwordx4 v133, s[4:5]
	s_mov_b32 m0, s60
	s_nop 0
	global_load_lds_dwordx4 v130, s[46:47]
	s_mov_b32 m0, s65
	s_nop 0
	global_load_lds_dwordx4 v131, s[46:47]
	s_waitcnt vmcnt(8) lgkmcnt(0)
	s_setprio 1
	s_barrier
	v_mfma_f32_16x16x32_bf16 v[62:65], v[136:139], v[168:171], v[62:65]
	v_mfma_f32_16x16x32_bf16 v[58:61], v[144:147], v[168:171], v[58:61]
	v_mfma_f32_16x16x32_bf16 v[46:49], v[136:139], v[176:179], v[46:49]
	v_mfma_f32_16x16x32_bf16 v[42:45], v[144:147], v[176:179], v[42:45]
	v_mfma_f32_16x16x32_bf16 v[30:33], v[136:139], v[184:187], v[30:33]
	v_mfma_f32_16x16x32_bf16 v[26:29], v[144:147], v[184:187], v[26:29]
	v_mfma_f32_16x16x32_bf16 v[14:17], v[136:139], v[192:195], v[14:17]
	v_mfma_f32_16x16x32_bf16 v[10:13], v[144:147], v[192:195], v[10:13]
	v_mfma_f32_16x16x32_bf16 v[62:65], v[140:143], v[172:175], v[62:65]
	v_mfma_f32_16x16x32_bf16 v[58:61], v[148:151], v[172:175], v[58:61]
	v_mfma_f32_16x16x32_bf16 v[46:49], v[140:143], v[180:183], v[46:49]
	v_mfma_f32_16x16x32_bf16 v[42:45], v[148:151], v[180:183], v[42:45]
	v_mfma_f32_16x16x32_bf16 v[30:33], v[140:143], v[188:191], v[30:33]
	v_mfma_f32_16x16x32_bf16 v[26:29], v[148:151], v[188:191], v[26:29]
	v_mfma_f32_16x16x32_bf16 v[14:17], v[140:143], v[198:201], v[14:17]
	v_mfma_f32_16x16x32_bf16 v[10:13], v[148:151], v[198:201], v[10:13]
	s_setprio 0
	s_setprio 1
	v_mfma_f32_16x16x32_bf16 v[54:57], v[152:155], v[168:171], v[54:57]
	v_mfma_f32_16x16x32_bf16 v[50:53], v[160:163], v[168:171], v[50:53]
	v_mfma_f32_16x16x32_bf16 v[38:41], v[152:155], v[176:179], v[38:41]
	v_mfma_f32_16x16x32_bf16 v[34:37], v[160:163], v[176:179], v[34:37]
	v_mfma_f32_16x16x32_bf16 v[22:25], v[152:155], v[184:187], v[22:25]
	v_mfma_f32_16x16x32_bf16 v[18:21], v[160:163], v[184:187], v[18:21]
	v_mfma_f32_16x16x32_bf16 v[6:9], v[152:155], v[192:195], v[6:9]
	v_mfma_f32_16x16x32_bf16 v[2:5], v[160:163], v[192:195], v[2:5]
	v_mfma_f32_16x16x32_bf16 v[54:57], v[156:159], v[172:175], v[54:57]
	v_mfma_f32_16x16x32_bf16 v[50:53], v[164:167], v[172:175], v[50:53]
	v_mfma_f32_16x16x32_bf16 v[38:41], v[156:159], v[180:183], v[38:41]
	v_mfma_f32_16x16x32_bf16 v[34:37], v[164:167], v[180:183], v[34:37]
	v_mfma_f32_16x16x32_bf16 v[22:25], v[156:159], v[188:191], v[22:25]
	v_mfma_f32_16x16x32_bf16 v[18:21], v[164:167], v[188:191], v[18:21]
	v_mfma_f32_16x16x32_bf16 v[6:9], v[156:159], v[198:201], v[6:9]
	v_mfma_f32_16x16x32_bf16 v[2:5], v[164:167], v[198:201], v[2:5]
	s_setprio 0
	s_barrier
	ds_read_b128 v[136:139], v0 offset:32768
	ds_read_b128 v[140:143], v0 offset:33792
	ds_read_b128 v[144:147], v0 offset:34816
	ds_read_b128 v[148:151], v0 offset:35840
	ds_read_b128 v[152:155], v0 offset:49152
	ds_read_b128 v[156:159], v0 offset:50176
	ds_read_b128 v[160:163], v0 offset:51200
	ds_read_b128 v[164:167], v0 offset:52224
	s_add_u32 s4, s46, 0xb0000
	s_mov_b32 m0, s68
	ds_read_b128 v[168:171], v135 offset:32768
	ds_read_b128 v[172:175], v135 offset:33792
	ds_read_b128 v[176:179], v135 offset:34816
	ds_read_b128 v[180:183], v135 offset:35840
	ds_read_b128 v[184:187], v135 offset:36864
	ds_read_b128 v[188:191], v135 offset:37888
	ds_read_b128 v[192:195], v135 offset:38912
	ds_read_b128 v[198:201], v135 offset:39936
	s_addc_u32 s5, s47, 0
	s_add_i32 s85, 0, 0x18000
	s_add_i32 s86, 0, 0x1c000
	s_nop 0
	global_load_lds_dwordx4 v130, s[4:5]
	s_mov_b32 m0, s69
	s_nop 0
	global_load_lds_dwordx4 v131, s[4:5]
	s_waitcnt vmcnt(8) lgkmcnt(0)
	s_setprio 1
	s_barrier
	v_mfma_f32_16x16x32_bf16 v[126:129], v[136:139], v[168:171], v[126:129]
	v_mfma_f32_16x16x32_bf16 v[122:125], v[144:147], v[168:171], v[122:125]
	v_mfma_f32_16x16x32_bf16 v[110:113], v[136:139], v[176:179], v[110:113]
	v_mfma_f32_16x16x32_bf16 v[106:109], v[144:147], v[176:179], v[106:109]
	v_mfma_f32_16x16x32_bf16 v[94:97], v[136:139], v[184:187], v[94:97]
	v_mfma_f32_16x16x32_bf16 v[90:93], v[144:147], v[184:187], v[90:93]
	v_mfma_f32_16x16x32_bf16 v[78:81], v[136:139], v[192:195], v[78:81]
	v_mfma_f32_16x16x32_bf16 v[74:77], v[144:147], v[192:195], v[74:77]
	v_mfma_f32_16x16x32_bf16 v[126:129], v[140:143], v[172:175], v[126:129]
	v_mfma_f32_16x16x32_bf16 v[122:125], v[148:151], v[172:175], v[122:125]
	v_mfma_f32_16x16x32_bf16 v[110:113], v[140:143], v[180:183], v[110:113]
	v_mfma_f32_16x16x32_bf16 v[106:109], v[148:151], v[180:183], v[106:109]
	v_mfma_f32_16x16x32_bf16 v[94:97], v[140:143], v[188:191], v[94:97]
	v_mfma_f32_16x16x32_bf16 v[90:93], v[148:151], v[188:191], v[90:93]
	v_mfma_f32_16x16x32_bf16 v[78:81], v[140:143], v[198:201], v[78:81]
	v_mfma_f32_16x16x32_bf16 v[74:77], v[148:151], v[198:201], v[74:77]
	s_setprio 0
	s_setprio 1
	v_mfma_f32_16x16x32_bf16 v[118:121], v[152:155], v[168:171], v[118:121]
	v_mfma_f32_16x16x32_bf16 v[114:117], v[160:163], v[168:171], v[114:117]
	v_mfma_f32_16x16x32_bf16 v[102:105], v[152:155], v[176:179], v[102:105]
	v_mfma_f32_16x16x32_bf16 v[98:101], v[160:163], v[176:179], v[98:101]
	v_mfma_f32_16x16x32_bf16 v[86:89], v[152:155], v[184:187], v[86:89]
	v_mfma_f32_16x16x32_bf16 v[82:85], v[160:163], v[184:187], v[82:85]
	v_mfma_f32_16x16x32_bf16 v[70:73], v[152:155], v[192:195], v[70:73]
	v_mfma_f32_16x16x32_bf16 v[66:69], v[160:163], v[192:195], v[66:69]
	v_mfma_f32_16x16x32_bf16 v[118:121], v[156:159], v[172:175], v[118:121]
	v_mfma_f32_16x16x32_bf16 v[114:117], v[164:167], v[172:175], v[114:117]
	v_mfma_f32_16x16x32_bf16 v[102:105], v[156:159], v[180:183], v[102:105]
	v_mfma_f32_16x16x32_bf16 v[98:101], v[164:167], v[180:183], v[98:101]
	v_mfma_f32_16x16x32_bf16 v[86:89], v[156:159], v[188:191], v[86:89]
	v_mfma_f32_16x16x32_bf16 v[82:85], v[164:167], v[188:191], v[82:85]
	v_mfma_f32_16x16x32_bf16 v[70:73], v[156:159], v[198:201], v[70:73]
	v_mfma_f32_16x16x32_bf16 v[66:69], v[164:167], v[198:201], v[66:69]
	s_setprio 0
	s_barrier
	ds_read_b128 v[168:171], v135 offset:49152
	ds_read_b128 v[172:175], v135 offset:50176
	ds_read_b128 v[176:179], v135 offset:51200
	ds_read_b128 v[180:183], v135 offset:52224
	ds_read_b128 v[184:187], v135 offset:53248
	ds_read_b128 v[188:191], v135 offset:54272
	ds_read_b128 v[192:195], v135 offset:55296
	ds_read_b128 v[198:201], v135 offset:56320
	s_add_i32 s4, s85, s26
	s_add_u32 s100, s58, s38
	s_addc_u32 s101, s59, s39
	s_mov_b32 m0, s4
	s_nop 0
	global_load_lds_dwordx4 v132, s[100:101]
	s_add_i32 m0, s4, 0x2000
	s_add_u32 s4, s58, 0xb0080
	s_addc_u32 s5, s59, 0
	s_add_i32 s58, s86, s26
	global_load_lds_dwordx4 v133, s[100:101]
	s_mov_b32 m0, s58
	s_nop 0
	global_load_lds_dwordx4 v132, s[4:5]
	s_add_i32 m0, s58, 0x2000
	s_nop 0
	global_load_lds_dwordx4 v133, s[4:5]
	s_mov_b32 m0, s75
	s_add_u32 s100, s46, s38
	s_addc_u32 s101, s47, s39
	v_mov_b32_e32 v0, v131
	global_load_lds_dwordx4 v130, s[100:101]
	s_mov_b32 m0, s78
	s_nop 0
	global_load_lds_dwordx4 v131, s[100:101]
	s_waitcnt vmcnt(8) lgkmcnt(0)
	s_setprio 1
	s_barrier
	v_mfma_f32_16x16x32_bf16 v[62:65], v[136:139], v[168:171], v[62:65]
	v_mfma_f32_16x16x32_bf16 v[58:61], v[144:147], v[168:171], v[58:61]
	v_mfma_f32_16x16x32_bf16 v[46:49], v[136:139], v[176:179], v[46:49]
	v_mfma_f32_16x16x32_bf16 v[42:45], v[144:147], v[176:179], v[42:45]
	v_mfma_f32_16x16x32_bf16 v[30:33], v[136:139], v[184:187], v[30:33]
	v_mfma_f32_16x16x32_bf16 v[26:29], v[144:147], v[184:187], v[26:29]
	v_mfma_f32_16x16x32_bf16 v[14:17], v[136:139], v[192:195], v[14:17]
	v_mfma_f32_16x16x32_bf16 v[10:13], v[144:147], v[192:195], v[10:13]
	v_mfma_f32_16x16x32_bf16 v[62:65], v[140:143], v[172:175], v[62:65]
	v_mfma_f32_16x16x32_bf16 v[58:61], v[148:151], v[172:175], v[58:61]
	v_mfma_f32_16x16x32_bf16 v[46:49], v[140:143], v[180:183], v[46:49]
	v_mfma_f32_16x16x32_bf16 v[42:45], v[148:151], v[180:183], v[42:45]
	v_mfma_f32_16x16x32_bf16 v[30:33], v[140:143], v[188:191], v[30:33]
	v_mfma_f32_16x16x32_bf16 v[26:29], v[148:151], v[188:191], v[26:29]
	v_mfma_f32_16x16x32_bf16 v[14:17], v[140:143], v[198:201], v[14:17]
	v_mfma_f32_16x16x32_bf16 v[10:13], v[148:151], v[198:201], v[10:13]
	s_setprio 0
	s_setprio 1
	v_mfma_f32_16x16x32_bf16 v[54:57], v[152:155], v[168:171], v[54:57]
	v_mfma_f32_16x16x32_bf16 v[50:53], v[160:163], v[168:171], v[50:53]
	v_mfma_f32_16x16x32_bf16 v[38:41], v[152:155], v[176:179], v[38:41]
	v_mfma_f32_16x16x32_bf16 v[34:37], v[160:163], v[176:179], v[34:37]
	v_mfma_f32_16x16x32_bf16 v[22:25], v[152:155], v[184:187], v[22:25]
	v_mfma_f32_16x16x32_bf16 v[18:21], v[160:163], v[184:187], v[18:21]
	v_mfma_f32_16x16x32_bf16 v[6:9], v[152:155], v[192:195], v[6:9]
	v_mfma_f32_16x16x32_bf16 v[2:5], v[160:163], v[192:195], v[2:5]
	v_mfma_f32_16x16x32_bf16 v[54:57], v[156:159], v[172:175], v[54:57]
	v_mfma_f32_16x16x32_bf16 v[50:53], v[164:167], v[172:175], v[50:53]
	v_mfma_f32_16x16x32_bf16 v[38:41], v[156:159], v[180:183], v[38:41]
	v_mfma_f32_16x16x32_bf16 v[34:37], v[164:167], v[180:183], v[34:37]
	v_mfma_f32_16x16x32_bf16 v[22:25], v[156:159], v[188:191], v[22:25]
	v_mfma_f32_16x16x32_bf16 v[18:21], v[164:167], v[188:191], v[18:21]
	v_mfma_f32_16x16x32_bf16 v[6:9], v[156:159], v[198:201], v[6:9]
	v_mfma_f32_16x16x32_bf16 v[2:5], v[164:167], v[198:201], v[2:5]
	s_setprio 0
	s_barrier
	s_add_i32 s84, s84, 2
	s_add_u32 s50, s50, 0x100
	s_addc_u32 s51, s51, 0
	s_cmp_gt_u32 s84, 41
	s_cbranch_scc0 .LBB0_821

.LBB0_869:
	s_add_i32 s69, 0, 0x10000
	v_add_u32_e32 v0, s69, v126
	ds_read_b128 v[128:131], v0
	ds_read_b128 v[142:145], v0 offset:1024
	ds_read_b128 v[146:149], v0 offset:2048
	ds_read_b128 v[150:153], v0 offset:3072
	ds_read_b128 v[154:157], v0 offset:16384
	ds_read_b128 v[160:163], v0 offset:17408
	ds_read_b128 v[164:167], v0 offset:18432
	ds_read_b128 v[168:171], v0 offset:19456
	ds_read_b128 v[172:175], v127
	ds_read_b128 v[176:179], v127 offset:1024
	ds_read_b128 v[180:183], v127 offset:2048
	ds_read_b128 v[184:187], v127 offset:3072
	ds_read_b128 v[188:191], v127 offset:4096
	ds_read_b128 v[192:195], v127 offset:5120
	ds_read_b128 v[196:199], v127 offset:6144
	ds_read_b128 v[200:203], v127 offset:7168
	s_add_u32 s4, s10, s2
	s_addc_u32 s5, s11, s3
	s_add_u32 s22, s4, 0x100
	s_addc_u32 s23, s5, 0
	s_add_u32 s46, s58, s2
	s_addc_u32 s47, s59, s3
	s_cmp_eq_u32 s68, 40
	s_cselect_b32 s23, s11, s23
	s_cselect_b32 s22, s10, s22
	s_cselect_b32 s47, s17, s47
	s_cselect_b32 s46, s16, s46
	s_add_i32 s70, 0, 0x14000
	s_add_i32 m0, s41, 0xc000
	s_add_u32 s100, s4, s62
	s_addc_u32 s101, s5, s63
	global_load_lds_dwordx4 v122, s[100:101]
	s_add_i32 m0, s41, 0xe000
	s_nop 0
	global_load_lds_dwordx4 v123, s[100:101]
	s_waitcnt vmcnt(8) lgkmcnt(0)
	s_setprio 1
	s_barrier
	v_mfma_f32_16x16x32_bf16 v[138:141], v[128:131], v[172:175], v[138:141]
	v_mfma_f32_16x16x32_bf16 v[132:135], v[146:149], v[172:175], v[134:137]
	v_mfma_f32_16x16x32_bf16 v[110:113], v[128:131], v[180:183], v[110:113]
	v_mfma_f32_16x16x32_bf16 v[106:109], v[146:149], v[180:183], v[106:109]
	v_mfma_f32_16x16x32_bf16 v[94:97], v[128:131], v[188:191], v[94:97]
	v_mfma_f32_16x16x32_bf16 v[90:93], v[146:149], v[188:191], v[90:93]
	v_mfma_f32_16x16x32_bf16 v[78:81], v[128:131], v[196:199], v[78:81]
	v_mfma_f32_16x16x32_bf16 v[74:77], v[146:149], v[196:199], v[74:77]
	v_mfma_f32_16x16x32_bf16 v[138:141], v[142:145], v[176:179], v[138:141]
	v_mfma_f32_16x16x32_bf16 v[132:135], v[150:153], v[176:179], v[132:135]
	v_mfma_f32_16x16x32_bf16 v[110:113], v[142:145], v[184:187], v[110:113]
	v_mfma_f32_16x16x32_bf16 v[106:109], v[150:153], v[184:187], v[106:109]
	v_mfma_f32_16x16x32_bf16 v[94:97], v[142:145], v[192:195], v[94:97]
	v_mfma_f32_16x16x32_bf16 v[90:93], v[150:153], v[192:195], v[90:93]
	v_mfma_f32_16x16x32_bf16 v[78:81], v[142:145], v[200:203], v[78:81]
	v_mfma_f32_16x16x32_bf16 v[74:77], v[150:153], v[200:203], v[74:77]
	s_setprio 0
	s_setprio 1
	v_mfma_f32_16x16x32_bf16 v[118:121], v[154:157], v[172:175], v[118:121]
	v_mfma_f32_16x16x32_bf16 v[114:117], v[164:167], v[172:175], v[114:117]
	v_mfma_f32_16x16x32_bf16 v[102:105], v[154:157], v[180:183], v[102:105]
	v_mfma_f32_16x16x32_bf16 v[98:101], v[164:167], v[180:183], v[98:101]
	v_mfma_f32_16x16x32_bf16 v[86:89], v[154:157], v[188:191], v[86:89]
	v_mfma_f32_16x16x32_bf16 v[82:85], v[164:167], v[188:191], v[82:85]
	v_mfma_f32_16x16x32_bf16 v[70:73], v[154:157], v[196:199], v[70:73]
	v_mfma_f32_16x16x32_bf16 v[66:69], v[164:167], v[196:199], v[66:69]
	v_mfma_f32_16x16x32_bf16 v[118:121], v[160:163], v[176:179], v[118:121]
	v_mfma_f32_16x16x32_bf16 v[114:117], v[168:171], v[176:179], v[114:117]
	v_mfma_f32_16x16x32_bf16 v[102:105], v[160:163], v[184:187], v[102:105]
	v_mfma_f32_16x16x32_bf16 v[98:101], v[168:171], v[184:187], v[98:101]
	v_mfma_f32_16x16x32_bf16 v[86:89], v[160:163], v[192:195], v[86:89]
	v_mfma_f32_16x16x32_bf16 v[82:85], v[168:171], v[192:195], v[82:85]
	v_mfma_f32_16x16x32_bf16 v[70:73], v[160:163], v[200:203], v[70:73]
	v_mfma_f32_16x16x32_bf16 v[66:69], v[168:171], v[200:203], v[66:69]
	s_setprio 0
	s_barrier
	ds_read_b128 v[172:175], v127 offset:16384
	ds_read_b128 v[176:179], v127 offset:17408
	ds_read_b128 v[180:183], v127 offset:18432
	ds_read_b128 v[184:187], v127 offset:19456
	ds_read_b128 v[188:191], v127 offset:20480
	ds_read_b128 v[192:195], v127 offset:21504
	ds_read_b128 v[196:199], v127 offset:22528
	ds_read_b128 v[200:203], v127 offset:23552
	s_add_i32 s4, s69, s26
	s_mov_b32 m0, s4
	s_nop 0
	global_load_lds_dwordx4 v124, s[46:47]
	s_add_i32 m0, s4, 0x2000
	s_add_u32 s4, s46, 0xb0000
	global_load_lds_dwordx4 v125, s[46:47]
	s_addc_u32 s5, s47, 0
	s_add_i32 s69, s70, s26
	s_mov_b32 m0, s69
	s_nop 0
	global_load_lds_dwordx4 v124, s[4:5]
	s_add_i32 m0, s69, 0x2000
	s_nop 0
	global_load_lds_dwordx4 v125, s[4:5]
	s_mov_b32 m0, s41
	s_nop 0
	global_load_lds_dwordx4 v122, s[22:23]
	s_mov_b32 m0, s48
	s_nop 0
	global_load_lds_dwordx4 v123, s[22:23]
	s_waitcnt vmcnt(8) lgkmcnt(0)
	s_setprio 1
	s_barrier
	v_mfma_f32_16x16x32_bf16 v[62:65], v[128:131], v[172:175], v[62:65]
	v_mfma_f32_16x16x32_bf16 v[58:61], v[146:149], v[172:175], v[58:61]
	v_mfma_f32_16x16x32_bf16 v[46:49], v[128:131], v[180:183], v[46:49]
	v_mfma_f32_16x16x32_bf16 v[42:45], v[146:149], v[180:183], v[42:45]
	v_mfma_f32_16x16x32_bf16 v[30:33], v[128:131], v[188:191], v[30:33]
	v_mfma_f32_16x16x32_bf16 v[26:29], v[146:149], v[188:191], v[26:29]
	v_mfma_f32_16x16x32_bf16 v[14:17], v[128:131], v[196:199], v[14:17]
	v_mfma_f32_16x16x32_bf16 v[10:13], v[146:149], v[196:199], v[10:13]
	v_mfma_f32_16x16x32_bf16 v[62:65], v[142:145], v[176:179], v[62:65]
	v_mfma_f32_16x16x32_bf16 v[58:61], v[150:153], v[176:179], v[58:61]
	v_mfma_f32_16x16x32_bf16 v[46:49], v[142:145], v[184:187], v[46:49]
	v_mfma_f32_16x16x32_bf16 v[42:45], v[150:153], v[184:187], v[42:45]
	v_mfma_f32_16x16x32_bf16 v[30:33], v[142:145], v[192:195], v[30:33]
	v_mfma_f32_16x16x32_bf16 v[26:29], v[150:153], v[192:195], v[26:29]
	v_mfma_f32_16x16x32_bf16 v[14:17], v[142:145], v[200:203], v[14:17]
	v_mfma_f32_16x16x32_bf16 v[10:13], v[150:153], v[200:203], v[10:13]
	s_setprio 0
	s_setprio 1
	v_mfma_f32_16x16x32_bf16 v[54:57], v[154:157], v[172:175], v[54:57]
	v_mfma_f32_16x16x32_bf16 v[50:53], v[164:167], v[172:175], v[50:53]
	v_mfma_f32_16x16x32_bf16 v[38:41], v[154:157], v[180:183], v[38:41]
	v_mfma_f32_16x16x32_bf16 v[34:37], v[164:167], v[180:183], v[34:37]
	v_mfma_f32_16x16x32_bf16 v[22:25], v[154:157], v[188:191], v[22:25]
	v_mfma_f32_16x16x32_bf16 v[18:21], v[164:167], v[188:191], v[18:21]
	v_mfma_f32_16x16x32_bf16 v[6:9], v[154:157], v[196:199], v[6:9]
	v_mfma_f32_16x16x32_bf16 v[2:5], v[164:167], v[196:199], v[2:5]
	v_mfma_f32_16x16x32_bf16 v[54:57], v[160:163], v[176:179], v[54:57]
	v_mfma_f32_16x16x32_bf16 v[50:53], v[168:171], v[176:179], v[50:53]
	v_mfma_f32_16x16x32_bf16 v[38:41], v[160:163], v[184:187], v[38:41]
	v_mfma_f32_16x16x32_bf16 v[34:37], v[168:171], v[184:187], v[34:37]
	v_mfma_f32_16x16x32_bf16 v[22:25], v[160:163], v[192:195], v[22:25]
	v_mfma_f32_16x16x32_bf16 v[18:21], v[168:171], v[192:195], v[18:21]
	v_mfma_f32_16x16x32_bf16 v[6:9], v[160:163], v[200:203], v[6:9]
	v_mfma_f32_16x16x32_bf16 v[2:5], v[168:171], v[200:203], v[2:5]
	s_setprio 0
	s_barrier
	ds_read_b128 v[128:131], v0 offset:32768
	ds_read_b128 v[142:145], v0 offset:33792
	ds_read_b128 v[146:149], v0 offset:34816
	ds_read_b128 v[150:153], v0 offset:35840
	ds_read_b128 v[154:157], v0 offset:49152
	ds_read_b128 v[160:163], v0 offset:50176
	ds_read_b128 v[164:167], v0 offset:51200
	ds_read_b128 v[168:171], v0 offset:52224
	s_add_u32 s4, s22, 0xb0000
	s_mov_b32 m0, s49
	ds_read_b128 v[172:175], v127 offset:32768
	ds_read_b128 v[176:179], v127 offset:33792
	ds_read_b128 v[180:183], v127 offset:34816
	ds_read_b128 v[184:187], v127 offset:35840
	ds_read_b128 v[188:191], v127 offset:36864
	ds_read_b128 v[192:195], v127 offset:37888
	ds_read_b128 v[196:199], v127 offset:38912
	ds_read_b128 v[200:203], v127 offset:39936
	s_addc_u32 s5, s23, 0
	s_add_i32 s69, 0, 0x18000
	s_add_i32 s70, 0, 0x1c000
	s_nop 0
	global_load_lds_dwordx4 v122, s[4:5]
	s_mov_b32 m0, s50
	s_nop 0
	global_load_lds_dwordx4 v123, s[4:5]
	s_waitcnt vmcnt(8) lgkmcnt(0)
	s_setprio 1
	s_barrier
	v_mfma_f32_16x16x32_bf16 v[136:139], v[128:131], v[172:175], v[138:141]
	v_mfma_f32_16x16x32_bf16 v[132:135], v[146:149], v[172:175], v[132:135]
	v_mfma_f32_16x16x32_bf16 v[110:113], v[128:131], v[180:183], v[110:113]
	v_mfma_f32_16x16x32_bf16 v[106:109], v[146:149], v[180:183], v[106:109]
	v_mfma_f32_16x16x32_bf16 v[94:97], v[128:131], v[188:191], v[94:97]
	v_mfma_f32_16x16x32_bf16 v[90:93], v[146:149], v[188:191], v[90:93]
	v_mfma_f32_16x16x32_bf16 v[78:81], v[128:131], v[196:199], v[78:81]
	v_mfma_f32_16x16x32_bf16 v[74:77], v[146:149], v[196:199], v[74:77]
	v_mfma_f32_16x16x32_bf16 v[138:141], v[142:145], v[176:179], v[136:139]
	v_mfma_f32_16x16x32_bf16 v[134:137], v[150:153], v[176:179], v[132:135]
	v_mfma_f32_16x16x32_bf16 v[110:113], v[142:145], v[184:187], v[110:113]
	v_mfma_f32_16x16x32_bf16 v[106:109], v[150:153], v[184:187], v[106:109]
	v_mfma_f32_16x16x32_bf16 v[94:97], v[142:145], v[192:195], v[94:97]
	v_mfma_f32_16x16x32_bf16 v[90:93], v[150:153], v[192:195], v[90:93]
	v_mfma_f32_16x16x32_bf16 v[78:81], v[142:145], v[200:203], v[78:81]
	v_mfma_f32_16x16x32_bf16 v[74:77], v[150:153], v[200:203], v[74:77]
	s_setprio 0
	s_setprio 1
	v_mfma_f32_16x16x32_bf16 v[118:121], v[154:157], v[172:175], v[118:121]
	v_mfma_f32_16x16x32_bf16 v[114:117], v[164:167], v[172:175], v[114:117]
	v_mfma_f32_16x16x32_bf16 v[102:105], v[154:157], v[180:183], v[102:105]
	v_mfma_f32_16x16x32_bf16 v[98:101], v[164:167], v[180:183], v[98:101]
	v_mfma_f32_16x16x32_bf16 v[86:89], v[154:157], v[188:191], v[86:89]
	v_mfma_f32_16x16x32_bf16 v[82:85], v[164:167], v[188:191], v[82:85]
	v_mfma_f32_16x16x32_bf16 v[70:73], v[154:157], v[196:199], v[70:73]
	v_mfma_f32_16x16x32_bf16 v[66:69], v[164:167], v[196:199], v[66:69]
	v_mfma_f32_16x16x32_bf16 v[118:121], v[160:163], v[176:179], v[118:121]
	v_mfma_f32_16x16x32_bf16 v[114:117], v[168:171], v[176:179], v[114:117]
	v_mfma_f32_16x16x32_bf16 v[102:105], v[160:163], v[184:187], v[102:105]
	v_mfma_f32_16x16x32_bf16 v[98:101], v[168:171], v[184:187], v[98:101]
	v_mfma_f32_16x16x32_bf16 v[86:89], v[160:163], v[192:195], v[86:89]
	v_mfma_f32_16x16x32_bf16 v[82:85], v[168:171], v[192:195], v[82:85]
	v_mfma_f32_16x16x32_bf16 v[70:73], v[160:163], v[200:203], v[70:73]
	v_mfma_f32_16x16x32_bf16 v[66:69], v[168:171], v[200:203], v[66:69]
	s_setprio 0
	s_barrier
	ds_read_b128 v[172:175], v127 offset:49152
	ds_read_b128 v[176:179], v127 offset:50176
	ds_read_b128 v[180:183], v127 offset:51200
	ds_read_b128 v[184:187], v127 offset:52224
	ds_read_b128 v[188:191], v127 offset:53248
	ds_read_b128 v[192:195], v127 offset:54272
	ds_read_b128 v[196:199], v127 offset:55296
	ds_read_b128 v[200:203], v127 offset:56320
	s_add_i32 s4, s69, s26
	s_add_u32 s100, s46, s38
	s_addc_u32 s101, s47, s39
	s_mov_b32 m0, s4
	s_nop 0
	global_load_lds_dwordx4 v124, s[100:101]
	s_add_i32 m0, s4, 0x2000
	s_add_u32 s4, s46, 0xb0080
	s_addc_u32 s5, s47, 0
	s_add_i32 s46, s70, s26
	global_load_lds_dwordx4 v125, s[100:101]
	s_mov_b32 m0, s46
	s_nop 0
	global_load_lds_dwordx4 v124, s[4:5]
	s_add_i32 m0, s46, 0x2000
	s_nop 0
	global_load_lds_dwordx4 v125, s[4:5]
	s_mov_b32 m0, s64
	s_add_u32 s100, s22, s38
	s_addc_u32 s101, s23, s39
	v_mov_b32_e32 v0, v123
	global_load_lds_dwordx4 v122, s[100:101]
	s_mov_b32 m0, s65
	s_nop 0
	global_load_lds_dwordx4 v123, s[100:101]
	s_waitcnt vmcnt(8) lgkmcnt(0)
	s_setprio 1
	s_barrier
	v_mfma_f32_16x16x32_bf16 v[62:65], v[128:131], v[172:175], v[62:65]
	v_mfma_f32_16x16x32_bf16 v[58:61], v[146:149], v[172:175], v[58:61]
	v_mfma_f32_16x16x32_bf16 v[46:49], v[128:131], v[180:183], v[46:49]
	v_mfma_f32_16x16x32_bf16 v[42:45], v[146:149], v[180:183], v[42:45]
	v_mfma_f32_16x16x32_bf16 v[30:33], v[128:131], v[188:191], v[30:33]
	v_mfma_f32_16x16x32_bf16 v[26:29], v[146:149], v[188:191], v[26:29]
	v_mfma_f32_16x16x32_bf16 v[14:17], v[128:131], v[196:199], v[14:17]
	v_mfma_f32_16x16x32_bf16 v[10:13], v[146:149], v[196:199], v[10:13]
	v_mfma_f32_16x16x32_bf16 v[62:65], v[142:145], v[176:179], v[62:65]
	v_mfma_f32_16x16x32_bf16 v[58:61], v[150:153], v[176:179], v[58:61]
	v_mfma_f32_16x16x32_bf16 v[46:49], v[142:145], v[184:187], v[46:49]
	v_mfma_f32_16x16x32_bf16 v[42:45], v[150:153], v[184:187], v[42:45]
	v_mfma_f32_16x16x32_bf16 v[30:33], v[142:145], v[192:195], v[30:33]
	v_mfma_f32_16x16x32_bf16 v[26:29], v[150:153], v[192:195], v[26:29]
	v_mfma_f32_16x16x32_bf16 v[14:17], v[142:145], v[200:203], v[14:17]
	v_mfma_f32_16x16x32_bf16 v[10:13], v[150:153], v[200:203], v[10:13]
	s_setprio 0
	s_setprio 1
	v_mfma_f32_16x16x32_bf16 v[54:57], v[154:157], v[172:175], v[54:57]
	v_mfma_f32_16x16x32_bf16 v[50:53], v[164:167], v[172:175], v[50:53]
	v_mfma_f32_16x16x32_bf16 v[38:41], v[154:157], v[180:183], v[38:41]
	v_mfma_f32_16x16x32_bf16 v[34:37], v[164:167], v[180:183], v[34:37]
	v_mfma_f32_16x16x32_bf16 v[22:25], v[154:157], v[188:191], v[22:25]
	v_mfma_f32_16x16x32_bf16 v[18:21], v[164:167], v[188:191], v[18:21]
	v_mfma_f32_16x16x32_bf16 v[6:9], v[154:157], v[196:199], v[6:9]
	v_mfma_f32_16x16x32_bf16 v[2:5], v[164:167], v[196:199], v[2:5]
	v_mfma_f32_16x16x32_bf16 v[54:57], v[160:163], v[176:179], v[54:57]
	v_mfma_f32_16x16x32_bf16 v[50:53], v[168:171], v[176:179], v[50:53]
	v_mfma_f32_16x16x32_bf16 v[38:41], v[160:163], v[184:187], v[38:41]
	v_mfma_f32_16x16x32_bf16 v[34:37], v[168:171], v[184:187], v[34:37]
	v_mfma_f32_16x16x32_bf16 v[22:25], v[160:163], v[192:195], v[22:25]
	v_mfma_f32_16x16x32_bf16 v[18:21], v[168:171], v[192:195], v[18:21]
	v_mfma_f32_16x16x32_bf16 v[6:9], v[160:163], v[200:203], v[6:9]
	v_mfma_f32_16x16x32_bf16 v[2:5], v[168:171], v[200:203], v[2:5]
	s_setprio 0
	s_barrier
	s_add_i32 s68, s68, 2
	s_add_u32 s2, s2, 0x100
	s_addc_u32 s3, s3, 0
	s_cmp_gt_u32 s68, 41
	s_cbranch_scc0 .LBB0_869

.LBB0_953:
	s_add_i32 s51, 0, 0x10000
	v_add_u32_e32 v0, s51, v135
	ds_read_b128 v[138:141], v0
	ds_read_b128 v[142:145], v0 offset:1024
	ds_read_b128 v[146:149], v0 offset:2048
	ds_read_b128 v[150:153], v0 offset:3072
	ds_read_b128 v[154:157], v0 offset:16384
	ds_read_b128 v[158:161], v0 offset:17408
	ds_read_b128 v[162:165], v0 offset:18432
	ds_read_b128 v[166:169], v0 offset:19456
	ds_read_b128 v[170:173], v136
	ds_read_b128 v[174:177], v136 offset:1024
	ds_read_b128 v[178:181], v136 offset:2048
	ds_read_b128 v[182:185], v136 offset:3072
	ds_read_b128 v[186:189], v136 offset:4096
	ds_read_b128 v[190:193], v136 offset:5120
	ds_read_b128 v[194:197], v136 offset:6144
	ds_read_b128 v[198:201], v136 offset:7168
	s_add_u32 s58, s4, s2
	s_addc_u32 s59, s5, s3
	s_add_u32 s14, s58, 0x100
	s_addc_u32 s15, s59, 0
	s_add_u32 s16, s43, s2
	s_addc_u32 s17, s46, s3
	s_cmp_eq_u32 s50, 40
	s_cselect_b32 s15, s5, s15
	s_cselect_b32 s14, s4, s14
	s_cselect_b32 s17, s7, s17
	s_cselect_b32 s16, s6, s16
	s_add_i32 s60, 0, 0x14000
	s_add_i32 m0, s37, 0xc000
	s_add_u32 s100, s58, s62
	s_addc_u32 s101, s59, s63
	global_load_lds_dwordx4 v130, s[100:101]
	s_add_i32 m0, s37, 0xe000
	s_nop 0
	global_load_lds_dwordx4 v131, s[100:101]
	s_waitcnt vmcnt(8) lgkmcnt(0)
	s_setprio 1
	s_barrier
	v_mfma_f32_16x16x32_bf16 v[126:129], v[138:141], v[170:173], v[126:129]
	v_mfma_f32_16x16x32_bf16 v[122:125], v[146:149], v[170:173], v[122:125]
	v_mfma_f32_16x16x32_bf16 v[110:113], v[138:141], v[178:181], v[110:113]
	v_mfma_f32_16x16x32_bf16 v[106:109], v[146:149], v[178:181], v[106:109]
	v_mfma_f32_16x16x32_bf16 v[94:97], v[138:141], v[186:189], v[94:97]
	v_mfma_f32_16x16x32_bf16 v[90:93], v[146:149], v[186:189], v[90:93]
	v_mfma_f32_16x16x32_bf16 v[78:81], v[138:141], v[194:197], v[78:81]
	v_mfma_f32_16x16x32_bf16 v[74:77], v[146:149], v[194:197], v[74:77]
	v_mfma_f32_16x16x32_bf16 v[126:129], v[142:145], v[174:177], v[126:129]
	v_mfma_f32_16x16x32_bf16 v[122:125], v[150:153], v[174:177], v[122:125]
	v_mfma_f32_16x16x32_bf16 v[110:113], v[142:145], v[182:185], v[110:113]
	v_mfma_f32_16x16x32_bf16 v[106:109], v[150:153], v[182:185], v[106:109]
	v_mfma_f32_16x16x32_bf16 v[94:97], v[142:145], v[190:193], v[94:97]
	v_mfma_f32_16x16x32_bf16 v[90:93], v[150:153], v[190:193], v[90:93]
	v_mfma_f32_16x16x32_bf16 v[78:81], v[142:145], v[198:201], v[78:81]
	v_mfma_f32_16x16x32_bf16 v[74:77], v[150:153], v[198:201], v[74:77]
	s_setprio 0
	s_setprio 1
	v_mfma_f32_16x16x32_bf16 v[118:121], v[154:157], v[170:173], v[118:121]
	v_mfma_f32_16x16x32_bf16 v[114:117], v[162:165], v[170:173], v[114:117]
	v_mfma_f32_16x16x32_bf16 v[102:105], v[154:157], v[178:181], v[102:105]
	v_mfma_f32_16x16x32_bf16 v[98:101], v[162:165], v[178:181], v[98:101]
	v_mfma_f32_16x16x32_bf16 v[86:89], v[154:157], v[186:189], v[86:89]
	v_mfma_f32_16x16x32_bf16 v[82:85], v[162:165], v[186:189], v[82:85]
	v_mfma_f32_16x16x32_bf16 v[70:73], v[154:157], v[194:197], v[70:73]
	v_mfma_f32_16x16x32_bf16 v[66:69], v[162:165], v[194:197], v[66:69]
	v_mfma_f32_16x16x32_bf16 v[118:121], v[158:161], v[174:177], v[118:121]
	v_mfma_f32_16x16x32_bf16 v[114:117], v[166:169], v[174:177], v[114:117]
	v_mfma_f32_16x16x32_bf16 v[102:105], v[158:161], v[182:185], v[102:105]
	v_mfma_f32_16x16x32_bf16 v[98:101], v[166:169], v[182:185], v[98:101]
	v_mfma_f32_16x16x32_bf16 v[86:89], v[158:161], v[190:193], v[86:89]
	v_mfma_f32_16x16x32_bf16 v[82:85], v[166:169], v[190:193], v[82:85]
	v_mfma_f32_16x16x32_bf16 v[70:73], v[158:161], v[198:201], v[70:73]
	v_mfma_f32_16x16x32_bf16 v[66:69], v[166:169], v[198:201], v[66:69]
	s_setprio 0
	s_barrier
	ds_read_b128 v[170:173], v136 offset:16384
	ds_read_b128 v[174:177], v136 offset:17408
	ds_read_b128 v[178:181], v136 offset:18432
	ds_read_b128 v[182:185], v136 offset:19456
	ds_read_b128 v[186:189], v136 offset:20480
	ds_read_b128 v[190:193], v136 offset:21504
	ds_read_b128 v[194:197], v136 offset:22528
	ds_read_b128 v[198:201], v136 offset:23552
	s_add_i32 s51, s51, s26
	s_mov_b32 m0, s51
	s_nop 0
	global_load_lds_dwordx4 v133, s[16:17]
	s_add_i32 m0, s51, 0x2000
	s_add_u32 s58, s16, 0xb0000
	global_load_lds_dwordx4 v134, s[16:17]
	s_addc_u32 s59, s17, 0
	s_add_i32 s51, s60, s26
	s_mov_b32 m0, s51
	s_nop 0
	global_load_lds_dwordx4 v133, s[58:59]
	s_add_i32 m0, s51, 0x2000
	s_nop 0
	global_load_lds_dwordx4 v134, s[58:59]
	s_mov_b32 m0, s37
	s_nop 0
	global_load_lds_dwordx4 v130, s[14:15]
	s_mov_b32 m0, s40
	s_nop 0
	global_load_lds_dwordx4 v131, s[14:15]
	s_waitcnt vmcnt(8) lgkmcnt(0)
	s_setprio 1
	s_barrier
	v_mfma_f32_16x16x32_bf16 v[62:65], v[138:141], v[170:173], v[62:65]
	v_mfma_f32_16x16x32_bf16 v[58:61], v[146:149], v[170:173], v[58:61]
	v_mfma_f32_16x16x32_bf16 v[46:49], v[138:141], v[178:181], v[46:49]
	v_mfma_f32_16x16x32_bf16 v[42:45], v[146:149], v[178:181], v[42:45]
	v_mfma_f32_16x16x32_bf16 v[30:33], v[138:141], v[186:189], v[30:33]
	v_mfma_f32_16x16x32_bf16 v[26:29], v[146:149], v[186:189], v[26:29]
	v_mfma_f32_16x16x32_bf16 v[14:17], v[138:141], v[194:197], v[14:17]
	v_mfma_f32_16x16x32_bf16 v[10:13], v[146:149], v[194:197], v[10:13]
	v_mfma_f32_16x16x32_bf16 v[62:65], v[142:145], v[174:177], v[62:65]
	v_mfma_f32_16x16x32_bf16 v[58:61], v[150:153], v[174:177], v[58:61]
	v_mfma_f32_16x16x32_bf16 v[46:49], v[142:145], v[182:185], v[46:49]
	v_mfma_f32_16x16x32_bf16 v[42:45], v[150:153], v[182:185], v[42:45]
	v_mfma_f32_16x16x32_bf16 v[30:33], v[142:145], v[190:193], v[30:33]
	v_mfma_f32_16x16x32_bf16 v[26:29], v[150:153], v[190:193], v[26:29]
	v_mfma_f32_16x16x32_bf16 v[14:17], v[142:145], v[198:201], v[14:17]
	v_mfma_f32_16x16x32_bf16 v[10:13], v[150:153], v[198:201], v[10:13]
	s_setprio 0
	s_setprio 1
	v_mfma_f32_16x16x32_bf16 v[54:57], v[154:157], v[170:173], v[54:57]
	v_mfma_f32_16x16x32_bf16 v[50:53], v[162:165], v[170:173], v[50:53]
	v_mfma_f32_16x16x32_bf16 v[38:41], v[154:157], v[178:181], v[38:41]
	v_mfma_f32_16x16x32_bf16 v[34:37], v[162:165], v[178:181], v[34:37]
	v_mfma_f32_16x16x32_bf16 v[22:25], v[154:157], v[186:189], v[22:25]
	v_mfma_f32_16x16x32_bf16 v[18:21], v[162:165], v[186:189], v[18:21]
	v_mfma_f32_16x16x32_bf16 v[6:9], v[154:157], v[194:197], v[6:9]
	v_mfma_f32_16x16x32_bf16 v[2:5], v[162:165], v[194:197], v[2:5]
	v_mfma_f32_16x16x32_bf16 v[54:57], v[158:161], v[174:177], v[54:57]
	v_mfma_f32_16x16x32_bf16 v[50:53], v[166:169], v[174:177], v[50:53]
	v_mfma_f32_16x16x32_bf16 v[38:41], v[158:161], v[182:185], v[38:41]
	v_mfma_f32_16x16x32_bf16 v[34:37], v[166:169], v[182:185], v[34:37]
	v_mfma_f32_16x16x32_bf16 v[22:25], v[158:161], v[190:193], v[22:25]
	v_mfma_f32_16x16x32_bf16 v[18:21], v[166:169], v[190:193], v[18:21]
	v_mfma_f32_16x16x32_bf16 v[6:9], v[158:161], v[198:201], v[6:9]
	v_mfma_f32_16x16x32_bf16 v[2:5], v[166:169], v[198:201], v[2:5]
	s_setprio 0
	s_barrier
	ds_read_b128 v[138:141], v0 offset:32768
	ds_read_b128 v[142:145], v0 offset:33792
	ds_read_b128 v[146:149], v0 offset:34816
	ds_read_b128 v[150:153], v0 offset:35840
	ds_read_b128 v[154:157], v0 offset:49152
	ds_read_b128 v[158:161], v0 offset:50176
	ds_read_b128 v[162:165], v0 offset:51200
	ds_read_b128 v[166:169], v0 offset:52224
	s_add_u32 s58, s14, 0xb0000
	s_mov_b32 m0, s41
	ds_read_b128 v[170:173], v136 offset:32768
	ds_read_b128 v[174:177], v136 offset:33792
	ds_read_b128 v[178:181], v136 offset:34816
	ds_read_b128 v[182:185], v136 offset:35840
	ds_read_b128 v[186:189], v136 offset:36864
	ds_read_b128 v[190:193], v136 offset:37888
	ds_read_b128 v[194:197], v136 offset:38912
	ds_read_b128 v[198:201], v136 offset:39936
	s_addc_u32 s59, s15, 0
	s_add_i32 s51, 0, 0x18000
	s_add_i32 s60, 0, 0x1c000
	s_nop 0
	global_load_lds_dwordx4 v130, s[58:59]
	s_mov_b32 m0, s42
	s_nop 0
	global_load_lds_dwordx4 v131, s[58:59]
	s_waitcnt vmcnt(8) lgkmcnt(0)
	s_setprio 1
	s_barrier
	v_mfma_f32_16x16x32_bf16 v[126:129], v[138:141], v[170:173], v[126:129]
	v_mfma_f32_16x16x32_bf16 v[122:125], v[146:149], v[170:173], v[122:125]
	v_mfma_f32_16x16x32_bf16 v[110:113], v[138:141], v[178:181], v[110:113]
	v_mfma_f32_16x16x32_bf16 v[106:109], v[146:149], v[178:181], v[106:109]
	v_mfma_f32_16x16x32_bf16 v[94:97], v[138:141], v[186:189], v[94:97]
	v_mfma_f32_16x16x32_bf16 v[90:93], v[146:149], v[186:189], v[90:93]
	v_mfma_f32_16x16x32_bf16 v[78:81], v[138:141], v[194:197], v[78:81]
	v_mfma_f32_16x16x32_bf16 v[74:77], v[146:149], v[194:197], v[74:77]
	v_mfma_f32_16x16x32_bf16 v[126:129], v[142:145], v[174:177], v[126:129]
	v_mfma_f32_16x16x32_bf16 v[122:125], v[150:153], v[174:177], v[122:125]
	v_mfma_f32_16x16x32_bf16 v[110:113], v[142:145], v[182:185], v[110:113]
	v_mfma_f32_16x16x32_bf16 v[106:109], v[150:153], v[182:185], v[106:109]
	v_mfma_f32_16x16x32_bf16 v[94:97], v[142:145], v[190:193], v[94:97]
	v_mfma_f32_16x16x32_bf16 v[90:93], v[150:153], v[190:193], v[90:93]
	v_mfma_f32_16x16x32_bf16 v[78:81], v[142:145], v[198:201], v[78:81]
	v_mfma_f32_16x16x32_bf16 v[74:77], v[150:153], v[198:201], v[74:77]
	s_setprio 0
	s_setprio 1
	v_mfma_f32_16x16x32_bf16 v[118:121], v[154:157], v[170:173], v[118:121]
	v_mfma_f32_16x16x32_bf16 v[114:117], v[162:165], v[170:173], v[114:117]
	v_mfma_f32_16x16x32_bf16 v[102:105], v[154:157], v[178:181], v[102:105]
	v_mfma_f32_16x16x32_bf16 v[98:101], v[162:165], v[178:181], v[98:101]
	v_mfma_f32_16x16x32_bf16 v[86:89], v[154:157], v[186:189], v[86:89]
	v_mfma_f32_16x16x32_bf16 v[82:85], v[162:165], v[186:189], v[82:85]
	v_mfma_f32_16x16x32_bf16 v[70:73], v[154:157], v[194:197], v[70:73]
	v_mfma_f32_16x16x32_bf16 v[66:69], v[162:165], v[194:197], v[66:69]
	v_mfma_f32_16x16x32_bf16 v[118:121], v[158:161], v[174:177], v[118:121]
	v_mfma_f32_16x16x32_bf16 v[114:117], v[166:169], v[174:177], v[114:117]
	v_mfma_f32_16x16x32_bf16 v[102:105], v[158:161], v[182:185], v[102:105]
	v_mfma_f32_16x16x32_bf16 v[98:101], v[166:169], v[182:185], v[98:101]
	v_mfma_f32_16x16x32_bf16 v[86:89], v[158:161], v[190:193], v[86:89]
	v_mfma_f32_16x16x32_bf16 v[82:85], v[166:169], v[190:193], v[82:85]
	v_mfma_f32_16x16x32_bf16 v[70:73], v[158:161], v[198:201], v[70:73]
	v_mfma_f32_16x16x32_bf16 v[66:69], v[166:169], v[198:201], v[66:69]
	s_setprio 0
	s_barrier
	ds_read_b128 v[170:173], v136 offset:49152
	ds_read_b128 v[174:177], v136 offset:50176
	ds_read_b128 v[178:181], v136 offset:51200
	ds_read_b128 v[182:185], v136 offset:52224
	ds_read_b128 v[186:189], v136 offset:53248
	ds_read_b128 v[190:193], v136 offset:54272
	ds_read_b128 v[194:197], v136 offset:55296
	ds_read_b128 v[198:201], v136 offset:56320
	s_add_i32 s51, s51, s26
	s_add_u32 s100, s16, s38
	s_addc_u32 s101, s17, s39
	s_mov_b32 m0, s51
	s_nop 0
	global_load_lds_dwordx4 v133, s[100:101]
	s_add_i32 m0, s51, 0x2000
	s_nop 0
	s_add_u32 s16, s16, 0xb0080
	s_addc_u32 s17, s17, 0
	s_add_i32 s51, s60, s26
	global_load_lds_dwordx4 v134, s[100:101]
	s_mov_b32 m0, s51
	s_nop 0
	global_load_lds_dwordx4 v133, s[16:17]
	s_add_i32 m0, s51, 0x2000
	s_nop 0
	global_load_lds_dwordx4 v134, s[16:17]
	s_mov_b32 m0, s48
	s_add_u32 s100, s14, s38
	s_addc_u32 s101, s15, s39
	v_mov_b32_e32 v0, v131
	global_load_lds_dwordx4 v130, s[100:101]
	s_mov_b32 m0, s49
	s_nop 0
	global_load_lds_dwordx4 v131, s[100:101]
	s_waitcnt vmcnt(8) lgkmcnt(0)
	s_setprio 1
	s_barrier
	v_mfma_f32_16x16x32_bf16 v[62:65], v[138:141], v[170:173], v[62:65]
	v_mfma_f32_16x16x32_bf16 v[58:61], v[146:149], v[170:173], v[58:61]
	v_mfma_f32_16x16x32_bf16 v[46:49], v[138:141], v[178:181], v[46:49]
	v_mfma_f32_16x16x32_bf16 v[42:45], v[146:149], v[178:181], v[42:45]
	v_mfma_f32_16x16x32_bf16 v[30:33], v[138:141], v[186:189], v[30:33]
	v_mfma_f32_16x16x32_bf16 v[26:29], v[146:149], v[186:189], v[26:29]
	v_mfma_f32_16x16x32_bf16 v[14:17], v[138:141], v[194:197], v[14:17]
	v_mfma_f32_16x16x32_bf16 v[10:13], v[146:149], v[194:197], v[10:13]
	v_mfma_f32_16x16x32_bf16 v[62:65], v[142:145], v[174:177], v[62:65]
	v_mfma_f32_16x16x32_bf16 v[58:61], v[150:153], v[174:177], v[58:61]
	v_mfma_f32_16x16x32_bf16 v[46:49], v[142:145], v[182:185], v[46:49]
	v_mfma_f32_16x16x32_bf16 v[42:45], v[150:153], v[182:185], v[42:45]
	v_mfma_f32_16x16x32_bf16 v[30:33], v[142:145], v[190:193], v[30:33]
	v_mfma_f32_16x16x32_bf16 v[26:29], v[150:153], v[190:193], v[26:29]
	v_mfma_f32_16x16x32_bf16 v[14:17], v[142:145], v[198:201], v[14:17]
	v_mfma_f32_16x16x32_bf16 v[10:13], v[150:153], v[198:201], v[10:13]
	s_setprio 0
	s_setprio 1
	v_mfma_f32_16x16x32_bf16 v[54:57], v[154:157], v[170:173], v[54:57]
	v_mfma_f32_16x16x32_bf16 v[50:53], v[162:165], v[170:173], v[50:53]
	v_mfma_f32_16x16x32_bf16 v[38:41], v[154:157], v[178:181], v[38:41]
	v_mfma_f32_16x16x32_bf16 v[34:37], v[162:165], v[178:181], v[34:37]
	v_mfma_f32_16x16x32_bf16 v[22:25], v[154:157], v[186:189], v[22:25]
	v_mfma_f32_16x16x32_bf16 v[18:21], v[162:165], v[186:189], v[18:21]
	v_mfma_f32_16x16x32_bf16 v[6:9], v[154:157], v[194:197], v[6:9]
	v_mfma_f32_16x16x32_bf16 v[2:5], v[162:165], v[194:197], v[2:5]
	v_mfma_f32_16x16x32_bf16 v[54:57], v[158:161], v[174:177], v[54:57]
	v_mfma_f32_16x16x32_bf16 v[50:53], v[166:169], v[174:177], v[50:53]
	v_mfma_f32_16x16x32_bf16 v[38:41], v[158:161], v[182:185], v[38:41]
	v_mfma_f32_16x16x32_bf16 v[34:37], v[166:169], v[182:185], v[34:37]
	v_mfma_f32_16x16x32_bf16 v[22:25], v[158:161], v[190:193], v[22:25]
	v_mfma_f32_16x16x32_bf16 v[18:21], v[166:169], v[190:193], v[18:21]
	v_mfma_f32_16x16x32_bf16 v[6:9], v[158:161], v[198:201], v[6:9]
	v_mfma_f32_16x16x32_bf16 v[2:5], v[166:169], v[198:201], v[2:5]
	s_setprio 0
	s_barrier
	s_add_i32 s50, s50, 2
	s_add_u32 s2, s2, 0x100
	s_addc_u32 s3, s3, 0
	s_cmp_gt_u32 s50, 41
	s_cbranch_scc0 .LBB0_953

.LBB0_1087:
	s_add_u32 s2, s6, 0x40080
	s_addc_u32 s3, s7, 0
	s_add_u32 s8, s8, 0x100
	s_addc_u32 s9, s9, 0
	s_mov_b32 s22, -2
	s_add_u32 s4, s2, 0xfffc0080
	s_addc_u32 s5, s3, -1
	s_add_i32 s23, 0, 0x10000
	s_cmp_eq_u32 s22, 12
	s_cselect_b32 s5, s49, s5
	s_cselect_b32 s4, s48, s4
	s_waitcnt vmcnt(0)
	v_add_u32_e32 v0, s23, v145
	s_cselect_b32 s7, s97, s9
	s_cselect_b32 s6, s96, s8
	s_add_i32 s25, 0, 0x14000
	ds_read_b128 v[146:149], v0
	ds_read_b128 v[152:155], v0 offset:1024
	ds_read_b128 v[156:159], v0 offset:2048
	ds_read_b128 v[160:163], v0 offset:3072
	ds_read_b128 v[164:167], v0 offset:16384
	ds_read_b128 v[168:171], v0 offset:17408
	ds_read_b128 v[172:175], v0 offset:18432
	ds_read_b128 v[176:179], v0 offset:19456
	ds_read_b128 v[180:183], v150
	ds_read_b128 v[184:187], v150 offset:1024
	ds_read_b128 v[188:191], v150 offset:2048
	ds_read_b128 v[192:195], v150 offset:3072
	ds_read_b128 v[196:199], v150 offset:4096
	ds_read_b128 v[200:203], v150 offset:5120
	ds_read_b128 v[204:207], v150 offset:6144
	ds_read_b128 v[208:211], v150 offset:7168
	s_add_i32 m0, s60, 0xc000
	s_nop 0
	global_load_lds_dwordx4 v131, s[2:3]
	s_add_i32 m0, s60, 0xe000
	s_nop 0
	global_load_lds_dwordx4 v133, s[2:3]
	s_waitcnt vmcnt(8) lgkmcnt(0)
	s_setprio 1
	s_barrier
	v_mfma_f32_16x16x32_bf16 v[126:129], v[146:149], v[180:183], 0
	v_mfma_f32_16x16x32_bf16 v[122:125], v[156:159], v[180:183], 0
	v_mfma_f32_16x16x32_bf16 v[110:113], v[146:149], v[188:191], 0
	v_mfma_f32_16x16x32_bf16 v[106:109], v[156:159], v[188:191], 0
	v_mfma_f32_16x16x32_bf16 v[94:97], v[146:149], v[196:199], 0
	v_mfma_f32_16x16x32_bf16 v[90:93], v[156:159], v[196:199], 0
	v_mfma_f32_16x16x32_bf16 v[78:81], v[146:149], v[204:207], 0
	v_mfma_f32_16x16x32_bf16 v[74:77], v[156:159], v[204:207], 0
	v_mfma_f32_16x16x32_bf16 v[126:129], v[152:155], v[184:187], v[126:129]
	v_mfma_f32_16x16x32_bf16 v[122:125], v[160:163], v[184:187], v[122:125]
	v_mfma_f32_16x16x32_bf16 v[110:113], v[152:155], v[192:195], v[110:113]
	v_mfma_f32_16x16x32_bf16 v[106:109], v[160:163], v[192:195], v[106:109]
	v_mfma_f32_16x16x32_bf16 v[94:97], v[152:155], v[200:203], v[94:97]
	v_mfma_f32_16x16x32_bf16 v[90:93], v[160:163], v[200:203], v[90:93]
	v_mfma_f32_16x16x32_bf16 v[78:81], v[152:155], v[208:211], v[78:81]
	v_mfma_f32_16x16x32_bf16 v[74:77], v[160:163], v[208:211], v[74:77]
	s_setprio 0
	s_setprio 1
	v_mfma_f32_16x16x32_bf16 v[118:121], v[164:167], v[180:183], 0
	v_mfma_f32_16x16x32_bf16 v[114:117], v[172:175], v[180:183], 0
	v_mfma_f32_16x16x32_bf16 v[102:105], v[164:167], v[188:191], 0
	v_mfma_f32_16x16x32_bf16 v[98:101], v[172:175], v[188:191], 0
	v_mfma_f32_16x16x32_bf16 v[86:89], v[164:167], v[196:199], 0
	v_mfma_f32_16x16x32_bf16 v[82:85], v[172:175], v[196:199], 0
	v_mfma_f32_16x16x32_bf16 v[70:73], v[164:167], v[204:207], 0
	v_mfma_f32_16x16x32_bf16 v[66:69], v[172:175], v[204:207], 0
	v_mfma_f32_16x16x32_bf16 v[118:121], v[168:171], v[184:187], v[118:121]
	v_mfma_f32_16x16x32_bf16 v[114:117], v[176:179], v[184:187], v[114:117]
	v_mfma_f32_16x16x32_bf16 v[102:105], v[168:171], v[192:195], v[102:105]
	v_mfma_f32_16x16x32_bf16 v[98:101], v[176:179], v[192:195], v[98:101]
	v_mfma_f32_16x16x32_bf16 v[86:89], v[168:171], v[200:203], v[86:89]
	v_mfma_f32_16x16x32_bf16 v[82:85], v[176:179], v[200:203], v[82:85]
	v_mfma_f32_16x16x32_bf16 v[70:73], v[168:171], v[208:211], v[70:73]
	v_mfma_f32_16x16x32_bf16 v[66:69], v[176:179], v[208:211], v[66:69]
	s_setprio 0
	s_barrier
	ds_read_b128 v[180:183], v150 offset:16384
	ds_read_b128 v[184:187], v150 offset:17408
	ds_read_b128 v[188:191], v150 offset:18432
	ds_read_b128 v[192:195], v150 offset:19456
	ds_read_b128 v[196:199], v150 offset:20480
	ds_read_b128 v[200:203], v150 offset:21504
	ds_read_b128 v[204:207], v150 offset:22528
	ds_read_b128 v[208:211], v150 offset:23552
	s_add_i32 s23, s23, s42
	s_mov_b32 m0, s23
	s_nop 0
	global_load_lds_dwordx4 v137, s[6:7]
	s_add_i32 m0, s23, 0x2000
	s_add_u32 s46, s6, 0x40000
	global_load_lds_dwordx4 v139, s[6:7]
	s_addc_u32 s47, s7, 0
	s_add_i32 s23, s25, s42
	s_mov_b32 m0, s23
	s_nop 0
	global_load_lds_dwordx4 v137, s[46:47]
	s_add_i32 m0, s23, 0x2000
	s_nop 0
	global_load_lds_dwordx4 v139, s[46:47]
	s_mov_b32 m0, s60
	s_nop 0
	global_load_lds_dwordx4 v131, s[4:5]
	s_mov_b32 m0, s61
	s_nop 0
	global_load_lds_dwordx4 v133, s[4:5]
	s_waitcnt vmcnt(8) lgkmcnt(0)
	s_setprio 1
	s_barrier
	v_mfma_f32_16x16x32_bf16 v[62:65], v[146:149], v[180:183], 0
	v_mfma_f32_16x16x32_bf16 v[58:61], v[156:159], v[180:183], 0
	v_mfma_f32_16x16x32_bf16 v[46:49], v[146:149], v[188:191], 0
	v_mfma_f32_16x16x32_bf16 v[42:45], v[156:159], v[188:191], 0
	v_mfma_f32_16x16x32_bf16 v[30:33], v[146:149], v[196:199], 0
	v_mfma_f32_16x16x32_bf16 v[26:29], v[156:159], v[196:199], 0
	v_mfma_f32_16x16x32_bf16 v[14:17], v[146:149], v[204:207], 0
	v_mfma_f32_16x16x32_bf16 v[10:13], v[156:159], v[204:207], 0
	v_mfma_f32_16x16x32_bf16 v[62:65], v[152:155], v[184:187], v[62:65]
	v_mfma_f32_16x16x32_bf16 v[58:61], v[160:163], v[184:187], v[58:61]
	v_mfma_f32_16x16x32_bf16 v[46:49], v[152:155], v[192:195], v[46:49]
	v_mfma_f32_16x16x32_bf16 v[42:45], v[160:163], v[192:195], v[42:45]
	v_mfma_f32_16x16x32_bf16 v[30:33], v[152:155], v[200:203], v[30:33]
	v_mfma_f32_16x16x32_bf16 v[26:29], v[160:163], v[200:203], v[26:29]
	v_mfma_f32_16x16x32_bf16 v[14:17], v[152:155], v[208:211], v[14:17]
	v_mfma_f32_16x16x32_bf16 v[10:13], v[160:163], v[208:211], v[10:13]
	s_setprio 0
	s_setprio 1
	v_mfma_f32_16x16x32_bf16 v[54:57], v[164:167], v[180:183], 0
	v_mfma_f32_16x16x32_bf16 v[50:53], v[172:175], v[180:183], 0
	v_mfma_f32_16x16x32_bf16 v[38:41], v[164:167], v[188:191], 0
	v_mfma_f32_16x16x32_bf16 v[34:37], v[172:175], v[188:191], 0
	v_mfma_f32_16x16x32_bf16 v[22:25], v[164:167], v[196:199], 0
	v_mfma_f32_16x16x32_bf16 v[18:21], v[172:175], v[196:199], 0
	v_mfma_f32_16x16x32_bf16 v[6:9], v[164:167], v[204:207], 0
	v_mfma_f32_16x16x32_bf16 v[2:5], v[172:175], v[204:207], 0
	v_mfma_f32_16x16x32_bf16 v[54:57], v[168:171], v[184:187], v[54:57]
	v_mfma_f32_16x16x32_bf16 v[50:53], v[176:179], v[184:187], v[50:53]
	v_mfma_f32_16x16x32_bf16 v[38:41], v[168:171], v[192:195], v[38:41]
	v_mfma_f32_16x16x32_bf16 v[34:37], v[176:179], v[192:195], v[34:37]
	v_mfma_f32_16x16x32_bf16 v[22:25], v[168:171], v[200:203], v[22:25]
	v_mfma_f32_16x16x32_bf16 v[18:21], v[176:179], v[200:203], v[18:21]
	v_mfma_f32_16x16x32_bf16 v[6:9], v[168:171], v[208:211], v[6:9]
	v_mfma_f32_16x16x32_bf16 v[2:5], v[176:179], v[208:211], v[2:5]
	s_setprio 0
	s_barrier
	ds_read_b128 v[146:149], v0 offset:32768
	ds_read_b128 v[152:155], v0 offset:33792
	ds_read_b128 v[156:159], v0 offset:34816
	ds_read_b128 v[160:163], v0 offset:35840
	ds_read_b128 v[164:167], v0 offset:49152
	ds_read_b128 v[168:171], v0 offset:50176
	ds_read_b128 v[172:175], v0 offset:51200
	ds_read_b128 v[176:179], v0 offset:52224
	s_add_u32 s46, s4, 0x40000
	s_mov_b32 m0, s66
	ds_read_b128 v[180:183], v150 offset:32768
	ds_read_b128 v[184:187], v150 offset:33792
	ds_read_b128 v[188:191], v150 offset:34816
	ds_read_b128 v[192:195], v150 offset:35840
	ds_read_b128 v[196:199], v150 offset:36864
	ds_read_b128 v[200:203], v150 offset:37888
	ds_read_b128 v[204:207], v150 offset:38912
	ds_read_b128 v[208:211], v150 offset:39936
	s_addc_u32 s47, s5, 0
	s_add_i32 s23, 0, 0x18000
	s_add_i32 s25, 0, 0x1c000
	s_nop 0
	global_load_lds_dwordx4 v131, s[46:47]
	s_mov_b32 m0, s67
	s_nop 0
	global_load_lds_dwordx4 v133, s[46:47]
	s_waitcnt vmcnt(8) lgkmcnt(0)
	s_setprio 1
	s_barrier
	v_mfma_f32_16x16x32_bf16 v[126:129], v[146:149], v[180:183], v[126:129]
	v_mfma_f32_16x16x32_bf16 v[122:125], v[156:159], v[180:183], v[122:125]
	v_mfma_f32_16x16x32_bf16 v[110:113], v[146:149], v[188:191], v[110:113]
	v_mfma_f32_16x16x32_bf16 v[106:109], v[156:159], v[188:191], v[106:109]
	v_mfma_f32_16x16x32_bf16 v[94:97], v[146:149], v[196:199], v[94:97]
	v_mfma_f32_16x16x32_bf16 v[90:93], v[156:159], v[196:199], v[90:93]
	v_mfma_f32_16x16x32_bf16 v[78:81], v[146:149], v[204:207], v[78:81]
	v_mfma_f32_16x16x32_bf16 v[74:77], v[156:159], v[204:207], v[74:77]
	v_mfma_f32_16x16x32_bf16 v[126:129], v[152:155], v[184:187], v[126:129]
	v_mfma_f32_16x16x32_bf16 v[122:125], v[160:163], v[184:187], v[122:125]
	v_mfma_f32_16x16x32_bf16 v[110:113], v[152:155], v[192:195], v[110:113]
	v_mfma_f32_16x16x32_bf16 v[106:109], v[160:163], v[192:195], v[106:109]
	v_mfma_f32_16x16x32_bf16 v[94:97], v[152:155], v[200:203], v[94:97]
	v_mfma_f32_16x16x32_bf16 v[90:93], v[160:163], v[200:203], v[90:93]
	v_mfma_f32_16x16x32_bf16 v[78:81], v[152:155], v[208:211], v[78:81]
	v_mfma_f32_16x16x32_bf16 v[74:77], v[160:163], v[208:211], v[74:77]
	s_setprio 0
	s_setprio 1
	v_mfma_f32_16x16x32_bf16 v[118:121], v[164:167], v[180:183], v[118:121]
	v_mfma_f32_16x16x32_bf16 v[114:117], v[172:175], v[180:183], v[114:117]
	v_mfma_f32_16x16x32_bf16 v[102:105], v[164:167], v[188:191], v[102:105]
	v_mfma_f32_16x16x32_bf16 v[98:101], v[172:175], v[188:191], v[98:101]
	v_mfma_f32_16x16x32_bf16 v[86:89], v[164:167], v[196:199], v[86:89]
	v_mfma_f32_16x16x32_bf16 v[82:85], v[172:175], v[196:199], v[82:85]
	v_mfma_f32_16x16x32_bf16 v[70:73], v[164:167], v[204:207], v[70:73]
	v_mfma_f32_16x16x32_bf16 v[66:69], v[172:175], v[204:207], v[66:69]
	v_mfma_f32_16x16x32_bf16 v[118:121], v[168:171], v[184:187], v[118:121]
	v_mfma_f32_16x16x32_bf16 v[114:117], v[176:179], v[184:187], v[114:117]
	v_mfma_f32_16x16x32_bf16 v[102:105], v[168:171], v[192:195], v[102:105]
	v_mfma_f32_16x16x32_bf16 v[98:101], v[176:179], v[192:195], v[98:101]
	v_mfma_f32_16x16x32_bf16 v[86:89], v[168:171], v[200:203], v[86:89]
	v_mfma_f32_16x16x32_bf16 v[82:85], v[176:179], v[200:203], v[82:85]
	v_mfma_f32_16x16x32_bf16 v[70:73], v[168:171], v[208:211], v[70:73]
	v_mfma_f32_16x16x32_bf16 v[66:69], v[176:179], v[208:211], v[66:69]
	s_setprio 0
	s_barrier
	ds_read_b128 v[180:183], v150 offset:49152
	ds_read_b128 v[184:187], v150 offset:50176
	ds_read_b128 v[188:191], v150 offset:51200
	ds_read_b128 v[192:195], v150 offset:52224
	ds_read_b128 v[196:199], v150 offset:53248
	ds_read_b128 v[200:203], v150 offset:54272
	ds_read_b128 v[204:207], v150 offset:55296
	ds_read_b128 v[208:211], v150 offset:56320
	s_add_i32 s23, s23, s42
	s_add_u32 s100, s6, s38
	s_addc_u32 s101, s7, s39
	s_mov_b32 m0, s23
	s_nop 0
	global_load_lds_dwordx4 v137, s[100:101]
	s_add_i32 m0, s23, 0x2000
	s_nop 0
	s_add_u32 s6, s6, 0x40080
	s_addc_u32 s7, s7, 0
	s_add_i32 s23, s25, s42
	global_load_lds_dwordx4 v139, s[100:101]
	s_mov_b32 m0, s23
	s_nop 0
	global_load_lds_dwordx4 v137, s[6:7]
	s_add_i32 m0, s23, 0x2000
	s_nop 0
	global_load_lds_dwordx4 v139, s[6:7]
	s_mov_b32 m0, s70
	s_add_u32 s100, s4, s38
	s_addc_u32 s101, s5, s39
	v_mov_b32_e32 v0, v133
	global_load_lds_dwordx4 v131, s[100:101]
	s_mov_b32 m0, s71
	s_nop 0
	global_load_lds_dwordx4 v133, s[100:101]
	s_waitcnt vmcnt(8) lgkmcnt(0)
	s_setprio 1
	s_barrier
	v_mfma_f32_16x16x32_bf16 v[62:65], v[146:149], v[180:183], v[62:65]
	v_mfma_f32_16x16x32_bf16 v[58:61], v[156:159], v[180:183], v[58:61]
	v_mfma_f32_16x16x32_bf16 v[46:49], v[146:149], v[188:191], v[46:49]
	v_mfma_f32_16x16x32_bf16 v[42:45], v[156:159], v[188:191], v[42:45]
	v_mfma_f32_16x16x32_bf16 v[30:33], v[146:149], v[196:199], v[30:33]
	v_mfma_f32_16x16x32_bf16 v[26:29], v[156:159], v[196:199], v[26:29]
	v_mfma_f32_16x16x32_bf16 v[14:17], v[146:149], v[204:207], v[14:17]
	v_mfma_f32_16x16x32_bf16 v[10:13], v[156:159], v[204:207], v[10:13]
	v_mfma_f32_16x16x32_bf16 v[62:65], v[152:155], v[184:187], v[62:65]
	v_mfma_f32_16x16x32_bf16 v[58:61], v[160:163], v[184:187], v[58:61]
	v_mfma_f32_16x16x32_bf16 v[46:49], v[152:155], v[192:195], v[46:49]
	v_mfma_f32_16x16x32_bf16 v[42:45], v[160:163], v[192:195], v[42:45]
	v_mfma_f32_16x16x32_bf16 v[30:33], v[152:155], v[200:203], v[30:33]
	v_mfma_f32_16x16x32_bf16 v[26:29], v[160:163], v[200:203], v[26:29]
	v_mfma_f32_16x16x32_bf16 v[14:17], v[152:155], v[208:211], v[14:17]
	v_mfma_f32_16x16x32_bf16 v[10:13], v[160:163], v[208:211], v[10:13]
	s_setprio 0
	s_setprio 1
	v_mfma_f32_16x16x32_bf16 v[54:57], v[164:167], v[180:183], v[54:57]
	v_mfma_f32_16x16x32_bf16 v[50:53], v[172:175], v[180:183], v[50:53]
	v_mfma_f32_16x16x32_bf16 v[38:41], v[164:167], v[188:191], v[38:41]
	v_mfma_f32_16x16x32_bf16 v[34:37], v[172:175], v[188:191], v[34:37]
	v_mfma_f32_16x16x32_bf16 v[22:25], v[164:167], v[196:199], v[22:25]
	v_mfma_f32_16x16x32_bf16 v[18:21], v[172:175], v[196:199], v[18:21]
	v_mfma_f32_16x16x32_bf16 v[6:9], v[164:167], v[204:207], v[6:9]
	v_mfma_f32_16x16x32_bf16 v[2:5], v[172:175], v[204:207], v[2:5]
	v_mfma_f32_16x16x32_bf16 v[54:57], v[168:171], v[184:187], v[54:57]
	v_mfma_f32_16x16x32_bf16 v[50:53], v[176:179], v[184:187], v[50:53]
	v_mfma_f32_16x16x32_bf16 v[38:41], v[168:171], v[192:195], v[38:41]
	v_mfma_f32_16x16x32_bf16 v[34:37], v[176:179], v[192:195], v[34:37]
	v_mfma_f32_16x16x32_bf16 v[22:25], v[168:171], v[200:203], v[22:25]
	v_mfma_f32_16x16x32_bf16 v[18:21], v[176:179], v[200:203], v[18:21]
	v_mfma_f32_16x16x32_bf16 v[6:9], v[168:171], v[208:211], v[6:9]
	v_mfma_f32_16x16x32_bf16 v[2:5], v[176:179], v[208:211], v[2:5]
	s_setprio 0
	s_barrier
	s_add_i32 s22, s22, 2
	s_add_u32 s2, s2, 0x100
	s_addc_u32 s3, s3, 0
	s_add_u32 s8, s8, 0x100
	s_addc_u32 s9, s9, 0
	s_cmp_gt_u32 s22, 13
	s_cbranch_scc0 .LBB0_1088
	s_branch .Lpeel_exit_1088
	.p2align	6
.LBB0_1088:
	s_add_i32 s23, 0, 0x10000
	v_add_u32_e32 v0, s23, v145
	ds_read_b128 v[146:149], v0
	ds_read_b128 v[152:155], v0 offset:1024
	ds_read_b128 v[156:159], v0 offset:2048
	ds_read_b128 v[160:163], v0 offset:3072
	ds_read_b128 v[164:167], v0 offset:16384
	ds_read_b128 v[168:171], v0 offset:17408
	ds_read_b128 v[172:175], v0 offset:18432
	ds_read_b128 v[176:179], v0 offset:19456
	ds_read_b128 v[180:183], v150
	ds_read_b128 v[184:187], v150 offset:1024
	ds_read_b128 v[188:191], v150 offset:2048
	ds_read_b128 v[192:195], v150 offset:3072
	ds_read_b128 v[196:199], v150 offset:4096
	ds_read_b128 v[200:203], v150 offset:5120
	ds_read_b128 v[204:207], v150 offset:6144
	ds_read_b128 v[208:211], v150 offset:7168
	s_add_u32 s4, s2, 0xfffc0080
	s_addc_u32 s5, s3, -1
	s_cmp_eq_u32 s22, 12
	s_cselect_b32 s5, s49, s5
	s_cselect_b32 s4, s48, s4
	s_cselect_b32 s7, s97, s9
	s_cselect_b32 s6, s96, s8
	s_add_i32 s25, 0, 0x14000
	s_add_i32 m0, s60, 0xc000
	s_nop 0
	global_load_lds_dwordx4 v131, s[2:3]
	s_add_i32 m0, s60, 0xe000
	s_nop 0
	global_load_lds_dwordx4 v133, s[2:3]
	s_waitcnt vmcnt(8) lgkmcnt(0)
	s_setprio 1
	s_barrier
	v_mfma_f32_16x16x32_bf16 v[126:129], v[146:149], v[180:183], v[126:129]
	v_mfma_f32_16x16x32_bf16 v[122:125], v[156:159], v[180:183], v[122:125]
	v_mfma_f32_16x16x32_bf16 v[110:113], v[146:149], v[188:191], v[110:113]
	v_mfma_f32_16x16x32_bf16 v[106:109], v[156:159], v[188:191], v[106:109]
	v_mfma_f32_16x16x32_bf16 v[94:97], v[146:149], v[196:199], v[94:97]
	v_mfma_f32_16x16x32_bf16 v[90:93], v[156:159], v[196:199], v[90:93]
	v_mfma_f32_16x16x32_bf16 v[78:81], v[146:149], v[204:207], v[78:81]
	v_mfma_f32_16x16x32_bf16 v[74:77], v[156:159], v[204:207], v[74:77]
	v_mfma_f32_16x16x32_bf16 v[126:129], v[152:155], v[184:187], v[126:129]
	v_mfma_f32_16x16x32_bf16 v[122:125], v[160:163], v[184:187], v[122:125]
	v_mfma_f32_16x16x32_bf16 v[110:113], v[152:155], v[192:195], v[110:113]
	v_mfma_f32_16x16x32_bf16 v[106:109], v[160:163], v[192:195], v[106:109]
	v_mfma_f32_16x16x32_bf16 v[94:97], v[152:155], v[200:203], v[94:97]
	v_mfma_f32_16x16x32_bf16 v[90:93], v[160:163], v[200:203], v[90:93]
	v_mfma_f32_16x16x32_bf16 v[78:81], v[152:155], v[208:211], v[78:81]
	v_mfma_f32_16x16x32_bf16 v[74:77], v[160:163], v[208:211], v[74:77]
	s_setprio 0
	s_setprio 1
	v_mfma_f32_16x16x32_bf16 v[118:121], v[164:167], v[180:183], v[118:121]
	v_mfma_f32_16x16x32_bf16 v[114:117], v[172:175], v[180:183], v[114:117]
	v_mfma_f32_16x16x32_bf16 v[102:105], v[164:167], v[188:191], v[102:105]
	v_mfma_f32_16x16x32_bf16 v[98:101], v[172:175], v[188:191], v[98:101]
	v_mfma_f32_16x16x32_bf16 v[86:89], v[164:167], v[196:199], v[86:89]
	v_mfma_f32_16x16x32_bf16 v[82:85], v[172:175], v[196:199], v[82:85]
	v_mfma_f32_16x16x32_bf16 v[70:73], v[164:167], v[204:207], v[70:73]
	v_mfma_f32_16x16x32_bf16 v[66:69], v[172:175], v[204:207], v[66:69]
	v_mfma_f32_16x16x32_bf16 v[118:121], v[168:171], v[184:187], v[118:121]
	v_mfma_f32_16x16x32_bf16 v[114:117], v[176:179], v[184:187], v[114:117]
	v_mfma_f32_16x16x32_bf16 v[102:105], v[168:171], v[192:195], v[102:105]
	v_mfma_f32_16x16x32_bf16 v[98:101], v[176:179], v[192:195], v[98:101]
	v_mfma_f32_16x16x32_bf16 v[86:89], v[168:171], v[200:203], v[86:89]
	v_mfma_f32_16x16x32_bf16 v[82:85], v[176:179], v[200:203], v[82:85]
	v_mfma_f32_16x16x32_bf16 v[70:73], v[168:171], v[208:211], v[70:73]
	v_mfma_f32_16x16x32_bf16 v[66:69], v[176:179], v[208:211], v[66:69]
	s_setprio 0
	s_barrier
	ds_read_b128 v[180:183], v150 offset:16384
	ds_read_b128 v[184:187], v150 offset:17408
	ds_read_b128 v[188:191], v150 offset:18432
	ds_read_b128 v[192:195], v150 offset:19456
	ds_read_b128 v[196:199], v150 offset:20480
	ds_read_b128 v[200:203], v150 offset:21504
	ds_read_b128 v[204:207], v150 offset:22528
	ds_read_b128 v[208:211], v150 offset:23552
	s_add_i32 s23, s23, s42
	s_mov_b32 m0, s23
	s_nop 0
	global_load_lds_dwordx4 v137, s[6:7]
	s_add_i32 m0, s23, 0x2000
	s_add_u32 s46, s6, 0x40000
	global_load_lds_dwordx4 v139, s[6:7]
	s_addc_u32 s47, s7, 0
	s_add_i32 s23, s25, s42
	s_mov_b32 m0, s23
	s_nop 0
	global_load_lds_dwordx4 v137, s[46:47]
	s_add_i32 m0, s23, 0x2000
	s_nop 0
	global_load_lds_dwordx4 v139, s[46:47]
	s_mov_b32 m0, s60
	s_nop 0
	global_load_lds_dwordx4 v131, s[4:5]
	s_mov_b32 m0, s61
	s_nop 0
	global_load_lds_dwordx4 v133, s[4:5]
	s_waitcnt vmcnt(8) lgkmcnt(0)
	s_setprio 1
	s_barrier
	v_mfma_f32_16x16x32_bf16 v[62:65], v[146:149], v[180:183], v[62:65]
	v_mfma_f32_16x16x32_bf16 v[58:61], v[156:159], v[180:183], v[58:61]
	v_mfma_f32_16x16x32_bf16 v[46:49], v[146:149], v[188:191], v[46:49]
	v_mfma_f32_16x16x32_bf16 v[42:45], v[156:159], v[188:191], v[42:45]
	v_mfma_f32_16x16x32_bf16 v[30:33], v[146:149], v[196:199], v[30:33]
	v_mfma_f32_16x16x32_bf16 v[26:29], v[156:159], v[196:199], v[26:29]
	v_mfma_f32_16x16x32_bf16 v[14:17], v[146:149], v[204:207], v[14:17]
	v_mfma_f32_16x16x32_bf16 v[10:13], v[156:159], v[204:207], v[10:13]
	v_mfma_f32_16x16x32_bf16 v[62:65], v[152:155], v[184:187], v[62:65]
	v_mfma_f32_16x16x32_bf16 v[58:61], v[160:163], v[184:187], v[58:61]
	v_mfma_f32_16x16x32_bf16 v[46:49], v[152:155], v[192:195], v[46:49]
	v_mfma_f32_16x16x32_bf16 v[42:45], v[160:163], v[192:195], v[42:45]
	v_mfma_f32_16x16x32_bf16 v[30:33], v[152:155], v[200:203], v[30:33]
	v_mfma_f32_16x16x32_bf16 v[26:29], v[160:163], v[200:203], v[26:29]
	v_mfma_f32_16x16x32_bf16 v[14:17], v[152:155], v[208:211], v[14:17]
	v_mfma_f32_16x16x32_bf16 v[10:13], v[160:163], v[208:211], v[10:13]
	s_setprio 0
	s_setprio 1
	v_mfma_f32_16x16x32_bf16 v[54:57], v[164:167], v[180:183], v[54:57]
	v_mfma_f32_16x16x32_bf16 v[50:53], v[172:175], v[180:183], v[50:53]
	v_mfma_f32_16x16x32_bf16 v[38:41], v[164:167], v[188:191], v[38:41]
	v_mfma_f32_16x16x32_bf16 v[34:37], v[172:175], v[188:191], v[34:37]
	v_mfma_f32_16x16x32_bf16 v[22:25], v[164:167], v[196:199], v[22:25]
	v_mfma_f32_16x16x32_bf16 v[18:21], v[172:175], v[196:199], v[18:21]
	v_mfma_f32_16x16x32_bf16 v[6:9], v[164:167], v[204:207], v[6:9]
	v_mfma_f32_16x16x32_bf16 v[2:5], v[172:175], v[204:207], v[2:5]
	v_mfma_f32_16x16x32_bf16 v[54:57], v[168:171], v[184:187], v[54:57]
	v_mfma_f32_16x16x32_bf16 v[50:53], v[176:179], v[184:187], v[50:53]
	v_mfma_f32_16x16x32_bf16 v[38:41], v[168:171], v[192:195], v[38:41]
	v_mfma_f32_16x16x32_bf16 v[34:37], v[176:179], v[192:195], v[34:37]
	v_mfma_f32_16x16x32_bf16 v[22:25], v[168:171], v[200:203], v[22:25]
	v_mfma_f32_16x16x32_bf16 v[18:21], v[176:179], v[200:203], v[18:21]
	v_mfma_f32_16x16x32_bf16 v[6:9], v[168:171], v[208:211], v[6:9]
	v_mfma_f32_16x16x32_bf16 v[2:5], v[176:179], v[208:211], v[2:5]
	s_setprio 0
	s_barrier
	ds_read_b128 v[146:149], v0 offset:32768
	ds_read_b128 v[152:155], v0 offset:33792
	ds_read_b128 v[156:159], v0 offset:34816
	ds_read_b128 v[160:163], v0 offset:35840
	ds_read_b128 v[164:167], v0 offset:49152
	ds_read_b128 v[168:171], v0 offset:50176
	ds_read_b128 v[172:175], v0 offset:51200
	ds_read_b128 v[176:179], v0 offset:52224
	s_add_u32 s46, s4, 0x40000
	s_mov_b32 m0, s66
	ds_read_b128 v[180:183], v150 offset:32768
	ds_read_b128 v[184:187], v150 offset:33792
	ds_read_b128 v[188:191], v150 offset:34816
	ds_read_b128 v[192:195], v150 offset:35840
	ds_read_b128 v[196:199], v150 offset:36864
	ds_read_b128 v[200:203], v150 offset:37888
	ds_read_b128 v[204:207], v150 offset:38912
	ds_read_b128 v[208:211], v150 offset:39936
	s_addc_u32 s47, s5, 0
	s_add_i32 s23, 0, 0x18000
	s_add_i32 s25, 0, 0x1c000
	s_nop 0
	global_load_lds_dwordx4 v131, s[46:47]
	s_mov_b32 m0, s67
	s_nop 0
	global_load_lds_dwordx4 v133, s[46:47]
	s_waitcnt vmcnt(8) lgkmcnt(0)
	s_setprio 1
	s_barrier
	v_mfma_f32_16x16x32_bf16 v[126:129], v[146:149], v[180:183], v[126:129]
	v_mfma_f32_16x16x32_bf16 v[122:125], v[156:159], v[180:183], v[122:125]
	v_mfma_f32_16x16x32_bf16 v[110:113], v[146:149], v[188:191], v[110:113]
	v_mfma_f32_16x16x32_bf16 v[106:109], v[156:159], v[188:191], v[106:109]
	v_mfma_f32_16x16x32_bf16 v[94:97], v[146:149], v[196:199], v[94:97]
	v_mfma_f32_16x16x32_bf16 v[90:93], v[156:159], v[196:199], v[90:93]
	v_mfma_f32_16x16x32_bf16 v[78:81], v[146:149], v[204:207], v[78:81]
	v_mfma_f32_16x16x32_bf16 v[74:77], v[156:159], v[204:207], v[74:77]
	v_mfma_f32_16x16x32_bf16 v[126:129], v[152:155], v[184:187], v[126:129]
	v_mfma_f32_16x16x32_bf16 v[122:125], v[160:163], v[184:187], v[122:125]
	v_mfma_f32_16x16x32_bf16 v[110:113], v[152:155], v[192:195], v[110:113]
	v_mfma_f32_16x16x32_bf16 v[106:109], v[160:163], v[192:195], v[106:109]
	v_mfma_f32_16x16x32_bf16 v[94:97], v[152:155], v[200:203], v[94:97]
	v_mfma_f32_16x16x32_bf16 v[90:93], v[160:163], v[200:203], v[90:93]
	v_mfma_f32_16x16x32_bf16 v[78:81], v[152:155], v[208:211], v[78:81]
	v_mfma_f32_16x16x32_bf16 v[74:77], v[160:163], v[208:211], v[74:77]
	s_setprio 0
	s_setprio 1
	v_mfma_f32_16x16x32_bf16 v[118:121], v[164:167], v[180:183], v[118:121]
	v_mfma_f32_16x16x32_bf16 v[114:117], v[172:175], v[180:183], v[114:117]
	v_mfma_f32_16x16x32_bf16 v[102:105], v[164:167], v[188:191], v[102:105]
	v_mfma_f32_16x16x32_bf16 v[98:101], v[172:175], v[188:191], v[98:101]
	v_mfma_f32_16x16x32_bf16 v[86:89], v[164:167], v[196:199], v[86:89]
	v_mfma_f32_16x16x32_bf16 v[82:85], v[172:175], v[196:199], v[82:85]
	v_mfma_f32_16x16x32_bf16 v[70:73], v[164:167], v[204:207], v[70:73]
	v_mfma_f32_16x16x32_bf16 v[66:69], v[172:175], v[204:207], v[66:69]
	v_mfma_f32_16x16x32_bf16 v[118:121], v[168:171], v[184:187], v[118:121]
	v_mfma_f32_16x16x32_bf16 v[114:117], v[176:179], v[184:187], v[114:117]
	v_mfma_f32_16x16x32_bf16 v[102:105], v[168:171], v[192:195], v[102:105]
	v_mfma_f32_16x16x32_bf16 v[98:101], v[176:179], v[192:195], v[98:101]
	v_mfma_f32_16x16x32_bf16 v[86:89], v[168:171], v[200:203], v[86:89]
	v_mfma_f32_16x16x32_bf16 v[82:85], v[176:179], v[200:203], v[82:85]
	v_mfma_f32_16x16x32_bf16 v[70:73], v[168:171], v[208:211], v[70:73]
	v_mfma_f32_16x16x32_bf16 v[66:69], v[176:179], v[208:211], v[66:69]
	s_setprio 0
	s_barrier
	ds_read_b128 v[180:183], v150 offset:49152
	ds_read_b128 v[184:187], v150 offset:50176
	ds_read_b128 v[188:191], v150 offset:51200
	ds_read_b128 v[192:195], v150 offset:52224
	ds_read_b128 v[196:199], v150 offset:53248
	ds_read_b128 v[200:203], v150 offset:54272
	ds_read_b128 v[204:207], v150 offset:55296
	ds_read_b128 v[208:211], v150 offset:56320
	s_add_i32 s23, s23, s42
	s_add_u32 s100, s6, s38
	s_addc_u32 s101, s7, s39
	s_mov_b32 m0, s23
	s_nop 0
	global_load_lds_dwordx4 v137, s[100:101]
	s_add_i32 m0, s23, 0x2000
	s_nop 0
	s_add_u32 s6, s6, 0x40080
	s_addc_u32 s7, s7, 0
	s_add_i32 s23, s25, s42
	global_load_lds_dwordx4 v139, s[100:101]
	s_mov_b32 m0, s23
	s_nop 0
	global_load_lds_dwordx4 v137, s[6:7]
	s_add_i32 m0, s23, 0x2000
	s_nop 0
	global_load_lds_dwordx4 v139, s[6:7]
	s_mov_b32 m0, s70
	s_add_u32 s100, s4, s38
	s_addc_u32 s101, s5, s39
	v_mov_b32_e32 v0, v133
	global_load_lds_dwordx4 v131, s[100:101]
	s_mov_b32 m0, s71
	s_nop 0
	global_load_lds_dwordx4 v133, s[100:101]
	s_waitcnt vmcnt(8) lgkmcnt(0)
	s_setprio 1
	s_barrier
	v_mfma_f32_16x16x32_bf16 v[62:65], v[146:149], v[180:183], v[62:65]
	v_mfma_f32_16x16x32_bf16 v[58:61], v[156:159], v[180:183], v[58:61]
	v_mfma_f32_16x16x32_bf16 v[46:49], v[146:149], v[188:191], v[46:49]
	v_mfma_f32_16x16x32_bf16 v[42:45], v[156:159], v[188:191], v[42:45]
	v_mfma_f32_16x16x32_bf16 v[30:33], v[146:149], v[196:199], v[30:33]
	v_mfma_f32_16x16x32_bf16 v[26:29], v[156:159], v[196:199], v[26:29]
	v_mfma_f32_16x16x32_bf16 v[14:17], v[146:149], v[204:207], v[14:17]
	v_mfma_f32_16x16x32_bf16 v[10:13], v[156:159], v[204:207], v[10:13]
	v_mfma_f32_16x16x32_bf16 v[62:65], v[152:155], v[184:187], v[62:65]
	v_mfma_f32_16x16x32_bf16 v[58:61], v[160:163], v[184:187], v[58:61]
	v_mfma_f32_16x16x32_bf16 v[46:49], v[152:155], v[192:195], v[46:49]
	v_mfma_f32_16x16x32_bf16 v[42:45], v[160:163], v[192:195], v[42:45]
	v_mfma_f32_16x16x32_bf16 v[30:33], v[152:155], v[200:203], v[30:33]
	v_mfma_f32_16x16x32_bf16 v[26:29], v[160:163], v[200:203], v[26:29]
	v_mfma_f32_16x16x32_bf16 v[14:17], v[152:155], v[208:211], v[14:17]
	v_mfma_f32_16x16x32_bf16 v[10:13], v[160:163], v[208:211], v[10:13]
	s_setprio 0
	s_setprio 1
	v_mfma_f32_16x16x32_bf16 v[54:57], v[164:167], v[180:183], v[54:57]
	v_mfma_f32_16x16x32_bf16 v[50:53], v[172:175], v[180:183], v[50:53]
	v_mfma_f32_16x16x32_bf16 v[38:41], v[164:167], v[188:191], v[38:41]
	v_mfma_f32_16x16x32_bf16 v[34:37], v[172:175], v[188:191], v[34:37]
	v_mfma_f32_16x16x32_bf16 v[22:25], v[164:167], v[196:199], v[22:25]
	v_mfma_f32_16x16x32_bf16 v[18:21], v[172:175], v[196:199], v[18:21]
	v_mfma_f32_16x16x32_bf16 v[6:9], v[164:167], v[204:207], v[6:9]
	v_mfma_f32_16x16x32_bf16 v[2:5], v[172:175], v[204:207], v[2:5]
	v_mfma_f32_16x16x32_bf16 v[54:57], v[168:171], v[184:187], v[54:57]
	v_mfma_f32_16x16x32_bf16 v[50:53], v[176:179], v[184:187], v[50:53]
	v_mfma_f32_16x16x32_bf16 v[38:41], v[168:171], v[192:195], v[38:41]
	v_mfma_f32_16x16x32_bf16 v[34:37], v[176:179], v[192:195], v[34:37]
	v_mfma_f32_16x16x32_bf16 v[22:25], v[168:171], v[200:203], v[22:25]
	v_mfma_f32_16x16x32_bf16 v[18:21], v[176:179], v[200:203], v[18:21]
	v_mfma_f32_16x16x32_bf16 v[6:9], v[168:171], v[208:211], v[6:9]
	v_mfma_f32_16x16x32_bf16 v[2:5], v[176:179], v[208:211], v[2:5]
	s_setprio 0
	s_barrier
	s_add_i32 s22, s22, 2
	s_add_u32 s2, s2, 0x100
	s_addc_u32 s3, s3, 0
	s_add_u32 s8, s8, 0x100
	s_addc_u32 s9, s9, 0
	s_cmp_gt_u32 s22, 13
	s_cbranch_scc0 .LBB0_1088

.LBB0_1473:
	s_add_u32 s16, s4, s14
	s_addc_u32 s17, s5, s15
	s_add_u32 s22, s16, 0x100
	s_addc_u32 s23, s17, 0
	s_and_b64 s[10:11], s[12:13], exec
	s_cselect_b32 s11, s5, s23
	s_cselect_b32 s10, s4, s22
	s_add_u32 s14, s6, s14
	s_addc_u32 s15, s7, s15
	s_add_u32 s14, s14, 0x100
	s_addc_u32 s15, s15, 0
	s_add_i32 s69, 0, 0x10000
	s_and_b64 s[12:13], s[12:13], exec
	s_cselect_b32 s13, s7, s15
	s_cselect_b32 s12, s6, s14
	s_add_i32 s15, 0, 0x14000
	s_add_u32 s46, s16, 0x80080
	s_addc_u32 s47, s17, 0
	s_add_i32 s71, s69, s41
	s_add_i32 m0, s42, 0xc000
	s_add_i32 s74, s42, 0xe000
	s_add_i32 s67, s71, 0x2000
	v_add_u32_e32 v0, s69, v136
	s_add_u32 s22, s12, 0x40000
	ds_read_b128 v[138:141], v0
	ds_read_b128 v[142:145], v0 offset:1024
	ds_read_b128 v[146:149], v0 offset:2048
	ds_read_b128 v[150:153], v0 offset:3072
	s_addc_u32 s23, s13, 0
	s_add_i32 s68, s15, s41
	ds_read_b128 v[154:157], v0 offset:16384
	ds_read_b128 v[158:161], v0 offset:17408
	ds_read_b128 v[162:165], v0 offset:18432
	ds_read_b128 v[166:169], v0 offset:19456
	s_add_i32 s66, s68, 0x2000
	s_add_i32 s65, 0, 0x18000
	s_add_i32 s64, 0, 0x1c000
	s_add_u32 s16, s10, 0x80000
	s_addc_u32 s17, s11, 0
	s_add_i32 s61, s65, s41
	s_add_i32 s60, s61, 0x2000
	s_add_u32 s14, s12, 0x40080
	s_addc_u32 s15, s13, 0
	s_add_i32 s70, s64, s41
	s_add_i32 s69, s70, 0x2000
	ds_read_b128 v[170:173], v137
	ds_read_b128 v[174:177], v137 offset:1024
	ds_read_b128 v[178:181], v137 offset:2048
	ds_read_b128 v[182:185], v137 offset:3072
	ds_read_b128 v[186:189], v137 offset:4096
	ds_read_b128 v[190:193], v137 offset:5120
	ds_read_b128 v[194:197], v137 offset:6144
	ds_read_b128 v[198:201], v137 offset:7168
	s_nop 0
	global_load_lds_dwordx4 v130, s[46:47]
	s_mov_b32 m0, s74
	s_nop 0
	global_load_lds_dwordx4 v132, s[46:47]
	s_waitcnt vmcnt(8) lgkmcnt(0)
	s_setprio 1
	s_barrier
	v_mfma_f32_16x16x32_bf16 v[126:129], v[138:141], v[170:173], v[126:129]
	v_mfma_f32_16x16x32_bf16 v[122:125], v[146:149], v[170:173], v[122:125]
	v_mfma_f32_16x16x32_bf16 v[118:121], v[138:141], v[178:181], v[118:121]
	v_mfma_f32_16x16x32_bf16 v[110:113], v[146:149], v[178:181], v[110:113]
	v_mfma_f32_16x16x32_bf16 v[102:105], v[138:141], v[186:189], v[102:105]
	v_mfma_f32_16x16x32_bf16 v[94:97], v[146:149], v[186:189], v[94:97]
	v_mfma_f32_16x16x32_bf16 v[86:89], v[138:141], v[194:197], v[86:89]
	v_mfma_f32_16x16x32_bf16 v[78:81], v[146:149], v[194:197], v[78:81]
	v_mfma_f32_16x16x32_bf16 v[126:129], v[142:145], v[174:177], v[126:129]
	v_mfma_f32_16x16x32_bf16 v[122:125], v[150:153], v[174:177], v[122:125]
	v_mfma_f32_16x16x32_bf16 v[118:121], v[142:145], v[182:185], v[118:121]
	v_mfma_f32_16x16x32_bf16 v[110:113], v[150:153], v[182:185], v[110:113]
	v_mfma_f32_16x16x32_bf16 v[102:105], v[142:145], v[190:193], v[102:105]
	v_mfma_f32_16x16x32_bf16 v[94:97], v[150:153], v[190:193], v[94:97]
	v_mfma_f32_16x16x32_bf16 v[86:89], v[142:145], v[198:201], v[86:89]
	v_mfma_f32_16x16x32_bf16 v[78:81], v[150:153], v[198:201], v[78:81]
	s_setprio 0
	s_setprio 1
	v_mfma_f32_16x16x32_bf16 v[114:117], v[154:157], v[170:173], v[114:117]
	v_mfma_f32_16x16x32_bf16 v[106:109], v[162:165], v[170:173], v[106:109]
	v_mfma_f32_16x16x32_bf16 v[98:101], v[154:157], v[178:181], v[98:101]
	v_mfma_f32_16x16x32_bf16 v[90:93], v[162:165], v[178:181], v[90:93]
	v_mfma_f32_16x16x32_bf16 v[82:85], v[154:157], v[186:189], v[82:85]
	v_mfma_f32_16x16x32_bf16 v[74:77], v[162:165], v[186:189], v[74:77]
	v_mfma_f32_16x16x32_bf16 v[70:73], v[154:157], v[194:197], v[70:73]
	v_mfma_f32_16x16x32_bf16 v[62:65], v[162:165], v[194:197], v[62:65]
	v_mfma_f32_16x16x32_bf16 v[114:117], v[158:161], v[174:177], v[114:117]
	v_mfma_f32_16x16x32_bf16 v[106:109], v[166:169], v[174:177], v[106:109]
	v_mfma_f32_16x16x32_bf16 v[98:101], v[158:161], v[182:185], v[98:101]
	v_mfma_f32_16x16x32_bf16 v[90:93], v[166:169], v[182:185], v[90:93]
	v_mfma_f32_16x16x32_bf16 v[82:85], v[158:161], v[190:193], v[82:85]
	v_mfma_f32_16x16x32_bf16 v[74:77], v[166:169], v[190:193], v[74:77]
	v_mfma_f32_16x16x32_bf16 v[70:73], v[158:161], v[198:201], v[70:73]
	v_mfma_f32_16x16x32_bf16 v[62:65], v[166:169], v[198:201], v[62:65]
	s_setprio 0
	s_barrier
	ds_read_b128 v[170:173], v137 offset:16384
	ds_read_b128 v[174:177], v137 offset:17408
	ds_read_b128 v[178:181], v137 offset:18432
	ds_read_b128 v[182:185], v137 offset:19456
	ds_read_b128 v[186:189], v137 offset:20480
	ds_read_b128 v[190:193], v137 offset:21504
	ds_read_b128 v[194:197], v137 offset:22528
	ds_read_b128 v[198:201], v137 offset:23552
	s_mov_b32 m0, s71
	s_nop 0
	global_load_lds_dwordx4 v131, s[12:13]
	s_mov_b32 m0, s67
	s_nop 0
	global_load_lds_dwordx4 v133, s[12:13]
	s_mov_b32 m0, s68
	s_nop 0
	global_load_lds_dwordx4 v131, s[22:23]
	s_mov_b32 m0, s66
	s_nop 0
	global_load_lds_dwordx4 v133, s[22:23]
	s_mov_b32 m0, s42
	s_nop 0
	global_load_lds_dwordx4 v130, s[10:11]
	s_mov_b32 m0, s43
	s_nop 0
	global_load_lds_dwordx4 v132, s[10:11]
	s_waitcnt vmcnt(8) lgkmcnt(0)
	s_setprio 1
	s_barrier
	v_mfma_f32_16x16x32_bf16 v[66:69], v[138:141], v[170:173], v[66:69]
	v_mfma_f32_16x16x32_bf16 v[58:61], v[146:149], v[170:173], v[58:61]
	v_mfma_f32_16x16x32_bf16 v[54:57], v[138:141], v[178:181], v[54:57]
	v_mfma_f32_16x16x32_bf16 v[46:49], v[146:149], v[178:181], v[46:49]
	v_mfma_f32_16x16x32_bf16 v[38:41], v[138:141], v[186:189], v[38:41]
	v_mfma_f32_16x16x32_bf16 v[30:33], v[146:149], v[186:189], v[30:33]
	v_mfma_f32_16x16x32_bf16 v[22:25], v[138:141], v[194:197], v[22:25]
	v_mfma_f32_16x16x32_bf16 v[14:17], v[146:149], v[194:197], v[14:17]
	v_mfma_f32_16x16x32_bf16 v[66:69], v[142:145], v[174:177], v[66:69]
	v_mfma_f32_16x16x32_bf16 v[58:61], v[150:153], v[174:177], v[58:61]
	v_mfma_f32_16x16x32_bf16 v[54:57], v[142:145], v[182:185], v[54:57]
	v_mfma_f32_16x16x32_bf16 v[46:49], v[150:153], v[182:185], v[46:49]
	v_mfma_f32_16x16x32_bf16 v[38:41], v[142:145], v[190:193], v[38:41]
	v_mfma_f32_16x16x32_bf16 v[30:33], v[150:153], v[190:193], v[30:33]
	v_mfma_f32_16x16x32_bf16 v[22:25], v[142:145], v[198:201], v[22:25]
	v_mfma_f32_16x16x32_bf16 v[14:17], v[150:153], v[198:201], v[14:17]
	s_setprio 0
	s_setprio 1
	v_mfma_f32_16x16x32_bf16 v[50:53], v[154:157], v[170:173], v[50:53]
	v_mfma_f32_16x16x32_bf16 v[42:45], v[162:165], v[170:173], v[42:45]
	v_mfma_f32_16x16x32_bf16 v[34:37], v[154:157], v[178:181], v[34:37]
	v_mfma_f32_16x16x32_bf16 v[26:29], v[162:165], v[178:181], v[26:29]
	v_mfma_f32_16x16x32_bf16 v[18:21], v[154:157], v[186:189], v[18:21]
	v_mfma_f32_16x16x32_bf16 v[10:13], v[162:165], v[186:189], v[10:13]
	v_mfma_f32_16x16x32_bf16 v[6:9], v[154:157], v[194:197], v[6:9]
	v_mfma_f32_16x16x32_bf16 v[2:5], v[162:165], v[194:197], v[2:5]
	v_mfma_f32_16x16x32_bf16 v[50:53], v[158:161], v[174:177], v[50:53]
	v_mfma_f32_16x16x32_bf16 v[42:45], v[166:169], v[174:177], v[42:45]
	v_mfma_f32_16x16x32_bf16 v[34:37], v[158:161], v[182:185], v[34:37]
	v_mfma_f32_16x16x32_bf16 v[26:29], v[166:169], v[182:185], v[26:29]
	v_mfma_f32_16x16x32_bf16 v[18:21], v[158:161], v[190:193], v[18:21]
	v_mfma_f32_16x16x32_bf16 v[10:13], v[166:169], v[190:193], v[10:13]
	v_mfma_f32_16x16x32_bf16 v[6:9], v[158:161], v[198:201], v[6:9]
	v_mfma_f32_16x16x32_bf16 v[2:5], v[166:169], v[198:201], v[2:5]
	s_setprio 0
	s_barrier
	ds_read_b128 v[138:141], v0 offset:32768
	ds_read_b128 v[142:145], v0 offset:33792
	ds_read_b128 v[146:149], v0 offset:34816
	ds_read_b128 v[150:153], v0 offset:35840
	ds_read_b128 v[154:157], v0 offset:49152
	ds_read_b128 v[158:161], v0 offset:50176
	ds_read_b128 v[162:165], v0 offset:51200
	ds_read_b128 v[166:169], v0 offset:52224
	s_mov_b32 m0, s50
	ds_read_b128 v[170:173], v137 offset:32768
	ds_read_b128 v[174:177], v137 offset:33792
	ds_read_b128 v[178:181], v137 offset:34816
	ds_read_b128 v[182:185], v137 offset:35840
	ds_read_b128 v[186:189], v137 offset:36864
	ds_read_b128 v[190:193], v137 offset:37888
	ds_read_b128 v[194:197], v137 offset:38912
	ds_read_b128 v[198:201], v137 offset:39936
	s_nop 0
	global_load_lds_dwordx4 v130, s[16:17]
	s_mov_b32 m0, s51
	s_nop 0
	global_load_lds_dwordx4 v132, s[16:17]
	s_waitcnt vmcnt(8) lgkmcnt(0)
	s_setprio 1
	s_barrier
	v_mfma_f32_16x16x32_bf16 v[126:129], v[138:141], v[170:173], v[126:129]
	v_mfma_f32_16x16x32_bf16 v[122:125], v[146:149], v[170:173], v[122:125]
	v_mfma_f32_16x16x32_bf16 v[118:121], v[138:141], v[178:181], v[118:121]
	v_mfma_f32_16x16x32_bf16 v[110:113], v[146:149], v[178:181], v[110:113]
	v_mfma_f32_16x16x32_bf16 v[102:105], v[138:141], v[186:189], v[102:105]
	v_mfma_f32_16x16x32_bf16 v[94:97], v[146:149], v[186:189], v[94:97]
	v_mfma_f32_16x16x32_bf16 v[86:89], v[138:141], v[194:197], v[86:89]
	v_mfma_f32_16x16x32_bf16 v[78:81], v[146:149], v[194:197], v[78:81]
	v_mfma_f32_16x16x32_bf16 v[126:129], v[142:145], v[174:177], v[126:129]
	v_mfma_f32_16x16x32_bf16 v[122:125], v[150:153], v[174:177], v[122:125]
	v_mfma_f32_16x16x32_bf16 v[118:121], v[142:145], v[182:185], v[118:121]
	v_mfma_f32_16x16x32_bf16 v[110:113], v[150:153], v[182:185], v[110:113]
	v_mfma_f32_16x16x32_bf16 v[102:105], v[142:145], v[190:193], v[102:105]
	v_mfma_f32_16x16x32_bf16 v[94:97], v[150:153], v[190:193], v[94:97]
	v_mfma_f32_16x16x32_bf16 v[86:89], v[142:145], v[198:201], v[86:89]
	v_mfma_f32_16x16x32_bf16 v[78:81], v[150:153], v[198:201], v[78:81]
	s_setprio 0
	s_setprio 1
	v_mfma_f32_16x16x32_bf16 v[114:117], v[154:157], v[170:173], v[114:117]
	v_mfma_f32_16x16x32_bf16 v[106:109], v[162:165], v[170:173], v[106:109]
	v_mfma_f32_16x16x32_bf16 v[98:101], v[154:157], v[178:181], v[98:101]
	v_mfma_f32_16x16x32_bf16 v[90:93], v[162:165], v[178:181], v[90:93]
	v_mfma_f32_16x16x32_bf16 v[82:85], v[154:157], v[186:189], v[82:85]
	v_mfma_f32_16x16x32_bf16 v[74:77], v[162:165], v[186:189], v[74:77]
	v_mfma_f32_16x16x32_bf16 v[70:73], v[154:157], v[194:197], v[70:73]
	v_mfma_f32_16x16x32_bf16 v[62:65], v[162:165], v[194:197], v[62:65]
	v_mfma_f32_16x16x32_bf16 v[114:117], v[158:161], v[174:177], v[114:117]
	v_mfma_f32_16x16x32_bf16 v[106:109], v[166:169], v[174:177], v[106:109]
	v_mfma_f32_16x16x32_bf16 v[98:101], v[158:161], v[182:185], v[98:101]
	v_mfma_f32_16x16x32_bf16 v[90:93], v[166:169], v[182:185], v[90:93]
	v_mfma_f32_16x16x32_bf16 v[82:85], v[158:161], v[190:193], v[82:85]
	v_mfma_f32_16x16x32_bf16 v[74:77], v[166:169], v[190:193], v[74:77]
	v_mfma_f32_16x16x32_bf16 v[70:73], v[158:161], v[198:201], v[70:73]
	v_mfma_f32_16x16x32_bf16 v[62:65], v[166:169], v[198:201], v[62:65]
	s_setprio 0
	s_barrier
	ds_read_b128 v[170:173], v137 offset:49152
	ds_read_b128 v[174:177], v137 offset:50176
	ds_read_b128 v[178:181], v137 offset:51200
	ds_read_b128 v[182:185], v137 offset:52224
	ds_read_b128 v[186:189], v137 offset:53248
	ds_read_b128 v[190:193], v137 offset:54272
	ds_read_b128 v[194:197], v137 offset:55296
	ds_read_b128 v[198:201], v137 offset:56320
	s_mov_b32 m0, s61
	s_add_u32 s100, s12, s38
	s_addc_u32 s101, s13, s39
	global_load_lds_dwordx4 v131, s[100:101]
	s_mov_b32 m0, s60
	s_nop 0
	global_load_lds_dwordx4 v133, s[100:101]
	s_mov_b32 m0, s70
	s_nop 0
	global_load_lds_dwordx4 v131, s[14:15]
	s_mov_b32 m0, s69
	s_nop 0
	global_load_lds_dwordx4 v133, s[14:15]
	s_mov_b32 m0, s58
	s_add_u32 s100, s10, s38
	s_addc_u32 s101, s11, s39
	v_mov_b32_e32 v0, v132
	global_load_lds_dwordx4 v130, s[100:101]
	s_mov_b32 m0, s59
	s_nop 0
	global_load_lds_dwordx4 v132, s[100:101]
	s_waitcnt vmcnt(8) lgkmcnt(0)
	s_setprio 1
	s_barrier
	v_mfma_f32_16x16x32_bf16 v[66:69], v[138:141], v[170:173], v[66:69]
	v_mfma_f32_16x16x32_bf16 v[58:61], v[146:149], v[170:173], v[58:61]
	v_mfma_f32_16x16x32_bf16 v[54:57], v[138:141], v[178:181], v[54:57]
	v_mfma_f32_16x16x32_bf16 v[46:49], v[146:149], v[178:181], v[46:49]
	v_mfma_f32_16x16x32_bf16 v[38:41], v[138:141], v[186:189], v[38:41]
	v_mfma_f32_16x16x32_bf16 v[30:33], v[146:149], v[186:189], v[30:33]
	v_mfma_f32_16x16x32_bf16 v[22:25], v[138:141], v[194:197], v[22:25]
	v_mfma_f32_16x16x32_bf16 v[14:17], v[146:149], v[194:197], v[14:17]
	v_mfma_f32_16x16x32_bf16 v[66:69], v[142:145], v[174:177], v[66:69]
	v_mfma_f32_16x16x32_bf16 v[58:61], v[150:153], v[174:177], v[58:61]
	v_mfma_f32_16x16x32_bf16 v[54:57], v[142:145], v[182:185], v[54:57]
	v_mfma_f32_16x16x32_bf16 v[46:49], v[150:153], v[182:185], v[46:49]
	v_mfma_f32_16x16x32_bf16 v[38:41], v[142:145], v[190:193], v[38:41]
	v_mfma_f32_16x16x32_bf16 v[30:33], v[150:153], v[190:193], v[30:33]
	v_mfma_f32_16x16x32_bf16 v[22:25], v[142:145], v[198:201], v[22:25]
	v_mfma_f32_16x16x32_bf16 v[14:17], v[150:153], v[198:201], v[14:17]
	s_setprio 0
	s_setprio 1
	v_mfma_f32_16x16x32_bf16 v[50:53], v[154:157], v[170:173], v[50:53]
	v_mfma_f32_16x16x32_bf16 v[42:45], v[162:165], v[170:173], v[42:45]
	v_mfma_f32_16x16x32_bf16 v[34:37], v[154:157], v[178:181], v[34:37]
	v_mfma_f32_16x16x32_bf16 v[26:29], v[162:165], v[178:181], v[26:29]
	v_mfma_f32_16x16x32_bf16 v[18:21], v[154:157], v[186:189], v[18:21]
	v_mfma_f32_16x16x32_bf16 v[10:13], v[162:165], v[186:189], v[10:13]
	v_mfma_f32_16x16x32_bf16 v[6:9], v[154:157], v[194:197], v[6:9]
	v_mfma_f32_16x16x32_bf16 v[2:5], v[162:165], v[194:197], v[2:5]
	v_mfma_f32_16x16x32_bf16 v[50:53], v[158:161], v[174:177], v[50:53]
	v_mfma_f32_16x16x32_bf16 v[42:45], v[166:169], v[174:177], v[42:45]
	v_mfma_f32_16x16x32_bf16 v[34:37], v[158:161], v[182:185], v[34:37]
	v_mfma_f32_16x16x32_bf16 v[26:29], v[166:169], v[182:185], v[26:29]
	v_mfma_f32_16x16x32_bf16 v[18:21], v[158:161], v[190:193], v[18:21]
	v_mfma_f32_16x16x32_bf16 v[10:13], v[166:169], v[190:193], v[10:13]
	v_mfma_f32_16x16x32_bf16 v[6:9], v[158:161], v[198:201], v[6:9]
	v_mfma_f32_16x16x32_bf16 v[2:5], v[166:169], v[198:201], v[2:5]
	s_setprio 0
	s_barrier
	s_andn2_b64 vcc, exec, s[8:9]
	s_mov_b64 s[12:13], -1
	s_mov_b64 s[8:9], 0
	s_mov_b64 s[14:15], 0x100
	s_cbranch_vccz .LBB0_1473
	s_cmpk_lt_u32 s24, 0x100
	s_cbranch_scc0 .LBB0_1476
	s_barrier

.LBB0_1481:
	s_add_u32 s16, s4, s14
	s_addc_u32 s17, s5, s15
	s_add_u32 s22, s16, 0x100
	s_addc_u32 s23, s17, 0
	s_and_b64 s[10:11], s[12:13], exec
	s_cselect_b32 s11, s5, s23
	s_cselect_b32 s10, s4, s22
	s_add_u32 s14, s6, s14
	s_addc_u32 s15, s7, s15
	s_add_u32 s14, s14, 0x900
	s_addc_u32 s15, s15, 0
	s_add_i32 s70, 0, 0x10000
	s_and_b64 s[12:13], s[12:13], exec
	s_cselect_b32 s13, s58, s15
	s_cselect_b32 s12, s51, s14
	s_add_i32 s15, 0, 0x14000
	s_add_u32 s46, s16, 0x40080
	s_addc_u32 s47, s17, 0
	s_add_i32 s74, s70, s40
	s_add_i32 m0, s41, 0xc000
	s_add_i32 s75, s41, 0xe000
	s_add_i32 s68, s74, 0x2000
	v_add_u32_e32 v0, s70, v136
	s_add_u32 s22, s12, 0x80000
	ds_read_b128 v[138:141], v0
	ds_read_b128 v[142:145], v0 offset:1024
	ds_read_b128 v[146:149], v0 offset:2048
	ds_read_b128 v[150:153], v0 offset:3072
	s_addc_u32 s23, s13, 0
	s_add_i32 s69, s15, s40
	ds_read_b128 v[154:157], v0 offset:16384
	ds_read_b128 v[158:161], v0 offset:17408
	ds_read_b128 v[162:165], v0 offset:18432
	ds_read_b128 v[166:169], v0 offset:19456
	s_add_i32 s67, s69, 0x2000
	s_add_i32 s66, 0, 0x18000
	s_add_i32 s65, 0, 0x1c000
	s_add_u32 s16, s10, 0x40000
	s_addc_u32 s17, s11, 0
	s_add_i32 s64, s66, s40
	s_add_i32 s61, s64, 0x2000
	s_add_u32 s14, s12, 0x80080
	s_addc_u32 s15, s13, 0
	s_add_i32 s71, s65, s40
	s_add_i32 s70, s71, 0x2000
	ds_read_b128 v[170:173], v137
	ds_read_b128 v[174:177], v137 offset:1024
	ds_read_b128 v[178:181], v137 offset:2048
	ds_read_b128 v[182:185], v137 offset:3072
	ds_read_b128 v[186:189], v137 offset:4096
	ds_read_b128 v[190:193], v137 offset:5120
	ds_read_b128 v[194:197], v137 offset:6144
	ds_read_b128 v[198:201], v137 offset:7168
	s_nop 0
	global_load_lds_dwordx4 v130, s[46:47]
	s_mov_b32 m0, s75
	s_nop 0
	global_load_lds_dwordx4 v132, s[46:47]
	s_waitcnt vmcnt(8) lgkmcnt(0)
	s_setprio 1
	s_barrier
	v_mfma_f32_16x16x32_bf16 v[126:129], v[138:141], v[170:173], v[126:129]
	v_mfma_f32_16x16x32_bf16 v[122:125], v[146:149], v[170:173], v[122:125]
	v_mfma_f32_16x16x32_bf16 v[118:121], v[138:141], v[178:181], v[118:121]
	v_mfma_f32_16x16x32_bf16 v[110:113], v[146:149], v[178:181], v[110:113]
	v_mfma_f32_16x16x32_bf16 v[102:105], v[138:141], v[186:189], v[102:105]
	v_mfma_f32_16x16x32_bf16 v[94:97], v[146:149], v[186:189], v[94:97]
	v_mfma_f32_16x16x32_bf16 v[86:89], v[138:141], v[194:197], v[86:89]
	v_mfma_f32_16x16x32_bf16 v[78:81], v[146:149], v[194:197], v[78:81]
	v_mfma_f32_16x16x32_bf16 v[126:129], v[142:145], v[174:177], v[126:129]
	v_mfma_f32_16x16x32_bf16 v[122:125], v[150:153], v[174:177], v[122:125]
	v_mfma_f32_16x16x32_bf16 v[118:121], v[142:145], v[182:185], v[118:121]
	v_mfma_f32_16x16x32_bf16 v[110:113], v[150:153], v[182:185], v[110:113]
	v_mfma_f32_16x16x32_bf16 v[102:105], v[142:145], v[190:193], v[102:105]
	v_mfma_f32_16x16x32_bf16 v[94:97], v[150:153], v[190:193], v[94:97]
	v_mfma_f32_16x16x32_bf16 v[86:89], v[142:145], v[198:201], v[86:89]
	v_mfma_f32_16x16x32_bf16 v[78:81], v[150:153], v[198:201], v[78:81]
	s_setprio 0
	s_setprio 1
	v_mfma_f32_16x16x32_bf16 v[114:117], v[154:157], v[170:173], v[114:117]
	v_mfma_f32_16x16x32_bf16 v[106:109], v[162:165], v[170:173], v[106:109]
	v_mfma_f32_16x16x32_bf16 v[98:101], v[154:157], v[178:181], v[98:101]
	v_mfma_f32_16x16x32_bf16 v[90:93], v[162:165], v[178:181], v[90:93]
	v_mfma_f32_16x16x32_bf16 v[82:85], v[154:157], v[186:189], v[82:85]
	v_mfma_f32_16x16x32_bf16 v[74:77], v[162:165], v[186:189], v[74:77]
	v_mfma_f32_16x16x32_bf16 v[70:73], v[154:157], v[194:197], v[70:73]
	v_mfma_f32_16x16x32_bf16 v[62:65], v[162:165], v[194:197], v[62:65]
	v_mfma_f32_16x16x32_bf16 v[114:117], v[158:161], v[174:177], v[114:117]
	v_mfma_f32_16x16x32_bf16 v[106:109], v[166:169], v[174:177], v[106:109]
	v_mfma_f32_16x16x32_bf16 v[98:101], v[158:161], v[182:185], v[98:101]
	v_mfma_f32_16x16x32_bf16 v[90:93], v[166:169], v[182:185], v[90:93]
	v_mfma_f32_16x16x32_bf16 v[82:85], v[158:161], v[190:193], v[82:85]
	v_mfma_f32_16x16x32_bf16 v[74:77], v[166:169], v[190:193], v[74:77]
	v_mfma_f32_16x16x32_bf16 v[70:73], v[158:161], v[198:201], v[70:73]
	v_mfma_f32_16x16x32_bf16 v[62:65], v[166:169], v[198:201], v[62:65]
	s_setprio 0
	s_barrier
	ds_read_b128 v[170:173], v137 offset:16384
	ds_read_b128 v[174:177], v137 offset:17408
	ds_read_b128 v[178:181], v137 offset:18432
	ds_read_b128 v[182:185], v137 offset:19456
	ds_read_b128 v[186:189], v137 offset:20480
	ds_read_b128 v[190:193], v137 offset:21504
	ds_read_b128 v[194:197], v137 offset:22528
	ds_read_b128 v[198:201], v137 offset:23552
	s_mov_b32 m0, s74
	s_nop 0
	global_load_lds_dwordx4 v131, s[12:13]
	s_mov_b32 m0, s68
	s_nop 0
	global_load_lds_dwordx4 v133, s[12:13]
	s_mov_b32 m0, s69
	s_nop 0
	global_load_lds_dwordx4 v131, s[22:23]
	s_mov_b32 m0, s67
	s_nop 0
	global_load_lds_dwordx4 v133, s[22:23]
	s_mov_b32 m0, s41
	s_nop 0
	global_load_lds_dwordx4 v130, s[10:11]
	s_mov_b32 m0, s42
	s_nop 0
	global_load_lds_dwordx4 v132, s[10:11]
	s_waitcnt vmcnt(8) lgkmcnt(0)
	s_setprio 1
	s_barrier
	v_mfma_f32_16x16x32_bf16 v[66:69], v[138:141], v[170:173], v[66:69]
	v_mfma_f32_16x16x32_bf16 v[58:61], v[146:149], v[170:173], v[58:61]
	v_mfma_f32_16x16x32_bf16 v[54:57], v[138:141], v[178:181], v[54:57]
	v_mfma_f32_16x16x32_bf16 v[46:49], v[146:149], v[178:181], v[46:49]
	v_mfma_f32_16x16x32_bf16 v[38:41], v[138:141], v[186:189], v[38:41]
	v_mfma_f32_16x16x32_bf16 v[30:33], v[146:149], v[186:189], v[30:33]
	v_mfma_f32_16x16x32_bf16 v[22:25], v[138:141], v[194:197], v[22:25]
	v_mfma_f32_16x16x32_bf16 v[14:17], v[146:149], v[194:197], v[14:17]
	v_mfma_f32_16x16x32_bf16 v[66:69], v[142:145], v[174:177], v[66:69]
	v_mfma_f32_16x16x32_bf16 v[58:61], v[150:153], v[174:177], v[58:61]
	v_mfma_f32_16x16x32_bf16 v[54:57], v[142:145], v[182:185], v[54:57]
	v_mfma_f32_16x16x32_bf16 v[46:49], v[150:153], v[182:185], v[46:49]
	v_mfma_f32_16x16x32_bf16 v[38:41], v[142:145], v[190:193], v[38:41]
	v_mfma_f32_16x16x32_bf16 v[30:33], v[150:153], v[190:193], v[30:33]
	v_mfma_f32_16x16x32_bf16 v[22:25], v[142:145], v[198:201], v[22:25]
	v_mfma_f32_16x16x32_bf16 v[14:17], v[150:153], v[198:201], v[14:17]
	s_setprio 0
	s_setprio 1
	v_mfma_f32_16x16x32_bf16 v[50:53], v[154:157], v[170:173], v[50:53]
	v_mfma_f32_16x16x32_bf16 v[42:45], v[162:165], v[170:173], v[42:45]
	v_mfma_f32_16x16x32_bf16 v[34:37], v[154:157], v[178:181], v[34:37]
	v_mfma_f32_16x16x32_bf16 v[26:29], v[162:165], v[178:181], v[26:29]
	v_mfma_f32_16x16x32_bf16 v[18:21], v[154:157], v[186:189], v[18:21]
	v_mfma_f32_16x16x32_bf16 v[10:13], v[162:165], v[186:189], v[10:13]
	v_mfma_f32_16x16x32_bf16 v[6:9], v[154:157], v[194:197], v[6:9]
	v_mfma_f32_16x16x32_bf16 v[2:5], v[162:165], v[194:197], v[2:5]
	v_mfma_f32_16x16x32_bf16 v[50:53], v[158:161], v[174:177], v[50:53]
	v_mfma_f32_16x16x32_bf16 v[42:45], v[166:169], v[174:177], v[42:45]
	v_mfma_f32_16x16x32_bf16 v[34:37], v[158:161], v[182:185], v[34:37]
	v_mfma_f32_16x16x32_bf16 v[26:29], v[166:169], v[182:185], v[26:29]
	v_mfma_f32_16x16x32_bf16 v[18:21], v[158:161], v[190:193], v[18:21]
	v_mfma_f32_16x16x32_bf16 v[10:13], v[166:169], v[190:193], v[10:13]
	v_mfma_f32_16x16x32_bf16 v[6:9], v[158:161], v[198:201], v[6:9]
	v_mfma_f32_16x16x32_bf16 v[2:5], v[166:169], v[198:201], v[2:5]
	s_setprio 0
	s_barrier
	ds_read_b128 v[138:141], v0 offset:32768
	ds_read_b128 v[142:145], v0 offset:33792
	ds_read_b128 v[146:149], v0 offset:34816
	ds_read_b128 v[150:153], v0 offset:35840
	ds_read_b128 v[154:157], v0 offset:49152
	ds_read_b128 v[158:161], v0 offset:50176
	ds_read_b128 v[162:165], v0 offset:51200
	ds_read_b128 v[166:169], v0 offset:52224
	s_mov_b32 m0, s43
	ds_read_b128 v[170:173], v137 offset:32768
	ds_read_b128 v[174:177], v137 offset:33792
	ds_read_b128 v[178:181], v137 offset:34816
	ds_read_b128 v[182:185], v137 offset:35840
	ds_read_b128 v[186:189], v137 offset:36864
	ds_read_b128 v[190:193], v137 offset:37888
	ds_read_b128 v[194:197], v137 offset:38912
	ds_read_b128 v[198:201], v137 offset:39936
	s_nop 0
	global_load_lds_dwordx4 v130, s[16:17]
	s_mov_b32 m0, s50
	s_nop 0
	global_load_lds_dwordx4 v132, s[16:17]
	s_waitcnt vmcnt(8) lgkmcnt(0)
	s_setprio 1
	s_barrier
	v_mfma_f32_16x16x32_bf16 v[126:129], v[138:141], v[170:173], v[126:129]
	v_mfma_f32_16x16x32_bf16 v[122:125], v[146:149], v[170:173], v[122:125]
	v_mfma_f32_16x16x32_bf16 v[118:121], v[138:141], v[178:181], v[118:121]
	v_mfma_f32_16x16x32_bf16 v[110:113], v[146:149], v[178:181], v[110:113]
	v_mfma_f32_16x16x32_bf16 v[102:105], v[138:141], v[186:189], v[102:105]
	v_mfma_f32_16x16x32_bf16 v[94:97], v[146:149], v[186:189], v[94:97]
	v_mfma_f32_16x16x32_bf16 v[86:89], v[138:141], v[194:197], v[86:89]
	v_mfma_f32_16x16x32_bf16 v[78:81], v[146:149], v[194:197], v[78:81]
	v_mfma_f32_16x16x32_bf16 v[126:129], v[142:145], v[174:177], v[126:129]
	v_mfma_f32_16x16x32_bf16 v[122:125], v[150:153], v[174:177], v[122:125]
	v_mfma_f32_16x16x32_bf16 v[118:121], v[142:145], v[182:185], v[118:121]
	v_mfma_f32_16x16x32_bf16 v[110:113], v[150:153], v[182:185], v[110:113]
	v_mfma_f32_16x16x32_bf16 v[102:105], v[142:145], v[190:193], v[102:105]
	v_mfma_f32_16x16x32_bf16 v[94:97], v[150:153], v[190:193], v[94:97]
	v_mfma_f32_16x16x32_bf16 v[86:89], v[142:145], v[198:201], v[86:89]
	v_mfma_f32_16x16x32_bf16 v[78:81], v[150:153], v[198:201], v[78:81]
	s_setprio 0
	s_setprio 1
	v_mfma_f32_16x16x32_bf16 v[114:117], v[154:157], v[170:173], v[114:117]
	v_mfma_f32_16x16x32_bf16 v[106:109], v[162:165], v[170:173], v[106:109]
	v_mfma_f32_16x16x32_bf16 v[98:101], v[154:157], v[178:181], v[98:101]
	v_mfma_f32_16x16x32_bf16 v[90:93], v[162:165], v[178:181], v[90:93]
	v_mfma_f32_16x16x32_bf16 v[82:85], v[154:157], v[186:189], v[82:85]
	v_mfma_f32_16x16x32_bf16 v[74:77], v[162:165], v[186:189], v[74:77]
	v_mfma_f32_16x16x32_bf16 v[70:73], v[154:157], v[194:197], v[70:73]
	v_mfma_f32_16x16x32_bf16 v[62:65], v[162:165], v[194:197], v[62:65]
	v_mfma_f32_16x16x32_bf16 v[114:117], v[158:161], v[174:177], v[114:117]
	v_mfma_f32_16x16x32_bf16 v[106:109], v[166:169], v[174:177], v[106:109]
	v_mfma_f32_16x16x32_bf16 v[98:101], v[158:161], v[182:185], v[98:101]
	v_mfma_f32_16x16x32_bf16 v[90:93], v[166:169], v[182:185], v[90:93]
	v_mfma_f32_16x16x32_bf16 v[82:85], v[158:161], v[190:193], v[82:85]
	v_mfma_f32_16x16x32_bf16 v[74:77], v[166:169], v[190:193], v[74:77]
	v_mfma_f32_16x16x32_bf16 v[70:73], v[158:161], v[198:201], v[70:73]
	v_mfma_f32_16x16x32_bf16 v[62:65], v[166:169], v[198:201], v[62:65]
	s_setprio 0
	s_barrier
	ds_read_b128 v[170:173], v137 offset:49152
	ds_read_b128 v[174:177], v137 offset:50176
	ds_read_b128 v[178:181], v137 offset:51200
	ds_read_b128 v[182:185], v137 offset:52224
	ds_read_b128 v[186:189], v137 offset:53248
	ds_read_b128 v[190:193], v137 offset:54272
	ds_read_b128 v[194:197], v137 offset:55296
	ds_read_b128 v[198:201], v137 offset:56320
	s_mov_b32 m0, s64
	s_add_u32 s100, s12, s38
	s_addc_u32 s101, s13, s39
	global_load_lds_dwordx4 v131, s[100:101]
	s_mov_b32 m0, s61
	s_nop 0
	global_load_lds_dwordx4 v133, s[100:101]
	s_mov_b32 m0, s71
	s_nop 0
	global_load_lds_dwordx4 v131, s[14:15]
	s_mov_b32 m0, s70
	s_nop 0
	global_load_lds_dwordx4 v133, s[14:15]
	s_mov_b32 m0, s59
	s_add_u32 s100, s10, s38
	s_addc_u32 s101, s11, s39
	v_mov_b32_e32 v0, v132
	global_load_lds_dwordx4 v130, s[100:101]
	s_mov_b32 m0, s60
	s_nop 0
	global_load_lds_dwordx4 v132, s[100:101]
	s_waitcnt vmcnt(8) lgkmcnt(0)
	s_setprio 1
	s_barrier
	v_mfma_f32_16x16x32_bf16 v[66:69], v[138:141], v[170:173], v[66:69]
	v_mfma_f32_16x16x32_bf16 v[58:61], v[146:149], v[170:173], v[58:61]
	v_mfma_f32_16x16x32_bf16 v[54:57], v[138:141], v[178:181], v[54:57]
	v_mfma_f32_16x16x32_bf16 v[46:49], v[146:149], v[178:181], v[46:49]
	v_mfma_f32_16x16x32_bf16 v[38:41], v[138:141], v[186:189], v[38:41]
	v_mfma_f32_16x16x32_bf16 v[30:33], v[146:149], v[186:189], v[30:33]
	v_mfma_f32_16x16x32_bf16 v[22:25], v[138:141], v[194:197], v[22:25]
	v_mfma_f32_16x16x32_bf16 v[14:17], v[146:149], v[194:197], v[14:17]
	v_mfma_f32_16x16x32_bf16 v[66:69], v[142:145], v[174:177], v[66:69]
	v_mfma_f32_16x16x32_bf16 v[58:61], v[150:153], v[174:177], v[58:61]
	v_mfma_f32_16x16x32_bf16 v[54:57], v[142:145], v[182:185], v[54:57]
	v_mfma_f32_16x16x32_bf16 v[46:49], v[150:153], v[182:185], v[46:49]
	v_mfma_f32_16x16x32_bf16 v[38:41], v[142:145], v[190:193], v[38:41]
	v_mfma_f32_16x16x32_bf16 v[30:33], v[150:153], v[190:193], v[30:33]
	v_mfma_f32_16x16x32_bf16 v[22:25], v[142:145], v[198:201], v[22:25]
	v_mfma_f32_16x16x32_bf16 v[14:17], v[150:153], v[198:201], v[14:17]
	s_setprio 0
	s_setprio 1
	v_mfma_f32_16x16x32_bf16 v[50:53], v[154:157], v[170:173], v[50:53]
	v_mfma_f32_16x16x32_bf16 v[42:45], v[162:165], v[170:173], v[42:45]
	v_mfma_f32_16x16x32_bf16 v[34:37], v[154:157], v[178:181], v[34:37]
	v_mfma_f32_16x16x32_bf16 v[26:29], v[162:165], v[178:181], v[26:29]
	v_mfma_f32_16x16x32_bf16 v[18:21], v[154:157], v[186:189], v[18:21]
	v_mfma_f32_16x16x32_bf16 v[10:13], v[162:165], v[186:189], v[10:13]
	v_mfma_f32_16x16x32_bf16 v[6:9], v[154:157], v[194:197], v[6:9]
	v_mfma_f32_16x16x32_bf16 v[2:5], v[162:165], v[194:197], v[2:5]
	v_mfma_f32_16x16x32_bf16 v[50:53], v[158:161], v[174:177], v[50:53]
	v_mfma_f32_16x16x32_bf16 v[42:45], v[166:169], v[174:177], v[42:45]
	v_mfma_f32_16x16x32_bf16 v[34:37], v[158:161], v[182:185], v[34:37]
	v_mfma_f32_16x16x32_bf16 v[26:29], v[166:169], v[182:185], v[26:29]
	v_mfma_f32_16x16x32_bf16 v[18:21], v[158:161], v[190:193], v[18:21]
	v_mfma_f32_16x16x32_bf16 v[10:13], v[166:169], v[190:193], v[10:13]
	v_mfma_f32_16x16x32_bf16 v[6:9], v[158:161], v[198:201], v[6:9]
	v_mfma_f32_16x16x32_bf16 v[2:5], v[166:169], v[198:201], v[2:5]
	s_setprio 0
	s_barrier
	s_andn2_b64 vcc, exec, s[8:9]
	s_mov_b64 s[12:13], -1
	s_mov_b64 s[8:9], 0
	s_mov_b64 s[14:15], 0x100
	s_cbranch_vccz .LBB0_1481
	s_cmpk_lt_u32 s24, 0x100
	s_cbranch_scc0 .LBB0_1484
	s_barrier

.LBB0_1570:
	s_add_i32 s50, 0, 0x10000
	v_add_u32_e32 v0, s50, v169
	ds_read_b128 v[172:175], v0
	ds_read_b128 v[176:179], v0 offset:1024
	ds_read_b128 v[180:183], v0 offset:2048
	ds_read_b128 v[184:187], v0 offset:3072
	ds_read_b128 v[188:191], v0 offset:16384
	ds_read_b128 v[192:195], v0 offset:17408
	ds_read_b128 v[196:199], v0 offset:18432
	ds_read_b128 v[200:203], v0 offset:19456
	ds_read_b128 v[204:207], v170
	ds_read_b128 v[208:211], v170 offset:1024
	ds_read_b128 v[212:215], v170 offset:2048
	ds_read_b128 v[216:219], v170 offset:3072
	ds_read_b128 v[220:223], v170 offset:4096
	ds_read_b128 v[224:227], v170 offset:5120
	ds_read_b128 v[232:235], v170 offset:6144
	ds_read_b128 v[242:245], v170 offset:7168
	s_add_u32 s48, s41, s6
	s_addc_u32 s49, s42, s7
	s_add_u32 s8, s48, 0x9800100
	s_addc_u32 s9, s49, 0
	s_add_u32 s10, s43, s6
	s_addc_u32 s11, s46, s7
	s_cmpk_eq_i32 s6, 0x700
	s_cselect_b32 s9, s3, s9
	s_cselect_b32 s8, s2, s8
	s_cselect_b32 s11, s26, s11
	s_cselect_b32 s10, s25, s10
	s_add_i32 s51, 0, 0x14000
	s_mov_b64 s[58:59], 0x9840080
	s_add_u32 s100, s48, s58
	s_addc_u32 s101, s49, s59
	s_add_i32 m0, s17, 0xc000
	s_nop 0
	global_load_lds_dwordx4 v164, s[100:101]
	s_add_i32 m0, s17, 0xe000
	s_nop 0
	global_load_lds_dwordx4 v166, s[100:101]
	s_waitcnt vmcnt(8) lgkmcnt(0)
	s_setprio 1
	s_barrier
	v_mfma_f32_16x16x32_bf16 v[160:163], v[172:175], v[204:207], v[160:163]
	v_mfma_f32_16x16x32_bf16 v[156:159], v[180:183], v[204:207], v[156:159]
	v_mfma_f32_16x16x32_bf16 v[112:115], v[172:175], v[212:215], v[112:115]
	v_mfma_f32_16x16x32_bf16 v[108:111], v[180:183], v[212:215], v[108:111]
	v_mfma_f32_16x16x32_bf16 v[96:99], v[172:175], v[220:223], v[96:99]
	v_mfma_f32_16x16x32_bf16 v[92:95], v[180:183], v[220:223], v[92:95]
	v_mfma_f32_16x16x32_bf16 v[80:83], v[172:175], v[232:235], v[80:83]
	v_mfma_f32_16x16x32_bf16 v[76:79], v[180:183], v[232:235], v[76:79]
	v_mfma_f32_16x16x32_bf16 v[160:163], v[176:179], v[208:211], v[160:163]
	v_mfma_f32_16x16x32_bf16 v[156:159], v[184:187], v[208:211], v[156:159]
	v_mfma_f32_16x16x32_bf16 v[112:115], v[176:179], v[216:219], v[112:115]
	v_mfma_f32_16x16x32_bf16 v[108:111], v[184:187], v[216:219], v[108:111]
	v_mfma_f32_16x16x32_bf16 v[96:99], v[176:179], v[224:227], v[96:99]
	v_mfma_f32_16x16x32_bf16 v[92:95], v[184:187], v[224:227], v[92:95]
	v_mfma_f32_16x16x32_bf16 v[80:83], v[176:179], v[242:245], v[80:83]
	v_mfma_f32_16x16x32_bf16 v[76:79], v[184:187], v[242:245], v[76:79]
	s_setprio 0
	s_setprio 1
	v_mfma_f32_16x16x32_bf16 v[128:131], v[188:191], v[204:207], v[128:131]
	v_mfma_f32_16x16x32_bf16 v[120:123], v[196:199], v[204:207], v[120:123]
	v_mfma_f32_16x16x32_bf16 v[104:107], v[188:191], v[212:215], v[104:107]
	v_mfma_f32_16x16x32_bf16 v[100:103], v[196:199], v[212:215], v[100:103]
	v_mfma_f32_16x16x32_bf16 v[88:91], v[188:191], v[220:223], v[88:91]
	v_mfma_f32_16x16x32_bf16 v[84:87], v[196:199], v[220:223], v[84:87]
	v_mfma_f32_16x16x32_bf16 v[72:75], v[188:191], v[232:235], v[72:75]
	v_mfma_f32_16x16x32_bf16 v[68:71], v[196:199], v[232:235], v[68:71]
	v_mfma_f32_16x16x32_bf16 v[128:131], v[192:195], v[208:211], v[128:131]
	v_mfma_f32_16x16x32_bf16 v[120:123], v[200:203], v[208:211], v[120:123]
	v_mfma_f32_16x16x32_bf16 v[104:107], v[192:195], v[216:219], v[104:107]
	v_mfma_f32_16x16x32_bf16 v[100:103], v[200:203], v[216:219], v[100:103]
	v_mfma_f32_16x16x32_bf16 v[88:91], v[192:195], v[224:227], v[88:91]
	v_mfma_f32_16x16x32_bf16 v[84:87], v[200:203], v[224:227], v[84:87]
	v_mfma_f32_16x16x32_bf16 v[72:75], v[192:195], v[242:245], v[72:75]
	v_mfma_f32_16x16x32_bf16 v[68:71], v[200:203], v[242:245], v[68:71]
	s_setprio 0
	s_barrier
	ds_read_b128 v[204:207], v170 offset:16384
	ds_read_b128 v[208:211], v170 offset:17408
	ds_read_b128 v[212:215], v170 offset:18432
	ds_read_b128 v[216:219], v170 offset:19456
	ds_read_b128 v[220:223], v170 offset:20480
	ds_read_b128 v[224:227], v170 offset:21504
	ds_read_b128 v[232:235], v170 offset:22528
	ds_read_b128 v[242:245], v170 offset:23552
	s_add_i32 s48, s50, s16
	s_mov_b32 m0, s48
	s_nop 0
	global_load_lds_dwordx4 v167, s[10:11]
	s_add_i32 m0, s48, 0x2000
	s_add_u32 s48, s10, 0x40000
	global_load_lds_dwordx4 v168, s[10:11]
	s_addc_u32 s49, s11, 0
	s_add_i32 s50, s51, s16
	s_mov_b32 m0, s50
	s_nop 0
	global_load_lds_dwordx4 v167, s[48:49]
	s_add_i32 m0, s50, 0x2000
	s_nop 0
	global_load_lds_dwordx4 v168, s[48:49]
	s_mov_b32 m0, s17
	s_nop 0
	global_load_lds_dwordx4 v164, s[8:9]
	s_mov_b32 m0, s22
	s_nop 0
	global_load_lds_dwordx4 v166, s[8:9]
	s_waitcnt vmcnt(8) lgkmcnt(0)
	s_setprio 1
	s_barrier
	v_mfma_f32_16x16x32_bf16 v[64:67], v[172:175], v[204:207], v[64:67]
	v_mfma_f32_16x16x32_bf16 v[60:63], v[180:183], v[204:207], v[60:63]
	v_mfma_f32_16x16x32_bf16 v[48:51], v[172:175], v[212:215], v[48:51]
	v_mfma_f32_16x16x32_bf16 v[44:47], v[180:183], v[212:215], v[44:47]
	v_mfma_f32_16x16x32_bf16 v[32:35], v[172:175], v[220:223], v[32:35]
	v_mfma_f32_16x16x32_bf16 v[28:31], v[180:183], v[220:223], v[28:31]
	v_mfma_f32_16x16x32_bf16 v[16:19], v[172:175], v[232:235], v[16:19]
	v_mfma_f32_16x16x32_bf16 v[12:15], v[180:183], v[232:235], v[12:15]
	v_mfma_f32_16x16x32_bf16 v[64:67], v[176:179], v[208:211], v[64:67]
	v_mfma_f32_16x16x32_bf16 v[60:63], v[184:187], v[208:211], v[60:63]
	v_mfma_f32_16x16x32_bf16 v[48:51], v[176:179], v[216:219], v[48:51]
	v_mfma_f32_16x16x32_bf16 v[44:47], v[184:187], v[216:219], v[44:47]
	v_mfma_f32_16x16x32_bf16 v[32:35], v[176:179], v[224:227], v[32:35]
	v_mfma_f32_16x16x32_bf16 v[28:31], v[184:187], v[224:227], v[28:31]
	v_mfma_f32_16x16x32_bf16 v[16:19], v[176:179], v[242:245], v[16:19]
	v_mfma_f32_16x16x32_bf16 v[12:15], v[184:187], v[242:245], v[12:15]
	s_setprio 0
	s_setprio 1
	v_mfma_f32_16x16x32_bf16 v[56:59], v[188:191], v[204:207], v[56:59]
	v_mfma_f32_16x16x32_bf16 v[52:55], v[196:199], v[204:207], v[52:55]
	v_mfma_f32_16x16x32_bf16 v[40:43], v[188:191], v[212:215], v[40:43]
	v_mfma_f32_16x16x32_bf16 v[36:39], v[196:199], v[212:215], v[36:39]
	v_mfma_f32_16x16x32_bf16 v[24:27], v[188:191], v[220:223], v[24:27]
	v_mfma_f32_16x16x32_bf16 v[20:23], v[196:199], v[220:223], v[20:23]
	v_mfma_f32_16x16x32_bf16 v[8:11], v[188:191], v[232:235], v[8:11]
	v_mfma_f32_16x16x32_bf16 v[2:5], v[196:199], v[232:235], v[4:7]
	v_mfma_f32_16x16x32_bf16 v[56:59], v[192:195], v[208:211], v[56:59]
	v_mfma_f32_16x16x32_bf16 v[52:55], v[200:203], v[208:211], v[52:55]
	v_mfma_f32_16x16x32_bf16 v[40:43], v[192:195], v[216:219], v[40:43]
	v_mfma_f32_16x16x32_bf16 v[36:39], v[200:203], v[216:219], v[36:39]
	v_mfma_f32_16x16x32_bf16 v[24:27], v[192:195], v[224:227], v[24:27]
	v_mfma_f32_16x16x32_bf16 v[20:23], v[200:203], v[224:227], v[20:23]
	v_mfma_f32_16x16x32_bf16 v[8:11], v[192:195], v[242:245], v[8:11]
	v_mfma_f32_16x16x32_bf16 v[2:5], v[200:203], v[242:245], v[2:5]
	s_setprio 0
	s_barrier
	ds_read_b128 v[172:175], v0 offset:32768
	ds_read_b128 v[176:179], v0 offset:33792
	ds_read_b128 v[180:183], v0 offset:34816
	ds_read_b128 v[184:187], v0 offset:35840
	ds_read_b128 v[188:191], v0 offset:49152
	ds_read_b128 v[192:195], v0 offset:50176
	ds_read_b128 v[196:199], v0 offset:51200
	ds_read_b128 v[200:203], v0 offset:52224
	s_add_u32 s48, s8, 0x40000
	s_mov_b32 m0, s23
	ds_read_b128 v[204:207], v170 offset:32768
	ds_read_b128 v[208:211], v170 offset:33792
	ds_read_b128 v[212:215], v170 offset:34816
	ds_read_b128 v[216:219], v170 offset:35840
	ds_read_b128 v[220:223], v170 offset:36864
	ds_read_b128 v[224:227], v170 offset:37888
	ds_read_b128 v[232:235], v170 offset:38912
	ds_read_b128 v[242:245], v170 offset:39936
	s_addc_u32 s49, s9, 0
	s_add_i32 s50, 0, 0x18000
	s_add_i32 s51, 0, 0x1c000
	s_nop 0
	global_load_lds_dwordx4 v164, s[48:49]
	s_mov_b32 m0, s24
	s_nop 0
	global_load_lds_dwordx4 v166, s[48:49]
	s_waitcnt vmcnt(8) lgkmcnt(0)
	s_setprio 1
	s_barrier
	v_mfma_f32_16x16x32_bf16 v[160:163], v[172:175], v[204:207], v[160:163]
	v_mfma_f32_16x16x32_bf16 v[156:159], v[180:183], v[204:207], v[156:159]
	v_mfma_f32_16x16x32_bf16 v[112:115], v[172:175], v[212:215], v[112:115]
	v_mfma_f32_16x16x32_bf16 v[108:111], v[180:183], v[212:215], v[108:111]
	v_mfma_f32_16x16x32_bf16 v[96:99], v[172:175], v[220:223], v[96:99]
	v_mfma_f32_16x16x32_bf16 v[92:95], v[180:183], v[220:223], v[92:95]
	v_mfma_f32_16x16x32_bf16 v[80:83], v[172:175], v[232:235], v[80:83]
	v_mfma_f32_16x16x32_bf16 v[76:79], v[180:183], v[232:235], v[76:79]
	v_mfma_f32_16x16x32_bf16 v[160:163], v[176:179], v[208:211], v[160:163]
	v_mfma_f32_16x16x32_bf16 v[156:159], v[184:187], v[208:211], v[156:159]
	v_mfma_f32_16x16x32_bf16 v[112:115], v[176:179], v[216:219], v[112:115]
	v_mfma_f32_16x16x32_bf16 v[108:111], v[184:187], v[216:219], v[108:111]
	v_mfma_f32_16x16x32_bf16 v[96:99], v[176:179], v[224:227], v[96:99]
	v_mfma_f32_16x16x32_bf16 v[92:95], v[184:187], v[224:227], v[92:95]
	v_mfma_f32_16x16x32_bf16 v[80:83], v[176:179], v[242:245], v[80:83]
	v_mfma_f32_16x16x32_bf16 v[76:79], v[184:187], v[242:245], v[76:79]
	s_setprio 0
	s_setprio 1
	v_mfma_f32_16x16x32_bf16 v[128:131], v[188:191], v[204:207], v[128:131]
	v_mfma_f32_16x16x32_bf16 v[120:123], v[196:199], v[204:207], v[120:123]
	v_mfma_f32_16x16x32_bf16 v[104:107], v[188:191], v[212:215], v[104:107]
	v_mfma_f32_16x16x32_bf16 v[100:103], v[196:199], v[212:215], v[100:103]
	v_mfma_f32_16x16x32_bf16 v[88:91], v[188:191], v[220:223], v[88:91]
	v_mfma_f32_16x16x32_bf16 v[84:87], v[196:199], v[220:223], v[84:87]
	v_mfma_f32_16x16x32_bf16 v[72:75], v[188:191], v[232:235], v[72:75]
	v_mfma_f32_16x16x32_bf16 v[68:71], v[196:199], v[232:235], v[68:71]
	v_mfma_f32_16x16x32_bf16 v[128:131], v[192:195], v[208:211], v[128:131]
	v_mfma_f32_16x16x32_bf16 v[120:123], v[200:203], v[208:211], v[120:123]
	v_mfma_f32_16x16x32_bf16 v[104:107], v[192:195], v[216:219], v[104:107]
	v_mfma_f32_16x16x32_bf16 v[100:103], v[200:203], v[216:219], v[100:103]
	v_mfma_f32_16x16x32_bf16 v[88:91], v[192:195], v[224:227], v[88:91]
	v_mfma_f32_16x16x32_bf16 v[84:87], v[200:203], v[224:227], v[84:87]
	v_mfma_f32_16x16x32_bf16 v[72:75], v[192:195], v[242:245], v[72:75]
	v_mfma_f32_16x16x32_bf16 v[68:71], v[200:203], v[242:245], v[68:71]
	s_setprio 0
	s_barrier
	ds_read_b128 v[204:207], v170 offset:49152
	ds_read_b128 v[208:211], v170 offset:50176
	ds_read_b128 v[212:215], v170 offset:51200
	ds_read_b128 v[216:219], v170 offset:52224
	ds_read_b128 v[220:223], v170 offset:53248
	ds_read_b128 v[224:227], v170 offset:54272
	ds_read_b128 v[232:235], v170 offset:55296
	ds_read_b128 v[242:245], v170 offset:56320
	s_add_i32 s48, s50, s16
	s_add_u32 s100, s10, s38
	s_addc_u32 s101, s11, s39
	s_mov_b32 m0, s48
	s_nop 0
	global_load_lds_dwordx4 v167, s[100:101]
	s_add_i32 m0, s48, 0x2000
	s_nop 0
	s_add_u32 s10, s10, 0x40080
	s_addc_u32 s11, s11, 0
	s_add_i32 s48, s51, s16
	global_load_lds_dwordx4 v168, s[100:101]
	s_mov_b32 m0, s48
	s_nop 0
	global_load_lds_dwordx4 v167, s[10:11]
	s_add_i32 m0, s48, 0x2000
	s_nop 0
	global_load_lds_dwordx4 v168, s[10:11]
	s_mov_b32 m0, s37
	s_add_u32 s100, s8, s38
	s_addc_u32 s101, s9, s39
	v_mov_b32_e32 v0, v166
	global_load_lds_dwordx4 v164, s[100:101]
	s_mov_b32 m0, s40
	s_nop 0
	global_load_lds_dwordx4 v166, s[100:101]
	s_waitcnt vmcnt(8) lgkmcnt(0)
	s_setprio 1
	s_barrier
	v_mfma_f32_16x16x32_bf16 v[64:67], v[172:175], v[204:207], v[64:67]
	v_mfma_f32_16x16x32_bf16 v[60:63], v[180:183], v[204:207], v[60:63]
	v_mfma_f32_16x16x32_bf16 v[48:51], v[172:175], v[212:215], v[48:51]
	v_mfma_f32_16x16x32_bf16 v[44:47], v[180:183], v[212:215], v[44:47]
	v_mfma_f32_16x16x32_bf16 v[32:35], v[172:175], v[220:223], v[32:35]
	v_mfma_f32_16x16x32_bf16 v[28:31], v[180:183], v[220:223], v[28:31]
	v_mfma_f32_16x16x32_bf16 v[16:19], v[172:175], v[232:235], v[16:19]
	v_mfma_f32_16x16x32_bf16 v[12:15], v[180:183], v[232:235], v[12:15]
	v_mfma_f32_16x16x32_bf16 v[64:67], v[176:179], v[208:211], v[64:67]
	v_mfma_f32_16x16x32_bf16 v[60:63], v[184:187], v[208:211], v[60:63]
	v_mfma_f32_16x16x32_bf16 v[48:51], v[176:179], v[216:219], v[48:51]
	v_mfma_f32_16x16x32_bf16 v[44:47], v[184:187], v[216:219], v[44:47]
	v_mfma_f32_16x16x32_bf16 v[32:35], v[176:179], v[224:227], v[32:35]
	v_mfma_f32_16x16x32_bf16 v[28:31], v[184:187], v[224:227], v[28:31]
	v_mfma_f32_16x16x32_bf16 v[16:19], v[176:179], v[242:245], v[16:19]
	v_mfma_f32_16x16x32_bf16 v[12:15], v[184:187], v[242:245], v[12:15]
	s_setprio 0
	s_setprio 1
	v_mfma_f32_16x16x32_bf16 v[56:59], v[188:191], v[204:207], v[56:59]
	v_mfma_f32_16x16x32_bf16 v[52:55], v[196:199], v[204:207], v[52:55]
	v_mfma_f32_16x16x32_bf16 v[40:43], v[188:191], v[212:215], v[40:43]
	v_mfma_f32_16x16x32_bf16 v[36:39], v[196:199], v[212:215], v[36:39]
	v_mfma_f32_16x16x32_bf16 v[24:27], v[188:191], v[220:223], v[24:27]
	v_mfma_f32_16x16x32_bf16 v[20:23], v[196:199], v[220:223], v[20:23]
	v_mfma_f32_16x16x32_bf16 v[6:9], v[188:191], v[232:235], v[8:11]
	v_mfma_f32_16x16x32_bf16 v[2:5], v[196:199], v[232:235], v[2:5]
	v_mfma_f32_16x16x32_bf16 v[56:59], v[192:195], v[208:211], v[56:59]
	v_mfma_f32_16x16x32_bf16 v[52:55], v[200:203], v[208:211], v[52:55]
	v_mfma_f32_16x16x32_bf16 v[40:43], v[192:195], v[216:219], v[40:43]
	v_mfma_f32_16x16x32_bf16 v[36:39], v[200:203], v[216:219], v[36:39]
	v_mfma_f32_16x16x32_bf16 v[24:27], v[192:195], v[224:227], v[24:27]
	v_mfma_f32_16x16x32_bf16 v[20:23], v[200:203], v[224:227], v[20:23]
	v_mfma_f32_16x16x32_bf16 v[8:11], v[192:195], v[242:245], v[6:9]
	v_mfma_f32_16x16x32_bf16 v[4:7], v[200:203], v[242:245], v[2:5]
	s_setprio 0
	s_barrier
	s_add_i32 s47, s47, 2
	s_add_u32 s6, s6, 0x100
	s_addc_u32 s7, s7, 0
	s_cmp_gt_u32 s47, 13
	s_cbranch_scc1 .LBB0_1573

.LBB0_1681:
	s_add_i32 s47, 0, 0x10000
	v_add_u32_e32 v0, s47, v136
	ds_read_b128 v[138:141], v0
	ds_read_b128 v[142:145], v0 offset:1024
	ds_read_b128 v[146:149], v0 offset:2048
	ds_read_b128 v[150:153], v0 offset:3072
	ds_read_b128 v[154:157], v0 offset:16384
	ds_read_b128 v[158:161], v0 offset:17408
	ds_read_b128 v[162:165], v0 offset:18432
	ds_read_b128 v[166:169], v0 offset:19456
	ds_read_b128 v[170:173], v137
	ds_read_b128 v[174:177], v137 offset:1024
	ds_read_b128 v[178:181], v137 offset:2048
	ds_read_b128 v[182:185], v137 offset:3072
	ds_read_b128 v[186:189], v137 offset:4096
	ds_read_b128 v[190:193], v137 offset:5120
	ds_read_b128 v[194:197], v137 offset:6144
	ds_read_b128 v[198:201], v137 offset:7168
	s_add_u32 s48, s6, s2
	s_addc_u32 s49, s7, s3
	s_add_u32 s10, s48, 0x100
	s_addc_u32 s11, s49, 0
	s_add_u32 s12, s37, s2
	s_addc_u32 s13, s40, s3
	s_cmp_eq_u32 s46, 12
	s_cselect_b32 s11, s7, s11
	s_cselect_b32 s10, s6, s10
	s_cselect_b32 s13, s9, s13
	s_cselect_b32 s12, s8, s12
	s_add_i32 s50, 0, 0x14000
	s_add_i32 m0, s23, 0xc000
	s_add_u32 s100, s48, s56
	s_addc_u32 s101, s49, s57
	global_load_lds_dwordx4 v130, s[100:101]
	s_add_i32 m0, s23, 0xe000
	s_nop 0
	global_load_lds_dwordx4 v132, s[100:101]
	s_waitcnt vmcnt(8) lgkmcnt(0)
	s_setprio 1
	s_barrier
	v_mfma_f32_16x16x32_bf16 v[126:129], v[138:141], v[170:173], v[126:129]
	v_mfma_f32_16x16x32_bf16 v[122:125], v[146:149], v[170:173], v[122:125]
	v_mfma_f32_16x16x32_bf16 v[110:113], v[138:141], v[178:181], v[110:113]
	v_mfma_f32_16x16x32_bf16 v[106:109], v[146:149], v[178:181], v[106:109]
	v_mfma_f32_16x16x32_bf16 v[94:97], v[138:141], v[186:189], v[94:97]
	v_mfma_f32_16x16x32_bf16 v[90:93], v[146:149], v[186:189], v[90:93]
	v_mfma_f32_16x16x32_bf16 v[78:81], v[138:141], v[194:197], v[78:81]
	v_mfma_f32_16x16x32_bf16 v[74:77], v[146:149], v[194:197], v[74:77]
	v_mfma_f32_16x16x32_bf16 v[126:129], v[142:145], v[174:177], v[126:129]
	v_mfma_f32_16x16x32_bf16 v[122:125], v[150:153], v[174:177], v[122:125]
	v_mfma_f32_16x16x32_bf16 v[110:113], v[142:145], v[182:185], v[110:113]
	v_mfma_f32_16x16x32_bf16 v[106:109], v[150:153], v[182:185], v[106:109]
	v_mfma_f32_16x16x32_bf16 v[94:97], v[142:145], v[190:193], v[94:97]
	v_mfma_f32_16x16x32_bf16 v[90:93], v[150:153], v[190:193], v[90:93]
	v_mfma_f32_16x16x32_bf16 v[78:81], v[142:145], v[198:201], v[78:81]
	v_mfma_f32_16x16x32_bf16 v[74:77], v[150:153], v[198:201], v[74:77]
	s_setprio 0
	s_setprio 1
	v_mfma_f32_16x16x32_bf16 v[118:121], v[154:157], v[170:173], v[118:121]
	v_mfma_f32_16x16x32_bf16 v[114:117], v[162:165], v[170:173], v[114:117]
	v_mfma_f32_16x16x32_bf16 v[102:105], v[154:157], v[178:181], v[102:105]
	v_mfma_f32_16x16x32_bf16 v[98:101], v[162:165], v[178:181], v[98:101]
	v_mfma_f32_16x16x32_bf16 v[86:89], v[154:157], v[186:189], v[86:89]
	v_mfma_f32_16x16x32_bf16 v[82:85], v[162:165], v[186:189], v[82:85]
	v_mfma_f32_16x16x32_bf16 v[70:73], v[154:157], v[194:197], v[70:73]
	v_mfma_f32_16x16x32_bf16 v[66:69], v[162:165], v[194:197], v[66:69]
	v_mfma_f32_16x16x32_bf16 v[118:121], v[158:161], v[174:177], v[118:121]
	v_mfma_f32_16x16x32_bf16 v[114:117], v[166:169], v[174:177], v[114:117]
	v_mfma_f32_16x16x32_bf16 v[102:105], v[158:161], v[182:185], v[102:105]
	v_mfma_f32_16x16x32_bf16 v[98:101], v[166:169], v[182:185], v[98:101]
	v_mfma_f32_16x16x32_bf16 v[86:89], v[158:161], v[190:193], v[86:89]
	v_mfma_f32_16x16x32_bf16 v[82:85], v[166:169], v[190:193], v[82:85]
	v_mfma_f32_16x16x32_bf16 v[70:73], v[158:161], v[198:201], v[70:73]
	v_mfma_f32_16x16x32_bf16 v[66:69], v[166:169], v[198:201], v[66:69]
	s_setprio 0
	s_barrier
	ds_read_b128 v[170:173], v137 offset:16384
	ds_read_b128 v[174:177], v137 offset:17408
	ds_read_b128 v[178:181], v137 offset:18432
	ds_read_b128 v[182:185], v137 offset:19456
	ds_read_b128 v[186:189], v137 offset:20480
	ds_read_b128 v[190:193], v137 offset:21504
	ds_read_b128 v[194:197], v137 offset:22528
	ds_read_b128 v[198:201], v137 offset:23552
	s_add_i32 s47, s47, s22
	s_mov_b32 m0, s47
	s_nop 0
	global_load_lds_dwordx4 v134, s[12:13]
	s_add_i32 m0, s47, 0x2000
	s_add_u32 s48, s12, 0x40000
	global_load_lds_dwordx4 v135, s[12:13]
	s_addc_u32 s49, s13, 0
	s_add_i32 s47, s50, s22
	s_mov_b32 m0, s47
	s_nop 0
	global_load_lds_dwordx4 v134, s[48:49]
	s_add_i32 m0, s47, 0x2000
	s_nop 0
	global_load_lds_dwordx4 v135, s[48:49]
	s_mov_b32 m0, s23
	s_nop 0
	global_load_lds_dwordx4 v130, s[10:11]
	s_mov_b32 m0, s24
	s_nop 0
	global_load_lds_dwordx4 v132, s[10:11]
	s_waitcnt vmcnt(8) lgkmcnt(0)
	s_setprio 1
	s_barrier
	v_mfma_f32_16x16x32_bf16 v[62:65], v[138:141], v[170:173], v[62:65]
	v_mfma_f32_16x16x32_bf16 v[58:61], v[146:149], v[170:173], v[58:61]
	v_mfma_f32_16x16x32_bf16 v[46:49], v[138:141], v[178:181], v[46:49]
	v_mfma_f32_16x16x32_bf16 v[42:45], v[146:149], v[178:181], v[42:45]
	v_mfma_f32_16x16x32_bf16 v[30:33], v[138:141], v[186:189], v[30:33]
	v_mfma_f32_16x16x32_bf16 v[26:29], v[146:149], v[186:189], v[26:29]
	v_mfma_f32_16x16x32_bf16 v[14:17], v[138:141], v[194:197], v[14:17]
	v_mfma_f32_16x16x32_bf16 v[10:13], v[146:149], v[194:197], v[10:13]
	v_mfma_f32_16x16x32_bf16 v[62:65], v[142:145], v[174:177], v[62:65]
	v_mfma_f32_16x16x32_bf16 v[58:61], v[150:153], v[174:177], v[58:61]
	v_mfma_f32_16x16x32_bf16 v[46:49], v[142:145], v[182:185], v[46:49]
	v_mfma_f32_16x16x32_bf16 v[42:45], v[150:153], v[182:185], v[42:45]
	v_mfma_f32_16x16x32_bf16 v[30:33], v[142:145], v[190:193], v[30:33]
	v_mfma_f32_16x16x32_bf16 v[26:29], v[150:153], v[190:193], v[26:29]
	v_mfma_f32_16x16x32_bf16 v[14:17], v[142:145], v[198:201], v[14:17]
	v_mfma_f32_16x16x32_bf16 v[10:13], v[150:153], v[198:201], v[10:13]
	s_setprio 0
	s_setprio 1
	v_mfma_f32_16x16x32_bf16 v[54:57], v[154:157], v[170:173], v[54:57]
	v_mfma_f32_16x16x32_bf16 v[50:53], v[162:165], v[170:173], v[50:53]
	v_mfma_f32_16x16x32_bf16 v[38:41], v[154:157], v[178:181], v[38:41]
	v_mfma_f32_16x16x32_bf16 v[34:37], v[162:165], v[178:181], v[34:37]
	v_mfma_f32_16x16x32_bf16 v[22:25], v[154:157], v[186:189], v[22:25]
	v_mfma_f32_16x16x32_bf16 v[18:21], v[162:165], v[186:189], v[18:21]
	v_mfma_f32_16x16x32_bf16 v[6:9], v[154:157], v[194:197], v[6:9]
	v_mfma_f32_16x16x32_bf16 v[2:5], v[162:165], v[194:197], v[2:5]
	v_mfma_f32_16x16x32_bf16 v[54:57], v[158:161], v[174:177], v[54:57]
	v_mfma_f32_16x16x32_bf16 v[50:53], v[166:169], v[174:177], v[50:53]
	v_mfma_f32_16x16x32_bf16 v[38:41], v[158:161], v[182:185], v[38:41]
	v_mfma_f32_16x16x32_bf16 v[34:37], v[166:169], v[182:185], v[34:37]
	v_mfma_f32_16x16x32_bf16 v[22:25], v[158:161], v[190:193], v[22:25]
	v_mfma_f32_16x16x32_bf16 v[18:21], v[166:169], v[190:193], v[18:21]
	v_mfma_f32_16x16x32_bf16 v[6:9], v[158:161], v[198:201], v[6:9]
	v_mfma_f32_16x16x32_bf16 v[2:5], v[166:169], v[198:201], v[2:5]
	s_setprio 0
	s_barrier
	ds_read_b128 v[138:141], v0 offset:32768
	ds_read_b128 v[142:145], v0 offset:33792
	ds_read_b128 v[146:149], v0 offset:34816
	ds_read_b128 v[150:153], v0 offset:35840
	ds_read_b128 v[154:157], v0 offset:49152
	ds_read_b128 v[158:161], v0 offset:50176
	ds_read_b128 v[162:165], v0 offset:51200
	ds_read_b128 v[166:169], v0 offset:52224
	s_add_u32 s48, s10, 0x40000
	s_mov_b32 m0, s25
	ds_read_b128 v[170:173], v137 offset:32768
	ds_read_b128 v[174:177], v137 offset:33792
	ds_read_b128 v[178:181], v137 offset:34816
	ds_read_b128 v[182:185], v137 offset:35840
	ds_read_b128 v[186:189], v137 offset:36864
	ds_read_b128 v[190:193], v137 offset:37888
	ds_read_b128 v[194:197], v137 offset:38912
	ds_read_b128 v[198:201], v137 offset:39936
	s_addc_u32 s49, s11, 0
	s_add_i32 s47, 0, 0x18000
	s_add_i32 s50, 0, 0x1c000
	s_nop 0
	global_load_lds_dwordx4 v130, s[48:49]
	s_mov_b32 m0, s26
	s_nop 0
	global_load_lds_dwordx4 v132, s[48:49]
	s_waitcnt vmcnt(8) lgkmcnt(0)
	s_setprio 1
	s_barrier
	v_mfma_f32_16x16x32_bf16 v[126:129], v[138:141], v[170:173], v[126:129]
	v_mfma_f32_16x16x32_bf16 v[122:125], v[146:149], v[170:173], v[122:125]
	v_mfma_f32_16x16x32_bf16 v[110:113], v[138:141], v[178:181], v[110:113]
	v_mfma_f32_16x16x32_bf16 v[106:109], v[146:149], v[178:181], v[106:109]
	v_mfma_f32_16x16x32_bf16 v[94:97], v[138:141], v[186:189], v[94:97]
	v_mfma_f32_16x16x32_bf16 v[90:93], v[146:149], v[186:189], v[90:93]
	v_mfma_f32_16x16x32_bf16 v[78:81], v[138:141], v[194:197], v[78:81]
	v_mfma_f32_16x16x32_bf16 v[74:77], v[146:149], v[194:197], v[74:77]
	v_mfma_f32_16x16x32_bf16 v[126:129], v[142:145], v[174:177], v[126:129]
	v_mfma_f32_16x16x32_bf16 v[122:125], v[150:153], v[174:177], v[122:125]
	v_mfma_f32_16x16x32_bf16 v[110:113], v[142:145], v[182:185], v[110:113]
	v_mfma_f32_16x16x32_bf16 v[106:109], v[150:153], v[182:185], v[106:109]
	v_mfma_f32_16x16x32_bf16 v[94:97], v[142:145], v[190:193], v[94:97]
	v_mfma_f32_16x16x32_bf16 v[90:93], v[150:153], v[190:193], v[90:93]
	v_mfma_f32_16x16x32_bf16 v[78:81], v[142:145], v[198:201], v[78:81]
	v_mfma_f32_16x16x32_bf16 v[74:77], v[150:153], v[198:201], v[74:77]
	s_setprio 0
	s_setprio 1
	v_mfma_f32_16x16x32_bf16 v[118:121], v[154:157], v[170:173], v[118:121]
	v_mfma_f32_16x16x32_bf16 v[114:117], v[162:165], v[170:173], v[114:117]
	v_mfma_f32_16x16x32_bf16 v[102:105], v[154:157], v[178:181], v[102:105]
	v_mfma_f32_16x16x32_bf16 v[98:101], v[162:165], v[178:181], v[98:101]
	v_mfma_f32_16x16x32_bf16 v[86:89], v[154:157], v[186:189], v[86:89]
	v_mfma_f32_16x16x32_bf16 v[82:85], v[162:165], v[186:189], v[82:85]
	v_mfma_f32_16x16x32_bf16 v[70:73], v[154:157], v[194:197], v[70:73]
	v_mfma_f32_16x16x32_bf16 v[66:69], v[162:165], v[194:197], v[66:69]
	v_mfma_f32_16x16x32_bf16 v[118:121], v[158:161], v[174:177], v[118:121]
	v_mfma_f32_16x16x32_bf16 v[114:117], v[166:169], v[174:177], v[114:117]
	v_mfma_f32_16x16x32_bf16 v[102:105], v[158:161], v[182:185], v[102:105]
	v_mfma_f32_16x16x32_bf16 v[98:101], v[166:169], v[182:185], v[98:101]
	v_mfma_f32_16x16x32_bf16 v[86:89], v[158:161], v[190:193], v[86:89]
	v_mfma_f32_16x16x32_bf16 v[82:85], v[166:169], v[190:193], v[82:85]
	v_mfma_f32_16x16x32_bf16 v[70:73], v[158:161], v[198:201], v[70:73]
	v_mfma_f32_16x16x32_bf16 v[66:69], v[166:169], v[198:201], v[66:69]
	s_setprio 0
	s_barrier
	ds_read_b128 v[170:173], v137 offset:49152
	ds_read_b128 v[174:177], v137 offset:50176
	ds_read_b128 v[178:181], v137 offset:51200
	ds_read_b128 v[182:185], v137 offset:52224
	ds_read_b128 v[186:189], v137 offset:53248
	ds_read_b128 v[190:193], v137 offset:54272
	ds_read_b128 v[194:197], v137 offset:55296
	ds_read_b128 v[198:201], v137 offset:56320
	s_add_i32 s47, s47, s22
	s_add_u32 s100, s12, s38
	s_addc_u32 s101, s13, s39
	s_mov_b32 m0, s47
	s_nop 0
	global_load_lds_dwordx4 v134, s[100:101]
	s_add_i32 m0, s47, 0x2000
	s_nop 0
	s_add_u32 s12, s12, 0x40080
	s_addc_u32 s13, s13, 0
	s_add_i32 s47, s50, s22
	global_load_lds_dwordx4 v135, s[100:101]
	s_mov_b32 m0, s47
	s_nop 0
	global_load_lds_dwordx4 v134, s[12:13]
	s_add_i32 m0, s47, 0x2000
	s_nop 0
	global_load_lds_dwordx4 v135, s[12:13]
	s_mov_b32 m0, s42
	s_add_u32 s100, s10, s38
	s_addc_u32 s101, s11, s39
	v_mov_b32_e32 v0, v132
	global_load_lds_dwordx4 v130, s[100:101]
	s_mov_b32 m0, s43
	s_nop 0
	global_load_lds_dwordx4 v132, s[100:101]
	s_waitcnt vmcnt(8) lgkmcnt(0)
	s_setprio 1
	s_barrier
	v_mfma_f32_16x16x32_bf16 v[62:65], v[138:141], v[170:173], v[62:65]
	v_mfma_f32_16x16x32_bf16 v[58:61], v[146:149], v[170:173], v[58:61]
	v_mfma_f32_16x16x32_bf16 v[46:49], v[138:141], v[178:181], v[46:49]
	v_mfma_f32_16x16x32_bf16 v[42:45], v[146:149], v[178:181], v[42:45]
	v_mfma_f32_16x16x32_bf16 v[30:33], v[138:141], v[186:189], v[30:33]
	v_mfma_f32_16x16x32_bf16 v[26:29], v[146:149], v[186:189], v[26:29]
	v_mfma_f32_16x16x32_bf16 v[14:17], v[138:141], v[194:197], v[14:17]
	v_mfma_f32_16x16x32_bf16 v[10:13], v[146:149], v[194:197], v[10:13]
	v_mfma_f32_16x16x32_bf16 v[62:65], v[142:145], v[174:177], v[62:65]
	v_mfma_f32_16x16x32_bf16 v[58:61], v[150:153], v[174:177], v[58:61]
	v_mfma_f32_16x16x32_bf16 v[46:49], v[142:145], v[182:185], v[46:49]
	v_mfma_f32_16x16x32_bf16 v[42:45], v[150:153], v[182:185], v[42:45]
	v_mfma_f32_16x16x32_bf16 v[30:33], v[142:145], v[190:193], v[30:33]
	v_mfma_f32_16x16x32_bf16 v[26:29], v[150:153], v[190:193], v[26:29]
	v_mfma_f32_16x16x32_bf16 v[14:17], v[142:145], v[198:201], v[14:17]
	v_mfma_f32_16x16x32_bf16 v[10:13], v[150:153], v[198:201], v[10:13]
	s_setprio 0
	s_setprio 1
	v_mfma_f32_16x16x32_bf16 v[54:57], v[154:157], v[170:173], v[54:57]
	v_mfma_f32_16x16x32_bf16 v[50:53], v[162:165], v[170:173], v[50:53]
	v_mfma_f32_16x16x32_bf16 v[38:41], v[154:157], v[178:181], v[38:41]
	v_mfma_f32_16x16x32_bf16 v[34:37], v[162:165], v[178:181], v[34:37]
	v_mfma_f32_16x16x32_bf16 v[22:25], v[154:157], v[186:189], v[22:25]
	v_mfma_f32_16x16x32_bf16 v[18:21], v[162:165], v[186:189], v[18:21]
	v_mfma_f32_16x16x32_bf16 v[6:9], v[154:157], v[194:197], v[6:9]
	v_mfma_f32_16x16x32_bf16 v[2:5], v[162:165], v[194:197], v[2:5]
	v_mfma_f32_16x16x32_bf16 v[54:57], v[158:161], v[174:177], v[54:57]
	v_mfma_f32_16x16x32_bf16 v[50:53], v[166:169], v[174:177], v[50:53]
	v_mfma_f32_16x16x32_bf16 v[38:41], v[158:161], v[182:185], v[38:41]
	v_mfma_f32_16x16x32_bf16 v[34:37], v[166:169], v[182:185], v[34:37]
	v_mfma_f32_16x16x32_bf16 v[22:25], v[158:161], v[190:193], v[22:25]
	v_mfma_f32_16x16x32_bf16 v[18:21], v[166:169], v[190:193], v[18:21]
	v_mfma_f32_16x16x32_bf16 v[6:9], v[158:161], v[198:201], v[6:9]
	v_mfma_f32_16x16x32_bf16 v[2:5], v[166:169], v[198:201], v[2:5]
	s_setprio 0
	s_barrier
	s_add_i32 s46, s46, 2
	s_add_u32 s2, s2, 0x100
	s_addc_u32 s3, s3, 0
	s_cmp_gt_u32 s46, 13
	s_cbranch_scc0 .LBB0_1681

.LBB0_1807:
	s_add_i32 s67, 0, 0x10000
	v_add_u32_e32 v0, s67, v126
	ds_read_b128 v[128:131], v0
	ds_read_b128 v[142:145], v0 offset:1024
	ds_read_b128 v[146:149], v0 offset:2048
	ds_read_b128 v[150:153], v0 offset:3072
	ds_read_b128 v[154:157], v0 offset:16384
	ds_read_b128 v[160:163], v0 offset:17408
	ds_read_b128 v[164:167], v0 offset:18432
	ds_read_b128 v[168:171], v0 offset:19456
	ds_read_b128 v[172:175], v127
	ds_read_b128 v[176:179], v127 offset:1024
	ds_read_b128 v[180:183], v127 offset:2048
	ds_read_b128 v[184:187], v127 offset:3072
	ds_read_b128 v[188:191], v127 offset:4096
	ds_read_b128 v[192:195], v127 offset:5120
	ds_read_b128 v[196:199], v127 offset:6144
	ds_read_b128 v[200:203], v127 offset:7168
	s_add_u32 s68, s4, s14
	s_addc_u32 s69, s5, s15
	s_add_u32 s16, s68, 0x100
	s_addc_u32 s17, s69, 0
	s_add_u32 s22, s50, s14
	s_addc_u32 s23, s51, s15
	s_cmp_eq_u32 s66, 12
	s_cselect_b32 s17, s5, s17
	s_cselect_b32 s16, s4, s16
	s_cselect_b32 s23, s13, s23
	s_cselect_b32 s22, s12, s22
	s_add_i32 s70, 0, 0x14000
	s_add_i32 m0, s43, 0xc000
	s_add_u32 s100, s68, s56
	s_addc_u32 s101, s69, s57
	global_load_lds_dwordx4 v122, s[100:101]
	s_add_i32 m0, s43, 0xe000
	s_nop 0
	global_load_lds_dwordx4 v123, s[100:101]
	s_waitcnt vmcnt(8) lgkmcnt(0)
	s_setprio 1
	s_barrier
	v_mfma_f32_16x16x32_bf16 v[138:141], v[128:131], v[172:175], v[138:141]
	v_mfma_f32_16x16x32_bf16 v[132:135], v[146:149], v[172:175], v[134:137]
	v_mfma_f32_16x16x32_bf16 v[110:113], v[128:131], v[180:183], v[110:113]
	v_mfma_f32_16x16x32_bf16 v[106:109], v[146:149], v[180:183], v[106:109]
	v_mfma_f32_16x16x32_bf16 v[94:97], v[128:131], v[188:191], v[94:97]
	v_mfma_f32_16x16x32_bf16 v[90:93], v[146:149], v[188:191], v[90:93]
	v_mfma_f32_16x16x32_bf16 v[78:81], v[128:131], v[196:199], v[78:81]
	v_mfma_f32_16x16x32_bf16 v[74:77], v[146:149], v[196:199], v[74:77]
	v_mfma_f32_16x16x32_bf16 v[138:141], v[142:145], v[176:179], v[138:141]
	v_mfma_f32_16x16x32_bf16 v[132:135], v[150:153], v[176:179], v[132:135]
	v_mfma_f32_16x16x32_bf16 v[110:113], v[142:145], v[184:187], v[110:113]
	v_mfma_f32_16x16x32_bf16 v[106:109], v[150:153], v[184:187], v[106:109]
	v_mfma_f32_16x16x32_bf16 v[94:97], v[142:145], v[192:195], v[94:97]
	v_mfma_f32_16x16x32_bf16 v[90:93], v[150:153], v[192:195], v[90:93]
	v_mfma_f32_16x16x32_bf16 v[78:81], v[142:145], v[200:203], v[78:81]
	v_mfma_f32_16x16x32_bf16 v[74:77], v[150:153], v[200:203], v[74:77]
	s_setprio 0
	s_setprio 1
	v_mfma_f32_16x16x32_bf16 v[118:121], v[154:157], v[172:175], v[118:121]
	v_mfma_f32_16x16x32_bf16 v[114:117], v[164:167], v[172:175], v[114:117]
	v_mfma_f32_16x16x32_bf16 v[102:105], v[154:157], v[180:183], v[102:105]
	v_mfma_f32_16x16x32_bf16 v[98:101], v[164:167], v[180:183], v[98:101]
	v_mfma_f32_16x16x32_bf16 v[86:89], v[154:157], v[188:191], v[86:89]
	v_mfma_f32_16x16x32_bf16 v[82:85], v[164:167], v[188:191], v[82:85]
	v_mfma_f32_16x16x32_bf16 v[70:73], v[154:157], v[196:199], v[70:73]
	v_mfma_f32_16x16x32_bf16 v[66:69], v[164:167], v[196:199], v[66:69]
	v_mfma_f32_16x16x32_bf16 v[118:121], v[160:163], v[176:179], v[118:121]
	v_mfma_f32_16x16x32_bf16 v[114:117], v[168:171], v[176:179], v[114:117]
	v_mfma_f32_16x16x32_bf16 v[102:105], v[160:163], v[184:187], v[102:105]
	v_mfma_f32_16x16x32_bf16 v[98:101], v[168:171], v[184:187], v[98:101]
	v_mfma_f32_16x16x32_bf16 v[86:89], v[160:163], v[192:195], v[86:89]
	v_mfma_f32_16x16x32_bf16 v[82:85], v[168:171], v[192:195], v[82:85]
	v_mfma_f32_16x16x32_bf16 v[70:73], v[160:163], v[200:203], v[70:73]
	v_mfma_f32_16x16x32_bf16 v[66:69], v[168:171], v[200:203], v[66:69]
	s_setprio 0
	s_barrier
	ds_read_b128 v[172:175], v127 offset:16384
	ds_read_b128 v[176:179], v127 offset:17408
	ds_read_b128 v[180:183], v127 offset:18432
	ds_read_b128 v[184:187], v127 offset:19456
	ds_read_b128 v[188:191], v127 offset:20480
	ds_read_b128 v[192:195], v127 offset:21504
	ds_read_b128 v[196:199], v127 offset:22528
	ds_read_b128 v[200:203], v127 offset:23552
	s_add_i32 s67, s67, s42
	s_mov_b32 m0, s67
	s_nop 0
	global_load_lds_dwordx4 v124, s[22:23]
	s_add_i32 m0, s67, 0x2000
	s_add_u32 s68, s22, 0x40000
	global_load_lds_dwordx4 v125, s[22:23]
	s_addc_u32 s69, s23, 0
	s_add_i32 s67, s70, s42
	s_mov_b32 m0, s67
	s_nop 0
	global_load_lds_dwordx4 v124, s[68:69]
	s_add_i32 m0, s67, 0x2000
	s_nop 0
	global_load_lds_dwordx4 v125, s[68:69]
	s_mov_b32 m0, s43
	s_nop 0
	global_load_lds_dwordx4 v122, s[16:17]
	s_mov_b32 m0, s46
	s_nop 0
	global_load_lds_dwordx4 v123, s[16:17]
	s_waitcnt vmcnt(8) lgkmcnt(0)
	s_setprio 1
	s_barrier
	v_mfma_f32_16x16x32_bf16 v[62:65], v[128:131], v[172:175], v[62:65]
	v_mfma_f32_16x16x32_bf16 v[58:61], v[146:149], v[172:175], v[58:61]
	v_mfma_f32_16x16x32_bf16 v[46:49], v[128:131], v[180:183], v[46:49]
	v_mfma_f32_16x16x32_bf16 v[42:45], v[146:149], v[180:183], v[42:45]
	v_mfma_f32_16x16x32_bf16 v[30:33], v[128:131], v[188:191], v[30:33]
	v_mfma_f32_16x16x32_bf16 v[26:29], v[146:149], v[188:191], v[26:29]
	v_mfma_f32_16x16x32_bf16 v[14:17], v[128:131], v[196:199], v[14:17]
	v_mfma_f32_16x16x32_bf16 v[10:13], v[146:149], v[196:199], v[10:13]
	v_mfma_f32_16x16x32_bf16 v[62:65], v[142:145], v[176:179], v[62:65]
	v_mfma_f32_16x16x32_bf16 v[58:61], v[150:153], v[176:179], v[58:61]
	v_mfma_f32_16x16x32_bf16 v[46:49], v[142:145], v[184:187], v[46:49]
	v_mfma_f32_16x16x32_bf16 v[42:45], v[150:153], v[184:187], v[42:45]
	v_mfma_f32_16x16x32_bf16 v[30:33], v[142:145], v[192:195], v[30:33]
	v_mfma_f32_16x16x32_bf16 v[26:29], v[150:153], v[192:195], v[26:29]
	v_mfma_f32_16x16x32_bf16 v[14:17], v[142:145], v[200:203], v[14:17]
	v_mfma_f32_16x16x32_bf16 v[10:13], v[150:153], v[200:203], v[10:13]
	s_setprio 0
	s_setprio 1
	v_mfma_f32_16x16x32_bf16 v[54:57], v[154:157], v[172:175], v[54:57]
	v_mfma_f32_16x16x32_bf16 v[50:53], v[164:167], v[172:175], v[50:53]
	v_mfma_f32_16x16x32_bf16 v[38:41], v[154:157], v[180:183], v[38:41]
	v_mfma_f32_16x16x32_bf16 v[34:37], v[164:167], v[180:183], v[34:37]
	v_mfma_f32_16x16x32_bf16 v[22:25], v[154:157], v[188:191], v[22:25]
	v_mfma_f32_16x16x32_bf16 v[18:21], v[164:167], v[188:191], v[18:21]
	v_mfma_f32_16x16x32_bf16 v[6:9], v[154:157], v[196:199], v[6:9]
	v_mfma_f32_16x16x32_bf16 v[2:5], v[164:167], v[196:199], v[2:5]
	v_mfma_f32_16x16x32_bf16 v[54:57], v[160:163], v[176:179], v[54:57]
	v_mfma_f32_16x16x32_bf16 v[50:53], v[168:171], v[176:179], v[50:53]
	v_mfma_f32_16x16x32_bf16 v[38:41], v[160:163], v[184:187], v[38:41]
	v_mfma_f32_16x16x32_bf16 v[34:37], v[168:171], v[184:187], v[34:37]
	v_mfma_f32_16x16x32_bf16 v[22:25], v[160:163], v[192:195], v[22:25]
	v_mfma_f32_16x16x32_bf16 v[18:21], v[168:171], v[192:195], v[18:21]
	v_mfma_f32_16x16x32_bf16 v[6:9], v[160:163], v[200:203], v[6:9]
	v_mfma_f32_16x16x32_bf16 v[2:5], v[168:171], v[200:203], v[2:5]
	s_setprio 0
	s_barrier
	ds_read_b128 v[128:131], v0 offset:32768
	ds_read_b128 v[142:145], v0 offset:33792
	ds_read_b128 v[146:149], v0 offset:34816
	ds_read_b128 v[150:153], v0 offset:35840
	ds_read_b128 v[154:157], v0 offset:49152
	ds_read_b128 v[160:163], v0 offset:50176
	ds_read_b128 v[164:167], v0 offset:51200
	ds_read_b128 v[168:171], v0 offset:52224
	s_add_u32 s68, s16, 0x40000
	s_mov_b32 m0, s47
	ds_read_b128 v[172:175], v127 offset:32768
	ds_read_b128 v[176:179], v127 offset:33792
	ds_read_b128 v[180:183], v127 offset:34816
	ds_read_b128 v[184:187], v127 offset:35840
	ds_read_b128 v[188:191], v127 offset:36864
	ds_read_b128 v[192:195], v127 offset:37888
	ds_read_b128 v[196:199], v127 offset:38912
	ds_read_b128 v[200:203], v127 offset:39936
	s_addc_u32 s69, s17, 0
	s_add_i32 s67, 0, 0x18000
	s_add_i32 s70, 0, 0x1c000
	s_nop 0
	global_load_lds_dwordx4 v122, s[68:69]
	s_mov_b32 m0, s48
	s_nop 0
	global_load_lds_dwordx4 v123, s[68:69]
	s_waitcnt vmcnt(8) lgkmcnt(0)
	s_setprio 1
	s_barrier
	v_mfma_f32_16x16x32_bf16 v[136:139], v[128:131], v[172:175], v[138:141]
	v_mfma_f32_16x16x32_bf16 v[132:135], v[146:149], v[172:175], v[132:135]
	v_mfma_f32_16x16x32_bf16 v[110:113], v[128:131], v[180:183], v[110:113]
	v_mfma_f32_16x16x32_bf16 v[106:109], v[146:149], v[180:183], v[106:109]
	v_mfma_f32_16x16x32_bf16 v[94:97], v[128:131], v[188:191], v[94:97]
	v_mfma_f32_16x16x32_bf16 v[90:93], v[146:149], v[188:191], v[90:93]
	v_mfma_f32_16x16x32_bf16 v[78:81], v[128:131], v[196:199], v[78:81]
	v_mfma_f32_16x16x32_bf16 v[74:77], v[146:149], v[196:199], v[74:77]
	v_mfma_f32_16x16x32_bf16 v[138:141], v[142:145], v[176:179], v[136:139]
	v_mfma_f32_16x16x32_bf16 v[134:137], v[150:153], v[176:179], v[132:135]
	v_mfma_f32_16x16x32_bf16 v[110:113], v[142:145], v[184:187], v[110:113]
	v_mfma_f32_16x16x32_bf16 v[106:109], v[150:153], v[184:187], v[106:109]
	v_mfma_f32_16x16x32_bf16 v[94:97], v[142:145], v[192:195], v[94:97]
	v_mfma_f32_16x16x32_bf16 v[90:93], v[150:153], v[192:195], v[90:93]
	v_mfma_f32_16x16x32_bf16 v[78:81], v[142:145], v[200:203], v[78:81]
	v_mfma_f32_16x16x32_bf16 v[74:77], v[150:153], v[200:203], v[74:77]
	s_setprio 0
	s_setprio 1
	v_mfma_f32_16x16x32_bf16 v[118:121], v[154:157], v[172:175], v[118:121]
	v_mfma_f32_16x16x32_bf16 v[114:117], v[164:167], v[172:175], v[114:117]
	v_mfma_f32_16x16x32_bf16 v[102:105], v[154:157], v[180:183], v[102:105]
	v_mfma_f32_16x16x32_bf16 v[98:101], v[164:167], v[180:183], v[98:101]
	v_mfma_f32_16x16x32_bf16 v[86:89], v[154:157], v[188:191], v[86:89]
	v_mfma_f32_16x16x32_bf16 v[82:85], v[164:167], v[188:191], v[82:85]
	v_mfma_f32_16x16x32_bf16 v[70:73], v[154:157], v[196:199], v[70:73]
	v_mfma_f32_16x16x32_bf16 v[66:69], v[164:167], v[196:199], v[66:69]
	v_mfma_f32_16x16x32_bf16 v[118:121], v[160:163], v[176:179], v[118:121]
	v_mfma_f32_16x16x32_bf16 v[114:117], v[168:171], v[176:179], v[114:117]
	v_mfma_f32_16x16x32_bf16 v[102:105], v[160:163], v[184:187], v[102:105]
	v_mfma_f32_16x16x32_bf16 v[98:101], v[168:171], v[184:187], v[98:101]
	v_mfma_f32_16x16x32_bf16 v[86:89], v[160:163], v[192:195], v[86:89]
	v_mfma_f32_16x16x32_bf16 v[82:85], v[168:171], v[192:195], v[82:85]
	v_mfma_f32_16x16x32_bf16 v[70:73], v[160:163], v[200:203], v[70:73]
	v_mfma_f32_16x16x32_bf16 v[66:69], v[168:171], v[200:203], v[66:69]
	s_setprio 0
	s_barrier
	ds_read_b128 v[172:175], v127 offset:49152
	ds_read_b128 v[176:179], v127 offset:50176
	ds_read_b128 v[180:183], v127 offset:51200
	ds_read_b128 v[184:187], v127 offset:52224
	ds_read_b128 v[188:191], v127 offset:53248
	ds_read_b128 v[192:195], v127 offset:54272
	ds_read_b128 v[196:199], v127 offset:55296
	ds_read_b128 v[200:203], v127 offset:56320
	s_add_i32 s67, s67, s42
	s_add_u32 s100, s22, s38
	s_addc_u32 s101, s23, s39
	s_mov_b32 m0, s67
	s_nop 0
	global_load_lds_dwordx4 v124, s[100:101]
	s_add_i32 m0, s67, 0x2000
	s_nop 0
	s_add_u32 s22, s22, 0x40080
	s_addc_u32 s23, s23, 0
	s_add_i32 s67, s70, s42
	global_load_lds_dwordx4 v125, s[100:101]
	s_mov_b32 m0, s67
	s_nop 0
	global_load_lds_dwordx4 v124, s[22:23]
	s_add_i32 m0, s67, 0x2000
	s_nop 0
	global_load_lds_dwordx4 v125, s[22:23]
	s_mov_b32 m0, s64
	s_add_u32 s100, s16, s38
	s_addc_u32 s101, s17, s39
	v_mov_b32_e32 v0, v123
	global_load_lds_dwordx4 v122, s[100:101]
	s_mov_b32 m0, s65
	s_nop 0
	global_load_lds_dwordx4 v123, s[100:101]
	s_waitcnt vmcnt(8) lgkmcnt(0)
	s_setprio 1
	s_barrier
	v_mfma_f32_16x16x32_bf16 v[62:65], v[128:131], v[172:175], v[62:65]
	v_mfma_f32_16x16x32_bf16 v[58:61], v[146:149], v[172:175], v[58:61]
	v_mfma_f32_16x16x32_bf16 v[46:49], v[128:131], v[180:183], v[46:49]
	v_mfma_f32_16x16x32_bf16 v[42:45], v[146:149], v[180:183], v[42:45]
	v_mfma_f32_16x16x32_bf16 v[30:33], v[128:131], v[188:191], v[30:33]
	v_mfma_f32_16x16x32_bf16 v[26:29], v[146:149], v[188:191], v[26:29]
	v_mfma_f32_16x16x32_bf16 v[14:17], v[128:131], v[196:199], v[14:17]
	v_mfma_f32_16x16x32_bf16 v[10:13], v[146:149], v[196:199], v[10:13]
	v_mfma_f32_16x16x32_bf16 v[62:65], v[142:145], v[176:179], v[62:65]
	v_mfma_f32_16x16x32_bf16 v[58:61], v[150:153], v[176:179], v[58:61]
	v_mfma_f32_16x16x32_bf16 v[46:49], v[142:145], v[184:187], v[46:49]
	v_mfma_f32_16x16x32_bf16 v[42:45], v[150:153], v[184:187], v[42:45]
	v_mfma_f32_16x16x32_bf16 v[30:33], v[142:145], v[192:195], v[30:33]
	v_mfma_f32_16x16x32_bf16 v[26:29], v[150:153], v[192:195], v[26:29]
	v_mfma_f32_16x16x32_bf16 v[14:17], v[142:145], v[200:203], v[14:17]
	v_mfma_f32_16x16x32_bf16 v[10:13], v[150:153], v[200:203], v[10:13]
	s_setprio 0
	s_setprio 1
	v_mfma_f32_16x16x32_bf16 v[54:57], v[154:157], v[172:175], v[54:57]
	v_mfma_f32_16x16x32_bf16 v[50:53], v[164:167], v[172:175], v[50:53]
	v_mfma_f32_16x16x32_bf16 v[38:41], v[154:157], v[180:183], v[38:41]
	v_mfma_f32_16x16x32_bf16 v[34:37], v[164:167], v[180:183], v[34:37]
	v_mfma_f32_16x16x32_bf16 v[22:25], v[154:157], v[188:191], v[22:25]
	v_mfma_f32_16x16x32_bf16 v[18:21], v[164:167], v[188:191], v[18:21]
	v_mfma_f32_16x16x32_bf16 v[6:9], v[154:157], v[196:199], v[6:9]
	v_mfma_f32_16x16x32_bf16 v[2:5], v[164:167], v[196:199], v[2:5]
	v_mfma_f32_16x16x32_bf16 v[54:57], v[160:163], v[176:179], v[54:57]
	v_mfma_f32_16x16x32_bf16 v[50:53], v[168:171], v[176:179], v[50:53]
	v_mfma_f32_16x16x32_bf16 v[38:41], v[160:163], v[184:187], v[38:41]
	v_mfma_f32_16x16x32_bf16 v[34:37], v[168:171], v[184:187], v[34:37]
	v_mfma_f32_16x16x32_bf16 v[22:25], v[160:163], v[192:195], v[22:25]
	v_mfma_f32_16x16x32_bf16 v[18:21], v[168:171], v[192:195], v[18:21]
	v_mfma_f32_16x16x32_bf16 v[6:9], v[160:163], v[200:203], v[6:9]
	v_mfma_f32_16x16x32_bf16 v[2:5], v[168:171], v[200:203], v[2:5]
	s_setprio 0
	s_barrier
	s_add_i32 s66, s66, 2
	s_add_u32 s14, s14, 0x100
	s_addc_u32 s15, s15, 0
	s_cmp_gt_u32 s66, 13
	s_cbranch_scc0 .LBB0_1807

.LBB0_1886:
	s_add_i32 s47, 0, 0x10000
	v_add_u32_e32 v0, s47, v127
	ds_read_b128 v[130:133], v0
	ds_read_b128 v[134:137], v0 offset:1024
	ds_read_b128 v[138:141], v0 offset:2048
	ds_read_b128 v[142:145], v0 offset:3072
	ds_read_b128 v[146:149], v0 offset:16384
	ds_read_b128 v[158:161], v0 offset:17408
	ds_read_b128 v[162:165], v0 offset:18432
	ds_read_b128 v[166:169], v0 offset:19456
	ds_read_b128 v[170:173], v128
	ds_read_b128 v[174:177], v128 offset:1024
	ds_read_b128 v[178:181], v128 offset:2048
	ds_read_b128 v[182:185], v128 offset:3072
	ds_read_b128 v[186:189], v128 offset:4096
	ds_read_b128 v[190:193], v128 offset:5120
	ds_read_b128 v[194:197], v128 offset:6144
	ds_read_b128 v[198:201], v128 offset:7168
	s_add_u32 s6, s4, 0xfffc0080
	s_addc_u32 s7, s5, -1
	s_cmp_eq_u32 s46, 12
	s_cselect_b32 s7, s3, s7
	s_cselect_b32 s6, s2, s6
	s_cselect_b32 s11, s40, s43
	s_cselect_b32 s10, s26, s37
	s_add_i32 s50, 0, 0x14000
	s_add_i32 m0, s17, 0xc000
	s_nop 0
	global_load_lds_dwordx4 v122, s[4:5]
	s_add_i32 m0, s17, 0xe000
	s_nop 0
	global_load_lds_dwordx4 v123, s[4:5]
	s_waitcnt vmcnt(8) lgkmcnt(0)
	s_setprio 1
	s_barrier
	v_mfma_f32_16x16x32_bf16 v[154:157], v[130:133], v[170:173], v[154:157]
	v_mfma_f32_16x16x32_bf16 v[150:153], v[138:141], v[170:173], v[150:153]
	v_mfma_f32_16x16x32_bf16 v[110:113], v[130:133], v[178:181], v[110:113]
	v_mfma_f32_16x16x32_bf16 v[106:109], v[138:141], v[178:181], v[106:109]
	v_mfma_f32_16x16x32_bf16 v[94:97], v[130:133], v[186:189], v[94:97]
	v_mfma_f32_16x16x32_bf16 v[90:93], v[138:141], v[186:189], v[90:93]
	v_mfma_f32_16x16x32_bf16 v[78:81], v[130:133], v[194:197], v[78:81]
	v_mfma_f32_16x16x32_bf16 v[74:77], v[138:141], v[194:197], v[74:77]
	v_mfma_f32_16x16x32_bf16 v[154:157], v[134:137], v[174:177], v[154:157]
	v_mfma_f32_16x16x32_bf16 v[150:153], v[142:145], v[174:177], v[150:153]
	v_mfma_f32_16x16x32_bf16 v[110:113], v[134:137], v[182:185], v[110:113]
	v_mfma_f32_16x16x32_bf16 v[106:109], v[142:145], v[182:185], v[106:109]
	v_mfma_f32_16x16x32_bf16 v[94:97], v[134:137], v[190:193], v[94:97]
	v_mfma_f32_16x16x32_bf16 v[90:93], v[142:145], v[190:193], v[90:93]
	v_mfma_f32_16x16x32_bf16 v[78:81], v[134:137], v[198:201], v[78:81]
	v_mfma_f32_16x16x32_bf16 v[74:77], v[142:145], v[198:201], v[74:77]
	s_setprio 0
	s_setprio 1
	v_mfma_f32_16x16x32_bf16 v[118:121], v[146:149], v[170:173], v[118:121]
	v_mfma_f32_16x16x32_bf16 v[114:117], v[162:165], v[170:173], v[114:117]
	v_mfma_f32_16x16x32_bf16 v[102:105], v[146:149], v[178:181], v[102:105]
	v_mfma_f32_16x16x32_bf16 v[98:101], v[162:165], v[178:181], v[98:101]
	v_mfma_f32_16x16x32_bf16 v[86:89], v[146:149], v[186:189], v[86:89]
	v_mfma_f32_16x16x32_bf16 v[82:85], v[162:165], v[186:189], v[82:85]
	v_mfma_f32_16x16x32_bf16 v[70:73], v[146:149], v[194:197], v[70:73]
	v_mfma_f32_16x16x32_bf16 v[66:69], v[162:165], v[194:197], v[66:69]
	v_mfma_f32_16x16x32_bf16 v[118:121], v[158:161], v[174:177], v[118:121]
	v_mfma_f32_16x16x32_bf16 v[114:117], v[166:169], v[174:177], v[114:117]
	v_mfma_f32_16x16x32_bf16 v[102:105], v[158:161], v[182:185], v[102:105]
	v_mfma_f32_16x16x32_bf16 v[98:101], v[166:169], v[182:185], v[98:101]
	v_mfma_f32_16x16x32_bf16 v[86:89], v[158:161], v[190:193], v[86:89]
	v_mfma_f32_16x16x32_bf16 v[82:85], v[166:169], v[190:193], v[82:85]
	v_mfma_f32_16x16x32_bf16 v[70:73], v[158:161], v[198:201], v[70:73]
	v_mfma_f32_16x16x32_bf16 v[66:69], v[166:169], v[198:201], v[66:69]
	s_setprio 0
	s_barrier
	ds_read_b128 v[170:173], v128 offset:16384
	ds_read_b128 v[174:177], v128 offset:17408
	ds_read_b128 v[178:181], v128 offset:18432
	ds_read_b128 v[182:185], v128 offset:19456
	ds_read_b128 v[186:189], v128 offset:20480
	ds_read_b128 v[190:193], v128 offset:21504
	ds_read_b128 v[194:197], v128 offset:22528
	ds_read_b128 v[198:201], v128 offset:23552
	s_add_i32 s47, s47, s16
	s_mov_b32 m0, s47
	s_nop 0
	global_load_lds_dwordx4 v125, s[10:11]
	s_add_i32 m0, s47, 0x2000
	s_add_u32 s48, s10, 0x40000
	global_load_lds_dwordx4 v126, s[10:11]
	s_addc_u32 s49, s11, 0
	s_add_i32 s47, s50, s16
	s_mov_b32 m0, s47
	s_nop 0
	global_load_lds_dwordx4 v125, s[48:49]
	s_add_i32 m0, s47, 0x2000
	s_nop 0
	global_load_lds_dwordx4 v126, s[48:49]
	s_mov_b32 m0, s17
	s_nop 0
	global_load_lds_dwordx4 v122, s[6:7]
	s_mov_b32 m0, s22
	s_nop 0
	global_load_lds_dwordx4 v123, s[6:7]
	s_waitcnt vmcnt(8) lgkmcnt(0)
	s_setprio 1
	s_barrier
	v_mfma_f32_16x16x32_bf16 v[62:65], v[130:133], v[170:173], v[62:65]
	v_mfma_f32_16x16x32_bf16 v[58:61], v[138:141], v[170:173], v[58:61]
	v_mfma_f32_16x16x32_bf16 v[46:49], v[130:133], v[178:181], v[46:49]
	v_mfma_f32_16x16x32_bf16 v[42:45], v[138:141], v[178:181], v[42:45]
	v_mfma_f32_16x16x32_bf16 v[30:33], v[130:133], v[186:189], v[30:33]
	v_mfma_f32_16x16x32_bf16 v[26:29], v[138:141], v[186:189], v[26:29]
	v_mfma_f32_16x16x32_bf16 v[14:17], v[130:133], v[194:197], v[14:17]
	v_mfma_f32_16x16x32_bf16 v[10:13], v[138:141], v[194:197], v[10:13]
	v_mfma_f32_16x16x32_bf16 v[62:65], v[134:137], v[174:177], v[62:65]
	v_mfma_f32_16x16x32_bf16 v[58:61], v[142:145], v[174:177], v[58:61]
	v_mfma_f32_16x16x32_bf16 v[46:49], v[134:137], v[182:185], v[46:49]
	v_mfma_f32_16x16x32_bf16 v[42:45], v[142:145], v[182:185], v[42:45]
	v_mfma_f32_16x16x32_bf16 v[30:33], v[134:137], v[190:193], v[30:33]
	v_mfma_f32_16x16x32_bf16 v[26:29], v[142:145], v[190:193], v[26:29]
	v_mfma_f32_16x16x32_bf16 v[14:17], v[134:137], v[198:201], v[14:17]
	v_mfma_f32_16x16x32_bf16 v[10:13], v[142:145], v[198:201], v[10:13]
	s_setprio 0
	s_setprio 1
	v_mfma_f32_16x16x32_bf16 v[54:57], v[146:149], v[170:173], v[54:57]
	v_mfma_f32_16x16x32_bf16 v[50:53], v[162:165], v[170:173], v[50:53]
	v_mfma_f32_16x16x32_bf16 v[38:41], v[146:149], v[178:181], v[38:41]
	v_mfma_f32_16x16x32_bf16 v[34:37], v[162:165], v[178:181], v[34:37]
	v_mfma_f32_16x16x32_bf16 v[22:25], v[146:149], v[186:189], v[22:25]
	v_mfma_f32_16x16x32_bf16 v[18:21], v[162:165], v[186:189], v[18:21]
	v_mfma_f32_16x16x32_bf16 v[6:9], v[146:149], v[194:197], v[6:9]
	v_mfma_f32_16x16x32_bf16 v[2:5], v[162:165], v[194:197], v[2:5]
	v_mfma_f32_16x16x32_bf16 v[54:57], v[158:161], v[174:177], v[54:57]
	v_mfma_f32_16x16x32_bf16 v[50:53], v[166:169], v[174:177], v[50:53]
	v_mfma_f32_16x16x32_bf16 v[38:41], v[158:161], v[182:185], v[38:41]
	v_mfma_f32_16x16x32_bf16 v[34:37], v[166:169], v[182:185], v[34:37]
	v_mfma_f32_16x16x32_bf16 v[22:25], v[158:161], v[190:193], v[22:25]
	v_mfma_f32_16x16x32_bf16 v[18:21], v[166:169], v[190:193], v[18:21]
	v_mfma_f32_16x16x32_bf16 v[6:9], v[158:161], v[198:201], v[6:9]
	v_mfma_f32_16x16x32_bf16 v[2:5], v[166:169], v[198:201], v[2:5]
	s_setprio 0
	s_barrier
	ds_read_b128 v[130:133], v0 offset:32768
	ds_read_b128 v[134:137], v0 offset:33792
	ds_read_b128 v[138:141], v0 offset:34816
	ds_read_b128 v[142:145], v0 offset:35840
	ds_read_b128 v[146:149], v0 offset:49152
	ds_read_b128 v[158:161], v0 offset:50176
	ds_read_b128 v[162:165], v0 offset:51200
	ds_read_b128 v[166:169], v0 offset:52224
	s_add_u32 s48, s6, 0x40000
	s_mov_b32 m0, s23
	ds_read_b128 v[170:173], v128 offset:32768
	ds_read_b128 v[174:177], v128 offset:33792
	ds_read_b128 v[178:181], v128 offset:34816
	ds_read_b128 v[182:185], v128 offset:35840
	ds_read_b128 v[186:189], v128 offset:36864
	ds_read_b128 v[190:193], v128 offset:37888
	ds_read_b128 v[194:197], v128 offset:38912
	ds_read_b128 v[198:201], v128 offset:39936
	s_addc_u32 s49, s7, 0
	s_add_i32 s47, 0, 0x18000
	s_add_i32 s50, 0, 0x1c000
	s_nop 0
	global_load_lds_dwordx4 v122, s[48:49]
	s_mov_b32 m0, s24
	s_nop 0
	global_load_lds_dwordx4 v123, s[48:49]
	s_waitcnt vmcnt(8) lgkmcnt(0)
	s_setprio 1
	s_barrier
	v_mfma_f32_16x16x32_bf16 v[154:157], v[130:133], v[170:173], v[154:157]
	v_mfma_f32_16x16x32_bf16 v[150:153], v[138:141], v[170:173], v[150:153]
	v_mfma_f32_16x16x32_bf16 v[110:113], v[130:133], v[178:181], v[110:113]
	v_mfma_f32_16x16x32_bf16 v[106:109], v[138:141], v[178:181], v[106:109]
	v_mfma_f32_16x16x32_bf16 v[94:97], v[130:133], v[186:189], v[94:97]
	v_mfma_f32_16x16x32_bf16 v[90:93], v[138:141], v[186:189], v[90:93]
	v_mfma_f32_16x16x32_bf16 v[78:81], v[130:133], v[194:197], v[78:81]
	v_mfma_f32_16x16x32_bf16 v[74:77], v[138:141], v[194:197], v[74:77]
	v_mfma_f32_16x16x32_bf16 v[154:157], v[134:137], v[174:177], v[154:157]
	v_mfma_f32_16x16x32_bf16 v[150:153], v[142:145], v[174:177], v[150:153]
	v_mfma_f32_16x16x32_bf16 v[110:113], v[134:137], v[182:185], v[110:113]
	v_mfma_f32_16x16x32_bf16 v[106:109], v[142:145], v[182:185], v[106:109]
	v_mfma_f32_16x16x32_bf16 v[94:97], v[134:137], v[190:193], v[94:97]
	v_mfma_f32_16x16x32_bf16 v[90:93], v[142:145], v[190:193], v[90:93]
	v_mfma_f32_16x16x32_bf16 v[78:81], v[134:137], v[198:201], v[78:81]
	v_mfma_f32_16x16x32_bf16 v[74:77], v[142:145], v[198:201], v[74:77]
	s_setprio 0
	s_setprio 1
	v_mfma_f32_16x16x32_bf16 v[118:121], v[146:149], v[170:173], v[118:121]
	v_mfma_f32_16x16x32_bf16 v[114:117], v[162:165], v[170:173], v[114:117]
	v_mfma_f32_16x16x32_bf16 v[102:105], v[146:149], v[178:181], v[102:105]
	v_mfma_f32_16x16x32_bf16 v[98:101], v[162:165], v[178:181], v[98:101]
	v_mfma_f32_16x16x32_bf16 v[86:89], v[146:149], v[186:189], v[86:89]
	v_mfma_f32_16x16x32_bf16 v[82:85], v[162:165], v[186:189], v[82:85]
	v_mfma_f32_16x16x32_bf16 v[70:73], v[146:149], v[194:197], v[70:73]
	v_mfma_f32_16x16x32_bf16 v[66:69], v[162:165], v[194:197], v[66:69]
	v_mfma_f32_16x16x32_bf16 v[118:121], v[158:161], v[174:177], v[118:121]
	v_mfma_f32_16x16x32_bf16 v[114:117], v[166:169], v[174:177], v[114:117]
	v_mfma_f32_16x16x32_bf16 v[102:105], v[158:161], v[182:185], v[102:105]
	v_mfma_f32_16x16x32_bf16 v[98:101], v[166:169], v[182:185], v[98:101]
	v_mfma_f32_16x16x32_bf16 v[86:89], v[158:161], v[190:193], v[86:89]
	v_mfma_f32_16x16x32_bf16 v[82:85], v[166:169], v[190:193], v[82:85]
	v_mfma_f32_16x16x32_bf16 v[70:73], v[158:161], v[198:201], v[70:73]
	v_mfma_f32_16x16x32_bf16 v[66:69], v[166:169], v[198:201], v[66:69]
	s_setprio 0
	s_barrier
	ds_read_b128 v[170:173], v128 offset:49152
	ds_read_b128 v[174:177], v128 offset:50176
	ds_read_b128 v[178:181], v128 offset:51200
	ds_read_b128 v[182:185], v128 offset:52224
	ds_read_b128 v[186:189], v128 offset:53248
	ds_read_b128 v[190:193], v128 offset:54272
	ds_read_b128 v[194:197], v128 offset:55296
	ds_read_b128 v[198:201], v128 offset:56320
	s_add_i32 s47, s47, s16
	s_add_u32 s100, s10, s38
	s_addc_u32 s101, s11, s39
	s_mov_b32 m0, s47
	s_nop 0
	global_load_lds_dwordx4 v125, s[100:101]
	s_add_i32 m0, s47, 0x2000
	s_nop 0
	s_add_u32 s10, s10, 0x40080
	s_addc_u32 s11, s11, 0
	s_add_i32 s47, s50, s16
	global_load_lds_dwordx4 v126, s[100:101]
	s_mov_b32 m0, s47
	s_nop 0
	global_load_lds_dwordx4 v125, s[10:11]
	s_add_i32 m0, s47, 0x2000
	s_nop 0
	global_load_lds_dwordx4 v126, s[10:11]
	s_mov_b32 m0, s41
	s_add_u32 s100, s6, s38
	s_addc_u32 s101, s7, s39
	v_mov_b32_e32 v0, v123
	global_load_lds_dwordx4 v122, s[100:101]
	s_mov_b32 m0, s42
	s_nop 0
	global_load_lds_dwordx4 v123, s[100:101]
	s_waitcnt vmcnt(8) lgkmcnt(0)
	s_setprio 1
	s_barrier
	v_mfma_f32_16x16x32_bf16 v[62:65], v[130:133], v[170:173], v[62:65]
	v_mfma_f32_16x16x32_bf16 v[58:61], v[138:141], v[170:173], v[58:61]
	v_mfma_f32_16x16x32_bf16 v[46:49], v[130:133], v[178:181], v[46:49]
	v_mfma_f32_16x16x32_bf16 v[42:45], v[138:141], v[178:181], v[42:45]
	v_mfma_f32_16x16x32_bf16 v[30:33], v[130:133], v[186:189], v[30:33]
	v_mfma_f32_16x16x32_bf16 v[26:29], v[138:141], v[186:189], v[26:29]
	v_mfma_f32_16x16x32_bf16 v[14:17], v[130:133], v[194:197], v[14:17]
	v_mfma_f32_16x16x32_bf16 v[10:13], v[138:141], v[194:197], v[10:13]
	v_mfma_f32_16x16x32_bf16 v[62:65], v[134:137], v[174:177], v[62:65]
	v_mfma_f32_16x16x32_bf16 v[58:61], v[142:145], v[174:177], v[58:61]
	v_mfma_f32_16x16x32_bf16 v[46:49], v[134:137], v[182:185], v[46:49]
	v_mfma_f32_16x16x32_bf16 v[42:45], v[142:145], v[182:185], v[42:45]
	v_mfma_f32_16x16x32_bf16 v[30:33], v[134:137], v[190:193], v[30:33]
	v_mfma_f32_16x16x32_bf16 v[26:29], v[142:145], v[190:193], v[26:29]
	v_mfma_f32_16x16x32_bf16 v[14:17], v[134:137], v[198:201], v[14:17]
	v_mfma_f32_16x16x32_bf16 v[10:13], v[142:145], v[198:201], v[10:13]
	s_setprio 0
	s_setprio 1
	v_mfma_f32_16x16x32_bf16 v[54:57], v[146:149], v[170:173], v[54:57]
	v_mfma_f32_16x16x32_bf16 v[50:53], v[162:165], v[170:173], v[50:53]
	v_mfma_f32_16x16x32_bf16 v[38:41], v[146:149], v[178:181], v[38:41]
	v_mfma_f32_16x16x32_bf16 v[34:37], v[162:165], v[178:181], v[34:37]
	v_mfma_f32_16x16x32_bf16 v[22:25], v[146:149], v[186:189], v[22:25]
	v_mfma_f32_16x16x32_bf16 v[18:21], v[162:165], v[186:189], v[18:21]
	v_mfma_f32_16x16x32_bf16 v[6:9], v[146:149], v[194:197], v[6:9]
	v_mfma_f32_16x16x32_bf16 v[2:5], v[162:165], v[194:197], v[2:5]
	v_mfma_f32_16x16x32_bf16 v[54:57], v[158:161], v[174:177], v[54:57]
	v_mfma_f32_16x16x32_bf16 v[50:53], v[166:169], v[174:177], v[50:53]
	v_mfma_f32_16x16x32_bf16 v[38:41], v[158:161], v[182:185], v[38:41]
	v_mfma_f32_16x16x32_bf16 v[34:37], v[166:169], v[182:185], v[34:37]
	v_mfma_f32_16x16x32_bf16 v[22:25], v[158:161], v[190:193], v[22:25]
	v_mfma_f32_16x16x32_bf16 v[18:21], v[166:169], v[190:193], v[18:21]
	v_mfma_f32_16x16x32_bf16 v[6:9], v[158:161], v[198:201], v[6:9]
	v_mfma_f32_16x16x32_bf16 v[2:5], v[166:169], v[198:201], v[2:5]
	s_setprio 0
	s_barrier
	s_add_i32 s46, s46, 2
	s_add_u32 s4, s4, 0x100
	s_addc_u32 s5, s5, 0
	s_add_u32 s37, s37, 0x100
	s_addc_u32 s43, s43, 0
	s_cmp_gt_u32 s46, 13
	s_cbranch_scc0 .LBB0_1886
	s_cmpk_lt_u32 s14, 0x100
	s_cbranch_scc0 .LBB0_1889
	s_barrier
